# write-through stores on coalesced in-proj/token-phase images; dead per-iteration register initialisations removed from MLA and diff attention loops
# speedup vs baseline: 1.0260x; 1.0053x over previous
.LBB0_188:
	v_add_u32_e32 v142, s17, v148
	v_ashrrev_i32_e32 v143, 31, v142
	v_lshlrev_b64 v[142:143], 6, v[142:143]
	v_lshl_add_u64 v[146:147], v[136:137], 0, v[142:143]
	global_load_dwordx4 v[142:145], v[146:147], off
	global_load_dwordx4 v[152:155], v[146:147], off offset:1024
	global_load_dwordx4 v[156:159], v[146:147], off offset:2048
	global_load_dwordx4 v[160:163], v[146:147], off offset:3072
	v_add_co_u32_e32 v146, vcc, 0x2000, v146
	s_nop 1
	v_addc_co_u32_e32 v147, vcc, 0, v147, vcc
	global_load_dwordx4 v[168:171], v[146:147], off
	global_load_dwordx4 v[174:177], v[146:147], off offset:1024
	global_load_dwordx4 v[178:181], v[146:147], off offset:2048
	global_load_dwordx4 v[182:185], v[146:147], off offset:3072
	s_waitcnt vmcnt(0)
	v_mov_b32_e32 v146, v143
	v_mov_b32_e32 v147, v144
	v_mov_b32_e32 v143, v145
	v_pk_add_f32 v[142:143], v[146:147], v[142:143]
	v_add_f32_e32 v144, v152, v153
	v_add_f32_e32 v142, v142, v143
	ds_swizzle_b32 v143, v142 offset:swizzle(SWAP,16)
	v_add_f32_e32 v145, v154, v155
	v_add_f32_e32 v145, v144, v145
	ds_swizzle_b32 v146, v145 offset:swizzle(SWAP,16)
	v_add_u32_e32 v152, s15, v148
	s_waitcnt lgkmcnt(1)
	v_add_f32_e32 v142, v142, v143
	v_mov_b32_e32 v143, v142
	s_nop 1
	v_permlane32_swap_b32_e32 v142, v143
	v_add_f32_e32 v142, v142, v143
	v_fmamk_f32 v142, v142, 0x3a800000, v204
	v_rsq_f32_e32 v144, v142
	s_waitcnt lgkmcnt(0)
	v_add_f32_e32 v165, v145, v146
	v_add_f32_e32 v142, v156, v157
	v_add_f32_e32 v143, v158, v159
	v_add_f32_e32 v145, v160, v161
	v_add_f32_e32 v146, v162, v163
	v_add_f32_e32 v142, v142, v143
	v_add_f32_e32 v145, v145, v146
	ds_swizzle_b32 v143, v142 offset:swizzle(SWAP,16)
	ds_swizzle_b32 v146, v145 offset:swizzle(SWAP,16)
	v_mov_b32_e32 v166, v165
	s_nop 1
	v_permlane32_swap_b32_e32 v165, v166
	s_waitcnt lgkmcnt(1)
	v_add_f32_e32 v163, v142, v143
	s_waitcnt lgkmcnt(0)
	v_add_f32_e32 v161, v145, v146
	v_add_f32_e32 v142, v168, v169
	v_add_f32_e32 v143, v170, v171
	v_add_f32_e32 v145, v174, v175
	v_add_f32_e32 v146, v176, v177
	v_add_f32_e32 v142, v142, v143
	v_add_f32_e32 v145, v145, v146
	ds_swizzle_b32 v143, v142 offset:swizzle(SWAP,16)
	ds_swizzle_b32 v146, v145 offset:swizzle(SWAP,16)
	v_mov_b32_e32 v164, v163
	v_mov_b32_e32 v162, v161
	s_nop 0
	v_permlane32_swap_b32_e32 v163, v164
	s_waitcnt lgkmcnt(1)
	v_add_f32_e32 v159, v142, v143
	s_waitcnt lgkmcnt(0)
	v_add_f32_e32 v157, v145, v146
	v_add_f32_e32 v142, v178, v179
	v_add_f32_e32 v143, v180, v181
	v_add_f32_e32 v145, v182, v183
	v_add_f32_e32 v146, v184, v185
	v_add_f32_e32 v142, v142, v143
	v_add_f32_e32 v145, v145, v146
	ds_swizzle_b32 v143, v142 offset:swizzle(SWAP,16)
	ds_swizzle_b32 v146, v145 offset:swizzle(SWAP,16)
	v_mov_b32_e32 v160, v159
	v_mov_b32_e32 v158, v157
	v_permlane32_swap_b32_e32 v161, v162
	s_waitcnt lgkmcnt(1)
	v_add_f32_e32 v155, v142, v143
	s_waitcnt lgkmcnt(0)
	v_add_f32_e32 v153, v145, v146
	v_mov_b32_e32 v156, v155
	v_mov_b32_e32 v154, v153
	v_permlane32_swap_b32_e32 v159, v160
	v_permlane32_swap_b32_e32 v157, v158
	v_permlane32_swap_b32_e32 v155, v156
	v_permlane32_swap_b32_e32 v153, v154
	v_or_b32_e32 v168, s3, v150
	v_ashrrev_i32_e32 v145, 5, v152
	v_pk_mul_f32 v[126:127], v[126:127], v[144:145] op_sel_hi:[1,0]
	v_pk_mul_f32 v[124:125], v[124:125], v[144:145] op_sel_hi:[1,0]
	v_pk_mul_f32 v[122:123], v[122:123], v[144:145] op_sel_hi:[1,0]
	v_cvt_pk_bf16_f32 v124, v124, v125
	v_cvt_pk_bf16_f32 v125, v126, v127
	v_cvt_pk_bf16_f32 v127, v122, v123
	v_ashrrev_i32_e32 v122, 3, v168
	v_pk_mul_f32 v[120:121], v[120:121], v[144:145] op_sel_hi:[1,0]
	v_ashrrev_i32_e32 v123, 31, v122
	v_cvt_pk_bf16_f32 v126, v120, v121
	v_mad_i64_i32 v[120:121], s[2:3], v145, s22, v[122:123]
	v_ashrrev_i32_e32 v169, 31, v168
	v_lshlrev_b32_e32 v167, 4, v152
	v_lshlrev_b64 v[120:121], 9, v[120:121]
	v_lshl_add_u64 v[142:143], v[168:169], 1, s[44:45]
	v_mad_i64_i32 v[146:147], s[2:3], s34, v152, 0
	v_and_b32_e32 v172, 0x1f0, v167
	v_lshl_add_u64 v[120:121], s[6:7], 0, v[120:121]
	v_lshl_add_u64 v[146:147], v[146:147], 1, v[142:143]
	v_lshl_add_u64 v[120:121], v[120:121], 0, v[172:173]
	v_cndmask_b32_e64 v121, v147, v121, s[40:41]
	v_cndmask_b32_e64 v120, v146, v120, s[40:41]
	global_store_dwordx4 v[120:121], v[124:127], off sc1
	v_cndmask_b32_e64 v120, 0, 1, s[42:43]
	v_cmp_ne_u32_e64 s[2:3], 1, v120
	s_andn2_b64 vcc, exec, s[42:43]
	s_mov_b64 s[28:29], -1
	s_cbranch_vccnz .LBB0_190
	v_lshl_add_u64 v[126:127], v[146:147], 0, s[86:87]
	s_mov_b64 s[28:29], 0

.LBB0_192:
	v_add_f32_e32 v121, v165, v166
	v_fmamk_f32 v121, v121, 0x3a800000, v204
	v_rsq_f32_e32 v124, v121
	v_mov_b32_e32 v145, v144
	v_mov_b32_e32 v146, v144
	v_mov_b32_e32 v147, v144
	v_pk_mul_f32 v[116:117], v[116:117], v[144:145]
	v_pk_mul_f32 v[118:119], v[118:119], v[146:147]
	v_pk_mul_f32 v[146:147], v[110:111], v[146:147]
	v_pk_mul_f32 v[110:111], v[108:109], v[144:145]
	v_cvt_pk_bf16_f32 v108, v116, v117
	v_add_u32_e32 v117, 16, v152
	v_cvt_pk_bf16_f32 v109, v118, v119
	v_cvt_pk_bf16_f32 v110, v110, v111
	v_cvt_pk_bf16_f32 v111, v146, v147
	v_ashrrev_i32_e32 v116, 5, v117
	v_pk_mul_f32 v[112:113], v[112:113], v[124:125] op_sel_hi:[1,0]
	global_store_dwordx4 v[126:127], v[108:111], off sc1
	v_pk_mul_f32 v[118:119], v[106:107], v[124:125] op_sel_hi:[1,0]
	v_pk_mul_f32 v[106:107], v[104:105], v[124:125] op_sel_hi:[1,0]
	v_mad_i64_i32 v[108:109], s[28:29], s34, v117, 0
	v_cvt_pk_bf16_f32 v104, v112, v113
	v_mad_i64_i32 v[112:113], s[28:29], v116, s22, v[122:123]
	v_lshl_add_u64 v[110:111], v[108:109], 1, v[142:143]
	v_lshlrev_b32_e32 v108, 4, v117
	v_lshlrev_b64 v[112:113], 9, v[112:113]
	v_and_b32_e32 v108, 0x1f0, v108
	v_mov_b32_e32 v109, v173
	v_lshl_add_u64 v[112:113], s[6:7], 0, v[112:113]
	v_pk_mul_f32 v[114:115], v[114:115], v[124:125] op_sel_hi:[1,0]
	v_lshl_add_u64 v[112:113], v[112:113], 0, v[108:109]
	v_cvt_pk_bf16_f32 v105, v114, v115
	v_cvt_pk_bf16_f32 v106, v106, v107
	v_cvt_pk_bf16_f32 v107, v118, v119
	v_cndmask_b32_e64 v113, v111, v113, s[40:41]
	v_cndmask_b32_e64 v112, v110, v112, s[40:41]
	s_and_b64 vcc, exec, s[2:3]
	s_mov_b64 s[28:29], -1
	global_store_dwordx4 v[112:113], v[104:107], off sc1
	s_cbranch_vccnz .LBB0_194
	s_nop 0
	v_lshl_add_u64 v[104:105], v[110:111], 0, s[86:87]
	s_mov_b64 s[28:29], 0

.LBB0_196:
	v_mov_b32_e32 v125, v124
	v_mov_b32_e32 v106, v124
	v_mov_b32_e32 v107, v124
	v_pk_mul_f32 v[102:103], v[102:103], v[106:107]
	v_pk_mul_f32 v[100:101], v[100:101], v[124:125]
	v_pk_mul_f32 v[92:93], v[92:93], v[124:125]
	v_cvt_pk_bf16_f32 v100, v100, v101
	v_cvt_pk_bf16_f32 v101, v102, v103
	v_cvt_pk_bf16_f32 v102, v92, v93
	v_add_f32_e32 v92, v163, v164
	v_fmamk_f32 v92, v92, 0x3a800000, v204
	v_rsq_f32_e32 v92, v92
	v_pk_mul_f32 v[94:95], v[94:95], v[106:107]
	v_add_u32_e32 v93, 32, v152
	v_cvt_pk_bf16_f32 v103, v94, v95
	v_mad_i64_i32 v[94:95], s[28:29], s34, v93, 0
	v_ashrrev_i32_e32 v93, 5, v93
	v_pk_mul_f32 v[96:97], v[96:97], v[92:93] op_sel_hi:[1,0]
	global_store_dwordx4 v[104:105], v[100:103], off sc1
	v_lshl_add_u64 v[94:95], v[94:95], 1, v[142:143]
	v_pk_mul_f32 v[98:99], v[98:99], v[92:93] op_sel_hi:[1,0]
	v_pk_mul_f32 v[100:101], v[90:91], v[92:93] op_sel_hi:[1,0]
	v_pk_mul_f32 v[90:91], v[88:89], v[92:93] op_sel_hi:[1,0]
	v_cvt_pk_bf16_f32 v88, v96, v97
	v_mad_i64_i32 v[96:97], s[28:29], v93, s22, v[122:123]
	v_lshlrev_b64 v[96:97], 9, v[96:97]
	v_lshl_add_u64 v[96:97], s[6:7], 0, v[96:97]
	v_lshl_add_u64 v[96:97], v[96:97], 0, v[172:173]
	v_cvt_pk_bf16_f32 v89, v98, v99
	v_cvt_pk_bf16_f32 v90, v90, v91
	v_cvt_pk_bf16_f32 v91, v100, v101
	v_cndmask_b32_e64 v97, v95, v97, s[40:41]
	v_cndmask_b32_e64 v96, v94, v96, s[40:41]
	s_and_b64 vcc, exec, s[2:3]
	s_mov_b64 s[28:29], -1
	global_store_dwordx4 v[96:97], v[88:91], off sc1
	s_cbranch_vccnz .LBB0_198
	s_nop 0
	v_lshl_add_u64 v[88:89], v[94:95], 0, s[86:87]
	s_mov_b64 s[28:29], 0

.LBB0_200:
	v_mov_b32_e32 v93, v92
	v_mov_b32_e32 v90, v92
	v_mov_b32_e32 v91, v92
	v_pk_mul_f32 v[86:87], v[86:87], v[90:91]
	v_pk_mul_f32 v[84:85], v[84:85], v[92:93]
	v_pk_mul_f32 v[76:77], v[76:77], v[92:93]
	v_cvt_pk_bf16_f32 v84, v84, v85
	v_cvt_pk_bf16_f32 v85, v86, v87
	v_cvt_pk_bf16_f32 v86, v76, v77
	v_add_f32_e32 v76, v161, v162
	v_fmamk_f32 v76, v76, 0x3a800000, v204
	v_pk_mul_f32 v[78:79], v[78:79], v[90:91]
	v_rsq_f32_e32 v76, v76
	v_cvt_pk_bf16_f32 v87, v78, v79
	global_store_dwordx4 v[88:89], v[84:87], off sc1
	s_and_b64 vcc, exec, s[2:3]
	s_nop 0
	v_add_u32_e32 v86, 48, v152
	v_ashrrev_i32_e32 v77, 5, v86
	v_mad_i64_i32 v[78:79], s[28:29], s34, v86, 0
	v_pk_mul_f32 v[80:81], v[80:81], v[76:77] op_sel_hi:[1,0]
	v_lshl_add_u64 v[84:85], v[78:79], 1, v[142:143]
	v_lshlrev_b32_e32 v78, 4, v86
	v_pk_mul_f32 v[86:87], v[74:75], v[76:77] op_sel_hi:[1,0]
	v_pk_mul_f32 v[74:75], v[72:73], v[76:77] op_sel_hi:[1,0]
	v_cvt_pk_bf16_f32 v72, v80, v81
	v_mad_i64_i32 v[80:81], s[28:29], v77, s22, v[122:123]
	v_lshlrev_b64 v[80:81], 9, v[80:81]
	v_and_b32_e32 v78, 0x1f0, v78
	v_mov_b32_e32 v79, v173
	v_lshl_add_u64 v[80:81], s[6:7], 0, v[80:81]
	v_pk_mul_f32 v[82:83], v[82:83], v[76:77] op_sel_hi:[1,0]
	v_lshl_add_u64 v[80:81], v[80:81], 0, v[78:79]
	v_cvt_pk_bf16_f32 v73, v82, v83
	v_cvt_pk_bf16_f32 v74, v74, v75
	v_cvt_pk_bf16_f32 v75, v86, v87
	v_cndmask_b32_e64 v81, v85, v81, s[40:41]
	v_cndmask_b32_e64 v80, v84, v80, s[40:41]
	s_mov_b64 s[28:29], -1
	global_store_dwordx4 v[80:81], v[72:75], off sc1
	s_cbranch_vccnz .LBB0_202
	s_nop 0
	v_lshl_add_u64 v[72:73], v[84:85], 0, s[86:87]
	s_mov_b64 s[28:29], 0

.LBB0_204:
	v_mov_b32_e32 v77, v76
	v_mov_b32_e32 v74, v76
	v_mov_b32_e32 v75, v76
	v_pk_mul_f32 v[68:69], v[68:69], v[76:77]
	v_pk_mul_f32 v[64:65], v[64:65], v[76:77]
	v_pk_mul_f32 v[70:71], v[70:71], v[74:75]
	v_pk_mul_f32 v[74:75], v[66:67], v[74:75]
	v_cvt_pk_bf16_f32 v66, v68, v69
	v_cvt_pk_bf16_f32 v68, v64, v65
	v_add_f32_e32 v64, v159, v160
	v_fmamk_f32 v64, v64, 0x3a800000, v204
	v_rsq_f32_e32 v64, v64
	v_cvt_pk_bf16_f32 v67, v70, v71
	v_cvt_pk_bf16_f32 v69, v74, v75
	v_add_u32_e32 v65, 0x80, v152
	global_store_dwordx4 v[72:73], v[66:69], off sc1
	s_and_b64 vcc, exec, s[2:3]
	s_nop 0
	v_mad_i64_i32 v[66:67], s[28:29], s34, v65, 0
	v_ashrrev_i32_e32 v65, 5, v65
	v_pk_mul_f32 v[60:61], v[60:61], v[64:65] op_sel_hi:[1,0]
	v_pk_mul_f32 v[68:69], v[58:59], v[64:65] op_sel_hi:[1,0]
	v_pk_mul_f32 v[58:59], v[56:57], v[64:65] op_sel_hi:[1,0]
	v_cvt_pk_bf16_f32 v56, v60, v61
	v_mad_i64_i32 v[60:61], s[28:29], v65, s22, v[122:123]
	v_lshlrev_b64 v[60:61], 9, v[60:61]
	v_lshl_add_u64 v[60:61], s[6:7], 0, v[60:61]
	v_lshl_add_u64 v[66:67], v[66:67], 1, v[142:143]
	v_pk_mul_f32 v[62:63], v[62:63], v[64:65] op_sel_hi:[1,0]
	v_lshl_add_u64 v[60:61], v[60:61], 0, v[172:173]
	v_cvt_pk_bf16_f32 v57, v62, v63
	v_cvt_pk_bf16_f32 v58, v58, v59
	v_cvt_pk_bf16_f32 v59, v68, v69
	v_cndmask_b32_e64 v61, v67, v61, s[40:41]
	v_cndmask_b32_e64 v60, v66, v60, s[40:41]
	s_mov_b64 s[28:29], -1
	global_store_dwordx4 v[60:61], v[56:59], off sc1
	s_cbranch_vccnz .LBB0_206
	s_nop 0
	v_lshl_add_u64 v[56:57], v[66:67], 0, s[86:87]
	s_mov_b64 s[28:29], 0

.LBB0_208:
	v_mov_b32_e32 v65, v64
	v_mov_b32_e32 v58, v64
	v_mov_b32_e32 v59, v64
	v_pk_mul_f32 v[54:55], v[54:55], v[58:59]
	v_pk_mul_f32 v[52:53], v[52:53], v[64:65]
	v_pk_mul_f32 v[44:45], v[44:45], v[64:65]
	v_cvt_pk_bf16_f32 v52, v52, v53
	v_cvt_pk_bf16_f32 v53, v54, v55
	v_cvt_pk_bf16_f32 v54, v44, v45
	v_add_f32_e32 v44, v157, v158
	v_fmamk_f32 v44, v44, 0x3a800000, v204
	v_pk_mul_f32 v[46:47], v[46:47], v[58:59]
	v_rsq_f32_e32 v44, v44
	v_cvt_pk_bf16_f32 v55, v46, v47
	global_store_dwordx4 v[56:57], v[52:55], off sc1
	s_and_b64 vcc, exec, s[2:3]
	s_nop 0
	v_add_u32_e32 v54, 0x90, v152
	v_ashrrev_i32_e32 v45, 5, v54
	v_mad_i64_i32 v[46:47], s[28:29], s34, v54, 0
	v_pk_mul_f32 v[48:49], v[48:49], v[44:45] op_sel_hi:[1,0]
	v_lshl_add_u64 v[52:53], v[46:47], 1, v[142:143]
	v_lshlrev_b32_e32 v46, 4, v54
	v_pk_mul_f32 v[54:55], v[42:43], v[44:45] op_sel_hi:[1,0]
	v_pk_mul_f32 v[42:43], v[40:41], v[44:45] op_sel_hi:[1,0]
	v_cvt_pk_bf16_f32 v40, v48, v49
	v_mad_i64_i32 v[48:49], s[28:29], v45, s22, v[122:123]
	v_lshlrev_b64 v[48:49], 9, v[48:49]
	v_and_b32_e32 v46, 0x1f0, v46
	v_mov_b32_e32 v47, v173
	v_lshl_add_u64 v[48:49], s[6:7], 0, v[48:49]
	v_pk_mul_f32 v[50:51], v[50:51], v[44:45] op_sel_hi:[1,0]
	v_lshl_add_u64 v[48:49], v[48:49], 0, v[46:47]
	v_cvt_pk_bf16_f32 v41, v50, v51
	v_cvt_pk_bf16_f32 v42, v42, v43
	v_cvt_pk_bf16_f32 v43, v54, v55
	v_cndmask_b32_e64 v49, v53, v49, s[40:41]
	v_cndmask_b32_e64 v48, v52, v48, s[40:41]
	s_mov_b64 s[28:29], -1
	global_store_dwordx4 v[48:49], v[40:43], off sc1
	s_cbranch_vccnz .LBB0_210
	s_nop 0
	v_lshl_add_u64 v[40:41], v[52:53], 0, s[86:87]
	s_mov_b64 s[28:29], 0

.LBB0_212:
	v_mov_b32_e32 v45, v44
	v_mov_b32_e32 v42, v44
	v_mov_b32_e32 v43, v44
	v_pk_mul_f32 v[38:39], v[38:39], v[42:43]
	v_pk_mul_f32 v[36:37], v[36:37], v[44:45]
	v_pk_mul_f32 v[28:29], v[28:29], v[44:45]
	v_cvt_pk_bf16_f32 v36, v36, v37
	v_cvt_pk_bf16_f32 v37, v38, v39
	v_cvt_pk_bf16_f32 v38, v28, v29
	v_add_f32_e32 v28, v155, v156
	v_fmamk_f32 v28, v28, 0x3a800000, v204
	v_rsq_f32_e32 v28, v28
	v_pk_mul_f32 v[30:31], v[30:31], v[42:43]
	v_add_u32_e32 v29, 0xa0, v152
	v_cvt_pk_bf16_f32 v39, v30, v31
	v_mad_i64_i32 v[30:31], s[28:29], s34, v29, 0
	v_ashrrev_i32_e32 v29, 5, v29
	v_pk_mul_f32 v[32:33], v[32:33], v[28:29] op_sel_hi:[1,0]
	global_store_dwordx4 v[40:41], v[36:39], off sc1
	v_lshl_add_u64 v[30:31], v[30:31], 1, v[142:143]
	v_pk_mul_f32 v[34:35], v[34:35], v[28:29] op_sel_hi:[1,0]
	v_pk_mul_f32 v[36:37], v[26:27], v[28:29] op_sel_hi:[1,0]
	v_pk_mul_f32 v[26:27], v[24:25], v[28:29] op_sel_hi:[1,0]
	v_cvt_pk_bf16_f32 v24, v32, v33
	v_mad_i64_i32 v[32:33], s[28:29], v29, s22, v[122:123]
	v_lshlrev_b64 v[32:33], 9, v[32:33]
	v_lshl_add_u64 v[32:33], s[6:7], 0, v[32:33]
	v_lshl_add_u64 v[32:33], v[32:33], 0, v[172:173]
	v_cvt_pk_bf16_f32 v25, v34, v35
	v_cvt_pk_bf16_f32 v26, v26, v27
	v_cvt_pk_bf16_f32 v27, v36, v37
	v_cndmask_b32_e64 v33, v31, v33, s[40:41]
	v_cndmask_b32_e64 v32, v30, v32, s[40:41]
	s_and_b64 vcc, exec, s[2:3]
	s_mov_b64 s[28:29], -1
	global_store_dwordx4 v[32:33], v[24:27], off sc1
	s_cbranch_vccnz .LBB0_214
	s_nop 0
	v_lshl_add_u64 v[24:25], v[30:31], 0, s[86:87]
	s_mov_b64 s[28:29], 0

.LBB0_216:
	v_mov_b32_e32 v29, v28
	v_mov_b32_e32 v26, v28
	v_mov_b32_e32 v27, v28
	v_pk_mul_f32 v[22:23], v[22:23], v[26:27]
	v_pk_mul_f32 v[20:21], v[20:21], v[28:29]
	v_pk_mul_f32 v[12:13], v[12:13], v[28:29]
	v_cvt_pk_bf16_f32 v20, v20, v21
	v_cvt_pk_bf16_f32 v21, v22, v23
	v_cvt_pk_bf16_f32 v22, v12, v13
	v_add_f32_e32 v12, v153, v154
	v_fmamk_f32 v12, v12, 0x3a800000, v204
	v_pk_mul_f32 v[14:15], v[14:15], v[26:27]
	v_rsq_f32_e32 v12, v12
	v_cvt_pk_bf16_f32 v23, v14, v15
	global_store_dwordx4 v[24:25], v[20:23], off sc1
	s_and_b64 vcc, exec, s[2:3]
	s_mov_b64 s[2:3], -1
	v_add_u32_e32 v20, 0xb0, v152
	v_ashrrev_i32_e32 v13, 5, v20
	v_mad_i64_i32 v[14:15], s[28:29], s34, v20, 0
	v_lshlrev_b32_e32 v20, 4, v20
	v_pk_mul_f32 v[16:17], v[16:17], v[12:13] op_sel_hi:[1,0]
	v_and_b32_e32 v172, 0x1f0, v20
	v_pk_mul_f32 v[20:21], v[10:11], v[12:13] op_sel_hi:[1,0]
	v_pk_mul_f32 v[10:11], v[8:9], v[12:13] op_sel_hi:[1,0]
	v_cvt_pk_bf16_f32 v8, v16, v17
	v_mad_i64_i32 v[16:17], s[28:29], v13, s22, v[122:123]
	v_lshlrev_b64 v[16:17], 9, v[16:17]
	v_lshl_add_u64 v[16:17], s[6:7], 0, v[16:17]
	v_lshl_add_u64 v[14:15], v[14:15], 1, v[142:143]
	v_pk_mul_f32 v[18:19], v[18:19], v[12:13] op_sel_hi:[1,0]
	v_lshl_add_u64 v[16:17], v[16:17], 0, v[172:173]
	v_cvt_pk_bf16_f32 v9, v18, v19
	v_cvt_pk_bf16_f32 v10, v10, v11
	v_cvt_pk_bf16_f32 v11, v20, v21
	v_cndmask_b32_e64 v17, v15, v17, s[40:41]
	v_cndmask_b32_e64 v16, v14, v16, s[40:41]
	global_store_dwordx4 v[16:17], v[8:11], off sc1
	s_cbranch_vccnz .LBB0_218
	s_nop 0
	v_lshl_add_u64 v[8:9], v[14:15], 0, s[86:87]
	s_mov_b64 s[2:3], 0

.LBB0_220:
	v_mov_b32_e32 v13, v12
	v_mov_b32_e32 v10, v12
	v_mov_b32_e32 v11, v12
	v_pk_mul_f32 v[6:7], v[6:7], v[10:11]
	v_pk_mul_f32 v[4:5], v[4:5], v[12:13]
	v_pk_mul_f32 v[2:3], v[2:3], v[10:11]
	v_pk_mul_f32 v[0:1], v[0:1], v[12:13]
	v_cvt_pk_bf16_f32 v4, v4, v5
	v_cvt_pk_bf16_f32 v5, v6, v7
	v_cvt_pk_bf16_f32 v6, v0, v1
	v_cvt_pk_bf16_f32 v7, v2, v3
	s_andn2_b64 vcc, exec, s[38:39]
	s_mov_b64 s[2:3], -1
	global_store_dwordx4 v[8:9], v[4:7], off sc1
	s_cbranch_vccnz .LBB0_170
	s_andn2_b64 vcc, exec, s[0:1]
	s_cbranch_vccnz .LBB0_169
	s_barrier
	s_branch .LBB0_169

.LBB0_299:
	v_add_u32_e32 v142, s29, v148
	v_ashrrev_i32_e32 v143, 31, v142
	v_lshlrev_b64 v[142:143], 6, v[142:143]
	v_lshl_add_u64 v[146:147], v[136:137], 0, v[142:143]
	global_load_dwordx4 v[142:145], v[146:147], off
	global_load_dwordx4 v[152:155], v[146:147], off offset:1024
	global_load_dwordx4 v[156:159], v[146:147], off offset:2048
	global_load_dwordx4 v[160:163], v[146:147], off offset:3072
	v_add_co_u32_e32 v146, vcc, 0x2000, v146
	s_nop 1
	v_addc_co_u32_e32 v147, vcc, 0, v147, vcc
	global_load_dwordx4 v[168:171], v[146:147], off
	global_load_dwordx4 v[174:177], v[146:147], off offset:1024
	global_load_dwordx4 v[178:181], v[146:147], off offset:2048
	global_load_dwordx4 v[182:185], v[146:147], off offset:3072
	s_waitcnt vmcnt(0)
	v_mov_b32_e32 v146, v143
	v_mov_b32_e32 v147, v144
	v_mov_b32_e32 v143, v145
	v_pk_add_f32 v[142:143], v[146:147], v[142:143]
	v_add_f32_e32 v144, v152, v153
	v_add_f32_e32 v142, v142, v143
	ds_swizzle_b32 v143, v142 offset:swizzle(SWAP,16)
	v_add_f32_e32 v145, v154, v155
	v_add_f32_e32 v145, v144, v145
	ds_swizzle_b32 v146, v145 offset:swizzle(SWAP,16)
	v_add_u32_e32 v152, s17, v148
	s_waitcnt lgkmcnt(0)
	v_add_f32_e32 v142, v142, v143
	v_mov_b32_e32 v143, v142
	s_nop 1
	v_permlane32_swap_b32_e32 v142, v143
	v_add_f32_e32 v142, v142, v143
	v_fmamk_f32 v142, v142, 0x3a800000, v204
	v_rsq_f32_e32 v144, v142
	v_add_f32_e32 v165, v145, v146
	v_add_f32_e32 v142, v156, v157
	v_add_f32_e32 v143, v158, v159
	v_add_f32_e32 v145, v160, v161
	v_add_f32_e32 v146, v162, v163
	v_add_f32_e32 v142, v142, v143
	v_add_f32_e32 v145, v145, v146
	ds_swizzle_b32 v143, v142 offset:swizzle(SWAP,16)
	ds_swizzle_b32 v146, v145 offset:swizzle(SWAP,16)
	v_mov_b32_e32 v166, v165
	s_nop 1
	v_permlane32_swap_b32_e32 v165, v166
	s_waitcnt lgkmcnt(1)
	v_add_f32_e32 v163, v142, v143
	s_waitcnt lgkmcnt(0)
	v_add_f32_e32 v161, v145, v146
	v_add_f32_e32 v142, v168, v169
	v_add_f32_e32 v143, v170, v171
	v_add_f32_e32 v145, v174, v175
	v_add_f32_e32 v146, v176, v177
	v_add_f32_e32 v142, v142, v143
	v_add_f32_e32 v145, v145, v146
	ds_swizzle_b32 v143, v142 offset:swizzle(SWAP,16)
	ds_swizzle_b32 v146, v145 offset:swizzle(SWAP,16)
	v_mov_b32_e32 v164, v163
	v_mov_b32_e32 v162, v161
	s_nop 0
	v_permlane32_swap_b32_e32 v163, v164
	s_waitcnt lgkmcnt(1)
	v_add_f32_e32 v159, v142, v143
	s_waitcnt lgkmcnt(0)
	v_add_f32_e32 v157, v145, v146
	v_add_f32_e32 v142, v178, v179
	v_add_f32_e32 v143, v180, v181
	v_add_f32_e32 v145, v182, v183
	v_add_f32_e32 v146, v184, v185
	v_add_f32_e32 v142, v142, v143
	v_add_f32_e32 v145, v145, v146
	ds_swizzle_b32 v143, v142 offset:swizzle(SWAP,16)
	ds_swizzle_b32 v146, v145 offset:swizzle(SWAP,16)
	v_mov_b32_e32 v160, v159
	v_mov_b32_e32 v158, v157
	v_permlane32_swap_b32_e32 v161, v162
	s_waitcnt lgkmcnt(1)
	v_add_f32_e32 v155, v142, v143
	s_waitcnt lgkmcnt(0)
	v_add_f32_e32 v153, v145, v146
	v_mov_b32_e32 v156, v155
	v_mov_b32_e32 v154, v153
	v_permlane32_swap_b32_e32 v159, v160
	v_permlane32_swap_b32_e32 v157, v158
	v_permlane32_swap_b32_e32 v155, v156
	v_permlane32_swap_b32_e32 v153, v154
	v_or_b32_e32 v168, s15, v150
	v_ashrrev_i32_e32 v145, 5, v152
	v_pk_mul_f32 v[126:127], v[126:127], v[144:145] op_sel_hi:[1,0]
	v_pk_mul_f32 v[124:125], v[124:125], v[144:145] op_sel_hi:[1,0]
	v_pk_mul_f32 v[122:123], v[122:123], v[144:145] op_sel_hi:[1,0]
	v_cvt_pk_bf16_f32 v124, v124, v125
	v_cvt_pk_bf16_f32 v125, v126, v127
	v_cvt_pk_bf16_f32 v127, v122, v123
	v_ashrrev_i32_e32 v122, 3, v168
	v_ashrrev_i32_e32 v169, 31, v168
	v_pk_mul_f32 v[120:121], v[120:121], v[144:145] op_sel_hi:[1,0]
	v_ashrrev_i32_e32 v123, 31, v122
	v_lshl_add_u64 v[142:143], v[168:169], 1, s[2:3]
	v_cvt_pk_bf16_f32 v126, v120, v121
	v_mad_i64_i32 v[120:121], s[2:3], v145, s22, v[122:123]
	v_lshlrev_b32_e32 v167, 4, v152
	v_lshlrev_b64 v[120:121], 9, v[120:121]
	v_mad_i64_i32 v[146:147], s[2:3], s42, v152, 0
	v_and_b32_e32 v172, 0x1f0, v167
	v_lshl_add_u64 v[120:121], s[6:7], 0, v[120:121]
	v_lshl_add_u64 v[146:147], v[146:147], 1, v[142:143]
	v_lshl_add_u64 v[120:121], v[120:121], 0, v[172:173]
	v_cndmask_b32_e64 v121, v147, v121, s[40:41]
	v_cndmask_b32_e64 v120, v146, v120, s[40:41]
	global_store_dwordx4 v[120:121], v[124:127], off sc1
	v_cndmask_b32_e64 v120, 0, 1, s[44:45]
	v_cmp_ne_u32_e64 s[2:3], 1, v120
	s_andn2_b64 vcc, exec, s[44:45]
	s_mov_b64 s[28:29], -1
	s_cbranch_vccnz .LBB0_301
	v_lshl_add_u64 v[126:127], v[146:147], 0, s[86:87]
	s_mov_b64 s[28:29], 0

.LBB0_303:
	v_add_f32_e32 v121, v165, v166
	v_fmamk_f32 v121, v121, 0x3a800000, v204
	v_rsq_f32_e32 v124, v121
	v_mov_b32_e32 v145, v144
	v_mov_b32_e32 v146, v144
	v_mov_b32_e32 v147, v144
	v_pk_mul_f32 v[116:117], v[116:117], v[144:145]
	v_pk_mul_f32 v[118:119], v[118:119], v[146:147]
	v_pk_mul_f32 v[146:147], v[110:111], v[146:147]
	v_pk_mul_f32 v[110:111], v[108:109], v[144:145]
	v_cvt_pk_bf16_f32 v108, v116, v117
	v_add_u32_e32 v117, 16, v152
	v_cvt_pk_bf16_f32 v109, v118, v119
	v_cvt_pk_bf16_f32 v110, v110, v111
	v_cvt_pk_bf16_f32 v111, v146, v147
	v_ashrrev_i32_e32 v116, 5, v117
	v_pk_mul_f32 v[112:113], v[112:113], v[124:125] op_sel_hi:[1,0]
	global_store_dwordx4 v[126:127], v[108:111], off sc1
	v_pk_mul_f32 v[118:119], v[106:107], v[124:125] op_sel_hi:[1,0]
	v_pk_mul_f32 v[106:107], v[104:105], v[124:125] op_sel_hi:[1,0]
	v_mad_i64_i32 v[108:109], s[28:29], s42, v117, 0
	v_cvt_pk_bf16_f32 v104, v112, v113
	v_mad_i64_i32 v[112:113], s[28:29], v116, s22, v[122:123]
	v_lshl_add_u64 v[110:111], v[108:109], 1, v[142:143]
	v_lshlrev_b32_e32 v108, 4, v117
	v_lshlrev_b64 v[112:113], 9, v[112:113]
	v_and_b32_e32 v108, 0x1f0, v108
	v_mov_b32_e32 v109, v173
	v_lshl_add_u64 v[112:113], s[6:7], 0, v[112:113]
	v_pk_mul_f32 v[114:115], v[114:115], v[124:125] op_sel_hi:[1,0]
	v_lshl_add_u64 v[112:113], v[112:113], 0, v[108:109]
	v_cvt_pk_bf16_f32 v105, v114, v115
	v_cvt_pk_bf16_f32 v106, v106, v107
	v_cvt_pk_bf16_f32 v107, v118, v119
	v_cndmask_b32_e64 v113, v111, v113, s[40:41]
	v_cndmask_b32_e64 v112, v110, v112, s[40:41]
	s_and_b64 vcc, exec, s[2:3]
	s_mov_b64 s[28:29], -1
	global_store_dwordx4 v[112:113], v[104:107], off sc1
	s_cbranch_vccnz .LBB0_305
	s_nop 0
	v_lshl_add_u64 v[104:105], v[110:111], 0, s[86:87]
	s_mov_b64 s[28:29], 0

.LBB0_307:
	v_mov_b32_e32 v125, v124
	v_mov_b32_e32 v106, v124
	v_mov_b32_e32 v107, v124
	v_pk_mul_f32 v[102:103], v[102:103], v[106:107]
	v_pk_mul_f32 v[100:101], v[100:101], v[124:125]
	v_pk_mul_f32 v[92:93], v[92:93], v[124:125]
	v_cvt_pk_bf16_f32 v100, v100, v101
	v_cvt_pk_bf16_f32 v101, v102, v103
	v_cvt_pk_bf16_f32 v102, v92, v93
	v_add_f32_e32 v92, v163, v164
	v_fmamk_f32 v92, v92, 0x3a800000, v204
	v_rsq_f32_e32 v92, v92
	v_pk_mul_f32 v[94:95], v[94:95], v[106:107]
	v_add_u32_e32 v93, 32, v152
	v_cvt_pk_bf16_f32 v103, v94, v95
	v_mad_i64_i32 v[94:95], s[28:29], s42, v93, 0
	v_ashrrev_i32_e32 v93, 5, v93
	v_pk_mul_f32 v[96:97], v[96:97], v[92:93] op_sel_hi:[1,0]
	global_store_dwordx4 v[104:105], v[100:103], off sc1
	v_lshl_add_u64 v[94:95], v[94:95], 1, v[142:143]
	v_pk_mul_f32 v[98:99], v[98:99], v[92:93] op_sel_hi:[1,0]
	v_pk_mul_f32 v[100:101], v[90:91], v[92:93] op_sel_hi:[1,0]
	v_pk_mul_f32 v[90:91], v[88:89], v[92:93] op_sel_hi:[1,0]
	v_cvt_pk_bf16_f32 v88, v96, v97
	v_mad_i64_i32 v[96:97], s[28:29], v93, s22, v[122:123]
	v_lshlrev_b64 v[96:97], 9, v[96:97]
	v_lshl_add_u64 v[96:97], s[6:7], 0, v[96:97]
	v_lshl_add_u64 v[96:97], v[96:97], 0, v[172:173]
	v_cvt_pk_bf16_f32 v89, v98, v99
	v_cvt_pk_bf16_f32 v90, v90, v91
	v_cvt_pk_bf16_f32 v91, v100, v101
	v_cndmask_b32_e64 v97, v95, v97, s[40:41]
	v_cndmask_b32_e64 v96, v94, v96, s[40:41]
	s_and_b64 vcc, exec, s[2:3]
	s_mov_b64 s[28:29], -1
	global_store_dwordx4 v[96:97], v[88:91], off sc1
	s_cbranch_vccnz .LBB0_309
	s_nop 0
	v_lshl_add_u64 v[88:89], v[94:95], 0, s[86:87]
	s_mov_b64 s[28:29], 0

.LBB0_311:
	v_mov_b32_e32 v93, v92
	v_mov_b32_e32 v90, v92
	v_mov_b32_e32 v91, v92
	v_pk_mul_f32 v[86:87], v[86:87], v[90:91]
	v_pk_mul_f32 v[84:85], v[84:85], v[92:93]
	v_pk_mul_f32 v[76:77], v[76:77], v[92:93]
	v_cvt_pk_bf16_f32 v84, v84, v85
	v_cvt_pk_bf16_f32 v85, v86, v87
	v_cvt_pk_bf16_f32 v86, v76, v77
	v_add_f32_e32 v76, v161, v162
	v_fmamk_f32 v76, v76, 0x3a800000, v204
	v_pk_mul_f32 v[78:79], v[78:79], v[90:91]
	v_rsq_f32_e32 v76, v76
	v_cvt_pk_bf16_f32 v87, v78, v79
	global_store_dwordx4 v[88:89], v[84:87], off sc1
	s_and_b64 vcc, exec, s[2:3]
	s_nop 0
	v_add_u32_e32 v86, 48, v152
	v_ashrrev_i32_e32 v77, 5, v86
	v_mad_i64_i32 v[78:79], s[28:29], s42, v86, 0
	v_pk_mul_f32 v[80:81], v[80:81], v[76:77] op_sel_hi:[1,0]
	v_lshl_add_u64 v[84:85], v[78:79], 1, v[142:143]
	v_lshlrev_b32_e32 v78, 4, v86
	v_pk_mul_f32 v[86:87], v[74:75], v[76:77] op_sel_hi:[1,0]
	v_pk_mul_f32 v[74:75], v[72:73], v[76:77] op_sel_hi:[1,0]
	v_cvt_pk_bf16_f32 v72, v80, v81
	v_mad_i64_i32 v[80:81], s[28:29], v77, s22, v[122:123]
	v_lshlrev_b64 v[80:81], 9, v[80:81]
	v_and_b32_e32 v78, 0x1f0, v78
	v_mov_b32_e32 v79, v173
	v_lshl_add_u64 v[80:81], s[6:7], 0, v[80:81]
	v_pk_mul_f32 v[82:83], v[82:83], v[76:77] op_sel_hi:[1,0]
	v_lshl_add_u64 v[80:81], v[80:81], 0, v[78:79]
	v_cvt_pk_bf16_f32 v73, v82, v83
	v_cvt_pk_bf16_f32 v74, v74, v75
	v_cvt_pk_bf16_f32 v75, v86, v87
	v_cndmask_b32_e64 v81, v85, v81, s[40:41]
	v_cndmask_b32_e64 v80, v84, v80, s[40:41]
	s_mov_b64 s[28:29], -1
	global_store_dwordx4 v[80:81], v[72:75], off sc1
	s_cbranch_vccnz .LBB0_313
	s_nop 0
	v_lshl_add_u64 v[72:73], v[84:85], 0, s[86:87]
	s_mov_b64 s[28:29], 0

.LBB0_315:
	v_mov_b32_e32 v77, v76
	v_mov_b32_e32 v74, v76
	v_mov_b32_e32 v75, v76
	v_pk_mul_f32 v[68:69], v[68:69], v[76:77]
	v_pk_mul_f32 v[64:65], v[64:65], v[76:77]
	v_pk_mul_f32 v[70:71], v[70:71], v[74:75]
	v_pk_mul_f32 v[74:75], v[66:67], v[74:75]
	v_cvt_pk_bf16_f32 v66, v68, v69
	v_cvt_pk_bf16_f32 v68, v64, v65
	v_add_f32_e32 v64, v159, v160
	v_fmamk_f32 v64, v64, 0x3a800000, v204
	v_rsq_f32_e32 v64, v64
	v_cvt_pk_bf16_f32 v67, v70, v71
	v_cvt_pk_bf16_f32 v69, v74, v75
	v_add_u32_e32 v65, 0x80, v152
	global_store_dwordx4 v[72:73], v[66:69], off sc1
	s_and_b64 vcc, exec, s[2:3]
	s_nop 0
	v_mad_i64_i32 v[66:67], s[28:29], s42, v65, 0
	v_ashrrev_i32_e32 v65, 5, v65
	v_pk_mul_f32 v[60:61], v[60:61], v[64:65] op_sel_hi:[1,0]
	v_pk_mul_f32 v[68:69], v[58:59], v[64:65] op_sel_hi:[1,0]
	v_pk_mul_f32 v[58:59], v[56:57], v[64:65] op_sel_hi:[1,0]
	v_cvt_pk_bf16_f32 v56, v60, v61
	v_mad_i64_i32 v[60:61], s[28:29], v65, s22, v[122:123]
	v_lshlrev_b64 v[60:61], 9, v[60:61]
	v_lshl_add_u64 v[60:61], s[6:7], 0, v[60:61]
	v_lshl_add_u64 v[66:67], v[66:67], 1, v[142:143]
	v_pk_mul_f32 v[62:63], v[62:63], v[64:65] op_sel_hi:[1,0]
	v_lshl_add_u64 v[60:61], v[60:61], 0, v[172:173]
	v_cvt_pk_bf16_f32 v57, v62, v63
	v_cvt_pk_bf16_f32 v58, v58, v59
	v_cvt_pk_bf16_f32 v59, v68, v69
	v_cndmask_b32_e64 v61, v67, v61, s[40:41]
	v_cndmask_b32_e64 v60, v66, v60, s[40:41]
	s_mov_b64 s[28:29], -1
	global_store_dwordx4 v[60:61], v[56:59], off sc1
	s_cbranch_vccnz .LBB0_317
	s_nop 0
	v_lshl_add_u64 v[56:57], v[66:67], 0, s[86:87]
	s_mov_b64 s[28:29], 0

.LBB0_319:
	v_mov_b32_e32 v65, v64
	v_mov_b32_e32 v58, v64
	v_mov_b32_e32 v59, v64
	v_pk_mul_f32 v[54:55], v[54:55], v[58:59]
	v_pk_mul_f32 v[52:53], v[52:53], v[64:65]
	v_pk_mul_f32 v[44:45], v[44:45], v[64:65]
	v_cvt_pk_bf16_f32 v52, v52, v53
	v_cvt_pk_bf16_f32 v53, v54, v55
	v_cvt_pk_bf16_f32 v54, v44, v45
	v_add_f32_e32 v44, v157, v158
	v_fmamk_f32 v44, v44, 0x3a800000, v204
	v_pk_mul_f32 v[46:47], v[46:47], v[58:59]
	v_rsq_f32_e32 v44, v44
	v_cvt_pk_bf16_f32 v55, v46, v47
	global_store_dwordx4 v[56:57], v[52:55], off sc1
	s_and_b64 vcc, exec, s[2:3]
	s_nop 0
	v_add_u32_e32 v54, 0x90, v152
	v_ashrrev_i32_e32 v45, 5, v54
	v_mad_i64_i32 v[46:47], s[28:29], s42, v54, 0
	v_pk_mul_f32 v[48:49], v[48:49], v[44:45] op_sel_hi:[1,0]
	v_lshl_add_u64 v[52:53], v[46:47], 1, v[142:143]
	v_lshlrev_b32_e32 v46, 4, v54
	v_pk_mul_f32 v[54:55], v[42:43], v[44:45] op_sel_hi:[1,0]
	v_pk_mul_f32 v[42:43], v[40:41], v[44:45] op_sel_hi:[1,0]
	v_cvt_pk_bf16_f32 v40, v48, v49
	v_mad_i64_i32 v[48:49], s[28:29], v45, s22, v[122:123]
	v_lshlrev_b64 v[48:49], 9, v[48:49]
	v_and_b32_e32 v46, 0x1f0, v46
	v_mov_b32_e32 v47, v173
	v_lshl_add_u64 v[48:49], s[6:7], 0, v[48:49]
	v_pk_mul_f32 v[50:51], v[50:51], v[44:45] op_sel_hi:[1,0]
	v_lshl_add_u64 v[48:49], v[48:49], 0, v[46:47]
	v_cvt_pk_bf16_f32 v41, v50, v51
	v_cvt_pk_bf16_f32 v42, v42, v43
	v_cvt_pk_bf16_f32 v43, v54, v55
	v_cndmask_b32_e64 v49, v53, v49, s[40:41]
	v_cndmask_b32_e64 v48, v52, v48, s[40:41]
	s_mov_b64 s[28:29], -1
	global_store_dwordx4 v[48:49], v[40:43], off sc1
	s_cbranch_vccnz .LBB0_321
	s_nop 0
	v_lshl_add_u64 v[40:41], v[52:53], 0, s[86:87]
	s_mov_b64 s[28:29], 0

.LBB0_323:
	v_mov_b32_e32 v45, v44
	v_mov_b32_e32 v42, v44
	v_mov_b32_e32 v43, v44
	v_pk_mul_f32 v[38:39], v[38:39], v[42:43]
	v_pk_mul_f32 v[36:37], v[36:37], v[44:45]
	v_pk_mul_f32 v[28:29], v[28:29], v[44:45]
	v_cvt_pk_bf16_f32 v36, v36, v37
	v_cvt_pk_bf16_f32 v37, v38, v39
	v_cvt_pk_bf16_f32 v38, v28, v29
	v_add_f32_e32 v28, v155, v156
	v_fmamk_f32 v28, v28, 0x3a800000, v204
	v_rsq_f32_e32 v28, v28
	v_pk_mul_f32 v[30:31], v[30:31], v[42:43]
	v_add_u32_e32 v29, 0xa0, v152
	v_cvt_pk_bf16_f32 v39, v30, v31
	v_mad_i64_i32 v[30:31], s[28:29], s42, v29, 0
	v_ashrrev_i32_e32 v29, 5, v29
	v_pk_mul_f32 v[32:33], v[32:33], v[28:29] op_sel_hi:[1,0]
	global_store_dwordx4 v[40:41], v[36:39], off sc1
	v_lshl_add_u64 v[30:31], v[30:31], 1, v[142:143]
	v_pk_mul_f32 v[34:35], v[34:35], v[28:29] op_sel_hi:[1,0]
	v_pk_mul_f32 v[36:37], v[26:27], v[28:29] op_sel_hi:[1,0]
	v_pk_mul_f32 v[26:27], v[24:25], v[28:29] op_sel_hi:[1,0]
	v_cvt_pk_bf16_f32 v24, v32, v33
	v_mad_i64_i32 v[32:33], s[28:29], v29, s22, v[122:123]
	v_lshlrev_b64 v[32:33], 9, v[32:33]
	v_lshl_add_u64 v[32:33], s[6:7], 0, v[32:33]
	v_lshl_add_u64 v[32:33], v[32:33], 0, v[172:173]
	v_cvt_pk_bf16_f32 v25, v34, v35
	v_cvt_pk_bf16_f32 v26, v26, v27
	v_cvt_pk_bf16_f32 v27, v36, v37
	v_cndmask_b32_e64 v33, v31, v33, s[40:41]
	v_cndmask_b32_e64 v32, v30, v32, s[40:41]
	s_and_b64 vcc, exec, s[2:3]
	s_mov_b64 s[28:29], -1
	global_store_dwordx4 v[32:33], v[24:27], off sc1
	s_cbranch_vccnz .LBB0_325
	s_nop 0
	v_lshl_add_u64 v[24:25], v[30:31], 0, s[86:87]
	s_mov_b64 s[28:29], 0

.LBB0_327:
	v_mov_b32_e32 v29, v28
	v_mov_b32_e32 v26, v28
	v_mov_b32_e32 v27, v28
	v_pk_mul_f32 v[22:23], v[22:23], v[26:27]
	v_pk_mul_f32 v[20:21], v[20:21], v[28:29]
	v_pk_mul_f32 v[12:13], v[12:13], v[28:29]
	v_cvt_pk_bf16_f32 v20, v20, v21
	v_cvt_pk_bf16_f32 v21, v22, v23
	v_cvt_pk_bf16_f32 v22, v12, v13
	v_add_f32_e32 v12, v153, v154
	v_fmamk_f32 v12, v12, 0x3a800000, v204
	v_pk_mul_f32 v[14:15], v[14:15], v[26:27]
	v_rsq_f32_e32 v12, v12
	v_cvt_pk_bf16_f32 v23, v14, v15
	global_store_dwordx4 v[24:25], v[20:23], off sc1
	s_and_b64 vcc, exec, s[2:3]
	s_mov_b64 s[2:3], -1
	v_add_u32_e32 v20, 0xb0, v152
	v_ashrrev_i32_e32 v13, 5, v20
	v_mad_i64_i32 v[14:15], s[28:29], s42, v20, 0
	v_lshlrev_b32_e32 v20, 4, v20
	v_pk_mul_f32 v[16:17], v[16:17], v[12:13] op_sel_hi:[1,0]
	v_and_b32_e32 v172, 0x1f0, v20
	v_pk_mul_f32 v[20:21], v[10:11], v[12:13] op_sel_hi:[1,0]
	v_pk_mul_f32 v[10:11], v[8:9], v[12:13] op_sel_hi:[1,0]
	v_cvt_pk_bf16_f32 v8, v16, v17
	v_mad_i64_i32 v[16:17], s[28:29], v13, s22, v[122:123]
	v_lshlrev_b64 v[16:17], 9, v[16:17]
	v_lshl_add_u64 v[16:17], s[6:7], 0, v[16:17]
	v_lshl_add_u64 v[14:15], v[14:15], 1, v[142:143]
	v_pk_mul_f32 v[18:19], v[18:19], v[12:13] op_sel_hi:[1,0]
	v_lshl_add_u64 v[16:17], v[16:17], 0, v[172:173]
	v_cvt_pk_bf16_f32 v9, v18, v19
	v_cvt_pk_bf16_f32 v10, v10, v11
	v_cvt_pk_bf16_f32 v11, v20, v21
	v_cndmask_b32_e64 v17, v15, v17, s[40:41]
	v_cndmask_b32_e64 v16, v14, v16, s[40:41]
	global_store_dwordx4 v[16:17], v[8:11], off sc1
	s_cbranch_vccnz .LBB0_329
	s_nop 0
	v_lshl_add_u64 v[8:9], v[14:15], 0, s[86:87]
	s_mov_b64 s[2:3], 0

.LBB0_331:
	v_mov_b32_e32 v13, v12
	v_mov_b32_e32 v10, v12
	v_mov_b32_e32 v11, v12
	v_pk_mul_f32 v[6:7], v[6:7], v[10:11]
	v_pk_mul_f32 v[4:5], v[4:5], v[12:13]
	v_pk_mul_f32 v[2:3], v[2:3], v[10:11]
	v_pk_mul_f32 v[0:1], v[0:1], v[12:13]
	v_cvt_pk_bf16_f32 v4, v4, v5
	v_cvt_pk_bf16_f32 v5, v6, v7
	v_cvt_pk_bf16_f32 v6, v0, v1
	v_cvt_pk_bf16_f32 v7, v2, v3
	s_andn2_b64 vcc, exec, s[38:39]
	s_mov_b64 s[2:3], -1
	global_store_dwordx4 v[8:9], v[4:7], off sc1
	s_cbranch_vccnz .LBB0_282
	s_andn2_b64 vcc, exec, s[4:5]
	s_cbranch_vccnz .LBB0_281
	s_barrier
	s_branch .LBB0_281

.LBB0_338:
	s_and_b32 s81, s33, 0x7f
	s_lshr_b32 s82, s33, 7
	s_lshl_b32 s70, s81, 1
	s_lshl_b32 s71, s82, 8
	s_or_b32 s80, s70, s74
	s_or_b32 s70, s80, s71
	s_mul_hi_u32 s72, s70, 0x2800
	s_mul_i32 s73, s70, 0x2800
	v_mov_b32_e32 v1, s72
	v_or_b32_e32 v0, s73, v96
	s_mov_b32 s71, s8
	v_lshl_add_u64 v[0:1], v[0:1], 4, s[4:5]
	v_lshl_add_u64 v[2:3], v[0:1], 0, v[98:99]
	s_lshl_b64 s[70:71], s[70:71], 12
	v_lshl_add_u64 v[4:5], v[2:3], 0, s[6:7]
	v_lshl_add_u64 v[6:7], v[2:3], 0, s[10:11]
	v_lshl_add_u64 v[8:9], v[2:3], 0, s[14:15]
	v_lshl_add_u64 v[10:11], v[2:3], 0, s[16:17]
	global_load_dwordx2 v[152:153], v[4:5], off nt
	global_load_dwordx2 v[180:181], v[6:7], off nt
	global_load_dwordx2 v[118:119], v[8:9], off nt
	global_load_dwordx2 v[154:155], v[10:11], off nt
	v_lshl_add_u64 v[4:5], v[2:3], 0, s[18:19]
	v_lshl_add_u64 v[6:7], v[2:3], 0, s[26:27]
	v_lshl_add_u64 v[8:9], v[2:3], 0, s[28:29]
	v_lshl_add_u64 v[10:11], v[2:3], 0, s[34:35]
	global_load_dwordx2 v[174:175], v[4:5], off nt
	global_load_dwordx2 v[120:121], v[6:7], off nt
	global_load_dwordx2 v[156:157], v[8:9], off nt
	global_load_dwordx2 v[182:183], v[10:11], off nt
	v_lshl_add_u64 v[4:5], v[2:3], 0, s[38:39]
	v_lshl_add_u64 v[6:7], v[2:3], 0, s[40:41]
	v_lshl_add_u64 v[8:9], v[2:3], 0, s[42:43]
	v_lshl_add_u64 v[10:11], v[2:3], 0, s[44:45]
	global_load_dwordx2 v[124:125], v[4:5], off nt
	global_load_dwordx2 v[158:159], v[6:7], off nt
	global_load_dwordx2 v[188:189], v[8:9], off nt
	global_load_dwordx2 v[128:129], v[10:11], off nt
	v_lshl_add_u64 v[4:5], v[2:3], 0, s[46:47]
	v_lshl_add_u64 v[6:7], v[2:3], 0, s[48:49]
	v_lshl_add_u64 v[8:9], v[2:3], 0, s[50:51]
	v_lshl_add_u64 v[10:11], v[2:3], 0, s[52:53]
	global_load_dwordx2 v[160:161], v[4:5], off nt
	global_load_dwordx2 v[136:137], v[6:7], off nt
	global_load_dwordx2 v[122:123], v[8:9], off nt
	global_load_dwordx2 v[166:167], v[10:11], off nt
	v_lshl_add_u64 v[4:5], v[2:3], 0, s[54:55]
	v_lshl_add_u64 v[6:7], v[2:3], 0, s[56:57]
	v_lshl_add_u64 v[8:9], v[2:3], 0, s[58:59]
	v_lshl_add_u64 v[10:11], v[2:3], 0, s[60:61]
	global_load_dwordx2 v[140:141], v[4:5], off nt
	global_load_dwordx2 v[126:127], v[6:7], off nt
	global_load_dwordx2 v[162:163], v[8:9], off nt
	global_load_dwordx2 v[138:139], v[10:11], off nt
	v_lshl_add_u64 v[4:5], v[2:3], 0, s[62:63]
	v_lshl_add_u64 v[6:7], v[2:3], 0, s[64:65]
	v_lshl_add_u64 v[8:9], v[2:3], 0, s[66:67]
	v_lshl_add_u64 v[2:3], v[2:3], 0, s[68:69]
	v_lshl_add_u64 v[12:13], v[0:1], 0, v[114:115]
	global_load_dwordx2 v[130:131], v[4:5], off nt
	global_load_dwordx2 v[170:171], v[6:7], off nt
	global_load_dwordx2 v[142:143], v[8:9], off nt
	global_load_dwordx2 v[132:133], v[2:3], off nt
	s_nop 0
	global_load_dwordx4 v[8:11], v[12:13], off nt
	global_load_dwordx4 v[4:7], v[12:13], off offset:1024 nt
	global_load_dwordx4 v[0:3], v[12:13], off offset:2048 nt
	global_load_dwordx4 v[64:67], v[12:13], off offset:3072 nt
	v_lshl_add_u64 v[12:13], v[116:117], 0, s[70:71]
	global_load_dwordx4 v[68:71], v[12:13], off
	global_load_dwordx4 v[20:23], v[12:13], off offset:512
	global_load_dwordx4 v[16:19], v[12:13], off offset:2048
	s_nop 0
	global_load_dwordx4 v[12:15], v[12:13], off offset:2560
	s_nop 0
	global_load_dwordx4 v[88:91], v[100:101], off
	global_load_dwordx4 v[84:87], v[100:101], off offset:32
	global_load_dwordx4 v[144:147], v[100:101], off offset:64
	global_load_dwordx4 v[148:151], v[100:101], off offset:96
	global_load_dwordx4 v[80:83], v[102:103], off
	global_load_dwordx4 v[72:75], v[102:103], off offset:32
	global_load_dwordx4 v[92:95], v[102:103], off offset:64
	global_load_dwordx4 v[76:79], v[102:103], off offset:96
	global_load_dwordx4 v[56:59], v[104:105], off
	global_load_dwordx4 v[48:51], v[104:105], off offset:32
	global_load_dwordx4 v[40:43], v[104:105], off offset:64
	global_load_dwordx4 v[32:35], v[104:105], off offset:96
	global_load_dwordx4 v[60:63], v[104:105], off offset:128
	global_load_dwordx4 v[52:55], v[104:105], off offset:160
	global_load_dwordx4 v[44:47], v[104:105], off offset:192
	global_load_dwordx4 v[36:39], v[104:105], off offset:224
	s_waitcnt vmcnt(0)
	v_lshlrev_b32_e32 v184, 16, v159
	v_and_b32_e32 v185, 0xffff0000, v155
	v_and_b32_e32 v165, 0xffff0000, v159
	v_and_b32_e32 v164, 16, v155
	v_and_b32_e32 v215, 0xffff0000, v152
	v_lshlrev_b32_e32 v186, 16, v155
	v_pk_mov_b32 v[176:177], v[164:165], v[184:185] op_sel:[1,0]
	v_mov_b32_e32 v164, v150
	v_lshlrev_b32_e32 v150, 16, v158
	v_and_b32_e32 v155, 0xffff0000, v158
	v_mov_b32_e32 v169, v85
	v_mov_b32_e32 v85, v149
	v_and_b32_e32 v149, 0xffff0000, v153
	v_lshlrev_b32_e32 v158, 16, v153
	v_lshlrev_b32_e32 v214, 16, v156
	v_lshlrev_b32_e32 v152, 16, v152
	v_and_b32_e32 v153, 0xffff0000, v156
	v_mul_f32_e32 v156, v215, v215
	v_mov_b32_e32 v168, v148
	v_lshlrev_b32_e32 v148, 16, v157
	v_and_b32_e32 v159, 0xffff0000, v157
	v_pk_fma_f32 v[156:157], v[152:153], v[152:153], v[156:157] op_sel_hi:[1,1,0]
	v_mul_f32_e32 v178, v149, v149
	v_pk_fma_f32 v[156:157], v[158:159], v[158:159], v[156:157]
	v_mov_b32_e32 v187, v165
	v_mov_b32_e32 v165, v87
	v_mov_b32_e32 v87, v151
	v_and_b32_e32 v151, 0xffff0000, v154
	v_lshlrev_b32_e32 v154, 16, v154
	v_pk_add_f32 v[156:157], v[178:179], v[156:157] op_sel_hi:[0,1]
	v_pk_fma_f32 v[156:157], v[154:155], v[154:155], v[156:157]
	v_mul_f32_e32 v178, v151, v151
	v_pk_add_f32 v[156:157], v[178:179], v[156:157] op_sel_hi:[0,1]
	v_pk_fma_f32 v[156:157], v[186:187], v[186:187], v[156:157]
	v_mul_f32_e32 v178, v185, v185
	v_pk_add_f32 v[156:157], v[178:179], v[156:157] op_sel_hi:[0,1]
	v_pk_fma_f32 v[156:157], v[214:215], v[214:215], v[156:157]
	v_mul_f32_e32 v178, v153, v153
	v_pk_add_f32 v[156:157], v[178:179], v[156:157] op_sel_hi:[0,1]
	v_pk_fma_f32 v[156:157], v[148:149], v[148:149], v[156:157]
	v_mul_f32_e32 v178, v159, v159
	v_pk_add_f32 v[156:157], v[178:179], v[156:157] op_sel_hi:[0,1]
	v_pk_fma_f32 v[156:157], v[150:151], v[150:151], v[156:157]
	v_mul_f32_e32 v178, v155, v155
	v_pk_add_f32 v[156:157], v[178:179], v[156:157] op_sel_hi:[0,1]
	v_mul_f32_e32 v178, v177, v177
	v_pk_add_f32 v[156:157], v[178:179], v[156:157] op_sel_hi:[0,1]
	v_pk_fma_f32 v[156:157], v[176:177], v[176:177], v[156:157]
	v_mov_b32_e32 v176, v146
	v_mov_b32_e32 v157, v156
	s_nop 1
	v_permlane32_swap_b32_e32 v156, v157
	v_add_f32_e32 v156, v156, v157
	v_fmamk_f32 v156, v156, 0x3d000000, v204
	v_rsq_f32_e32 v156, v156
	v_mov_b32_e32 v179, v89
	v_mov_b32_e32 v89, v145
	v_mov_b32_e32 v177, v91
	v_mul_f32_e32 v146, 0x3e8293ee, v156
	v_mov_b32_e32 v178, v144
	v_pk_mul_f32 v[144:145], v[88:89], v[146:147] op_sel_hi:[1,0]
	v_mov_b32_e32 v91, v147
	v_pk_mul_f32 v[156:157], v[178:179], v[146:147] op_sel_hi:[1,0]
	v_pk_mul_f32 v[152:153], v[144:145], v[152:153]
	v_pk_mul_f32 v[144:145], v[176:177], v[146:147] op_sel_hi:[1,0]
	v_pk_mul_f32 v[156:157], v[156:157], v[214:215]
	v_pk_mul_f32 v[214:215], v[144:145], v[148:149]
	v_pk_mul_f32 v[144:145], v[90:91], v[146:147] op_sel_hi:[1,0]
	v_mov_b32_e32 v148, v152
	v_pk_mul_f32 v[158:159], v[144:145], v[158:159]
	v_pk_mul_f32 v[144:145], v[168:169], v[146:147] op_sel_hi:[1,0]
	v_mov_b32_e32 v149, v157
	v_pk_mul_f32 v[216:217], v[144:145], v[150:151]
	v_pk_mul_f32 v[144:145], v[84:85], v[146:147] op_sel_hi:[1,0]
	v_mov_b32_e32 v150, v156
	v_pk_mul_f32 v[218:219], v[144:145], v[154:155]
	v_pk_mul_f32 v[144:145], v[164:165], v[146:147] op_sel_hi:[1,0]
	v_mov_b32_e32 v151, v153
	v_pk_mul_f32 v[220:221], v[144:145], v[184:185]
	v_pk_mul_f32 v[144:145], v[86:87], v[146:147] op_sel_hi:[1,0]
	v_mov_b32_e32 v146, v69
	v_mov_b32_e32 v147, v71
	v_pk_mul_f32 v[222:223], v[144:145], v[186:187]
	v_mov_b32_e32 v144, v68
	v_mov_b32_e32 v145, v70
	v_pk_mul_f32 v[150:151], v[146:147], v[150:151]
	v_mov_b32_e32 v154, v214
	v_pk_fma_f32 v[224:225], v[144:145], v[148:149], v[150:151] neg_lo:[0,0,1] neg_hi:[0,0,1]
	v_mov_b32_e32 v148, v69
	v_mov_b32_e32 v69, v71
	v_mov_b32_e32 v149, v70
	v_pk_mul_f32 v[70:71], v[68:69], v[156:157]
	v_mov_b32_e32 v150, v21
	v_mov_b32_e32 v151, v23
	v_mov_b32_e32 v155, v159
	v_pk_fma_f32 v[226:227], v[148:149], v[152:153], v[70:71]
	v_mov_b32_e32 v70, v20
	v_mov_b32_e32 v71, v22
	v_mov_b32_e32 v152, v158
	v_mov_b32_e32 v153, v215
	v_pk_mul_f32 v[154:155], v[150:151], v[154:155]
	v_mov_b32_e32 v156, v218
	v_pk_fma_f32 v[228:229], v[70:71], v[152:153], v[154:155] neg_lo:[0,0,1] neg_hi:[0,0,1]
	v_mov_b32_e32 v152, v21
	v_mov_b32_e32 v21, v23
	v_mov_b32_e32 v153, v22
	v_pk_mul_f32 v[22:23], v[20:21], v[214:215]
	v_mov_b32_e32 v154, v17
	v_pk_fma_f32 v[230:231], v[152:153], v[158:159], v[22:23]
	v_mov_b32_e32 v155, v19
	v_mov_b32_e32 v158, v216
	v_mov_b32_e32 v159, v219
	v_mov_b32_e32 v22, v16
	v_mov_b32_e32 v23, v18
	v_mov_b32_e32 v157, v217
	v_pk_mul_f32 v[158:159], v[154:155], v[158:159]
	s_lshl_b32 s70, s82, 3
	v_pk_fma_f32 v[232:233], v[22:23], v[156:157], v[158:159] neg_lo:[0,0,1] neg_hi:[0,0,1]
	v_mov_b32_e32 v156, v17
	v_mov_b32_e32 v17, v19
	v_mov_b32_e32 v157, v18
	v_pk_mul_f32 v[18:19], v[16:17], v[216:217]
	v_mov_b32_e32 v158, v13
	v_mov_b32_e32 v159, v15
	v_mov_b32_e32 v186, v220
	v_mov_b32_e32 v187, v223
	s_add_i32 s70, s70, s77
	v_pk_fma_f32 v[218:219], v[156:157], v[218:219], v[18:19]
	v_mov_b32_e32 v18, v12
	v_mov_b32_e32 v19, v14
	v_mov_b32_e32 v184, v222
	v_mov_b32_e32 v185, v221
	v_pk_mul_f32 v[186:187], v[158:159], v[186:187]
	s_ashr_i32 s71, s70, 31
	v_pk_fma_f32 v[234:235], v[18:19], v[184:185], v[186:187] neg_lo:[0,0,1] neg_hi:[0,0,1]
	v_mov_b32_e32 v186, v12
	v_mov_b32_e32 v187, v15
	v_mov_b32_e32 v184, v13
	v_mov_b32_e32 v185, v14
	v_pk_mul_f32 v[214:215], v[186:187], v[220:221]
	s_lshl_b64 s[72:73], s[70:71], 19
	v_lshl_or_b32 v172, s80, 11, v191
	v_pk_fma_f32 v[220:221], v[184:185], v[222:223], v[214:215]
	v_lshl_add_u64 v[222:223], v[108:109], 0, s[72:73]
	v_cvt_pk_bf16_f32 v214, v224, v225
	v_cvt_pk_bf16_f32 v215, v228, v229
	v_cvt_pk_bf16_f32 v216, v232, v233
	v_cvt_pk_bf16_f32 v217, v234, v235
	v_lshl_add_u64 v[222:223], v[222:223], 0, v[172:173]
	global_store_dwordx4 v[222:223], v[214:217], off sc1
	v_lshlrev_b32_e32 v224, 16, v188
	v_and_b32_e32 v225, 0xffff0000, v174
	v_cvt_pk_bf16_f32 v214, v226, v227
	v_cvt_pk_bf16_f32 v215, v230, v231
	v_cvt_pk_bf16_f32 v216, v218, v219
	v_cvt_pk_bf16_f32 v217, v220, v221
	global_store_dwordx4 v[222:223], v[214:217], off offset:1024 sc1
	v_and_b32_e32 v218, 16, v175
	v_lshlrev_b32_e32 v226, 16, v174
	v_and_b32_e32 v215, 0xffff0000, v175
	v_lshlrev_b32_e32 v216, 16, v175
	v_and_b32_e32 v175, 0xffff0000, v188
	v_and_b32_e32 v174, 16, v174
	v_and_b32_e32 v233, 0xffff0000, v180
	v_lshlrev_b32_e32 v214, 16, v189
	v_and_b32_e32 v219, 0xffff0000, v189
	v_pk_mov_b32 v[188:189], v[174:175], v[224:225] op_sel:[1,0]
	v_mov_b32_e32 v174, v76
	v_and_b32_e32 v229, 0xffff0000, v181
	v_lshlrev_b32_e32 v230, 16, v181
	v_mov_b32_e32 v76, v94
	v_lshlrev_b32_e32 v180, 16, v180
	v_and_b32_e32 v181, 0xffff0000, v182
	v_mul_f32_e32 v94, v233, v233
	v_lshlrev_b32_e32 v228, 16, v183
	v_and_b32_e32 v231, 0xffff0000, v183
	v_lshlrev_b32_e32 v232, 16, v182
	v_pk_fma_f32 v[182:183], v[180:181], v[180:181], v[94:95] op_sel_hi:[1,1,0]
	v_mul_f32_e32 v94, v229, v229
	v_pk_fma_f32 v[182:183], v[230:231], v[230:231], v[182:183]
	v_mov_b32_e32 v227, v175
	v_pk_add_f32 v[182:183], v[94:95], v[182:183] op_sel_hi:[0,1]
	v_pk_fma_f32 v[182:183], v[226:227], v[226:227], v[182:183]
	v_mul_f32_e32 v94, v225, v225
	v_mov_b32_e32 v217, v219
	v_pk_add_f32 v[182:183], v[94:95], v[182:183] op_sel_hi:[0,1]
	v_pk_fma_f32 v[182:183], v[216:217], v[216:217], v[182:183]
	v_mul_f32_e32 v94, v215, v215
	v_pk_add_f32 v[182:183], v[94:95], v[182:183] op_sel_hi:[0,1]
	v_pk_fma_f32 v[182:183], v[232:233], v[232:233], v[182:183]
	v_mul_f32_e32 v94, v181, v181
	v_pk_add_f32 v[182:183], v[94:95], v[182:183] op_sel_hi:[0,1]
	v_pk_fma_f32 v[182:183], v[228:229], v[228:229], v[182:183]
	v_mul_f32_e32 v94, v231, v231
	v_pk_add_f32 v[182:183], v[94:95], v[182:183] op_sel_hi:[0,1]
	v_mul_f32_e32 v94, v189, v189
	v_pk_mov_b32 v[218:219], v[218:219], v[214:215] op_sel:[1,0]
	v_pk_add_f32 v[182:183], v[94:95], v[182:183] op_sel_hi:[0,1]
	v_pk_fma_f32 v[182:183], v[188:189], v[188:189], v[182:183]
	v_mul_f32_e32 v94, v219, v219
	v_pk_add_f32 v[182:183], v[94:95], v[182:183] op_sel_hi:[0,1]
	v_pk_fma_f32 v[182:183], v[218:219], v[218:219], v[182:183]
	v_mov_b32_e32 v175, v73
	v_mov_b32_e32 v73, v77
	v_mov_b32_e32 v77, v83
	v_mov_b32_e32 v83, v182
	s_nop 1
	v_permlane32_swap_b32_e32 v182, v83
	v_add_f32_e32 v83, v182, v83
	v_fmamk_f32 v83, v83, 0x3d000000, v204
	v_rsq_f32_e32 v182, v83
	v_mov_b32_e32 v83, v95
	v_mov_b32_e32 v95, v81
	v_mov_b32_e32 v81, v93
	v_mov_b32_e32 v94, v92
	v_pk_mul_f32 v[92:93], v[80:81], v[182:183] op_sel_hi:[1,0]
	v_mov_b32_e32 v220, v78
	v_mov_b32_e32 v221, v75
	v_pk_mul_f32 v[188:189], v[94:95], v[182:183] op_sel_hi:[1,0]
	v_pk_mul_f32 v[92:93], v[92:93], v[180:181]
	v_pk_mul_f32 v[180:181], v[76:77], v[182:183] op_sel_hi:[1,0]
	v_mov_b32_e32 v222, v74
	v_mov_b32_e32 v223, v79
	v_pk_mul_f32 v[188:189], v[188:189], v[232:233]
	v_pk_mul_f32 v[180:181], v[180:181], v[228:229]
	v_pk_mul_f32 v[228:229], v[174:175], v[182:183] op_sel_hi:[1,0]
	v_pk_mul_f32 v[220:221], v[220:221], v[182:183] op_sel_hi:[1,0]
	v_pk_mul_f32 v[218:219], v[82:83], v[182:183] op_sel_hi:[1,0]
	v_pk_mul_f32 v[224:225], v[228:229], v[224:225]
	v_pk_mul_f32 v[228:229], v[72:73], v[182:183] op_sel_hi:[1,0]
	v_pk_mul_f32 v[214:215], v[220:221], v[214:215]
	v_pk_mul_f32 v[182:183], v[222:223], v[182:183] op_sel_hi:[1,0]
	v_mov_b32_e32 v220, v188
	v_mov_b32_e32 v221, v93
	v_pk_mul_f32 v[218:219], v[218:219], v[230:231]
	v_pk_mul_f32 v[182:183], v[182:183], v[216:217]
	v_mov_b32_e32 v216, v92
	v_mov_b32_e32 v217, v189
	v_pk_mul_f32 v[220:221], v[146:147], v[220:221]
	v_pk_mul_f32 v[188:189], v[68:69], v[188:189]
	v_pk_fma_f32 v[216:217], v[144:145], v[216:217], v[220:221] neg_lo:[0,0,1] neg_hi:[0,0,1]
	v_mov_b32_e32 v220, v180
	v_mov_b32_e32 v221, v219
	v_pk_mul_f32 v[226:227], v[228:229], v[226:227]
	v_pk_fma_f32 v[92:93], v[148:149], v[92:93], v[188:189]
	v_mov_b32_e32 v188, v218
	v_mov_b32_e32 v189, v181
	v_pk_mul_f32 v[220:221], v[150:151], v[220:221]
	v_pk_mul_f32 v[180:181], v[20:21], v[180:181]
	v_pk_fma_f32 v[188:189], v[70:71], v[188:189], v[220:221] neg_lo:[0,0,1] neg_hi:[0,0,1]
	v_mov_b32_e32 v220, v224
	v_mov_b32_e32 v221, v227
	v_pk_fma_f32 v[218:219], v[152:153], v[218:219], v[180:181]
	v_mov_b32_e32 v180, v226
	v_mov_b32_e32 v181, v225
	v_pk_mul_f32 v[220:221], v[154:155], v[220:221]
	v_lshl_or_b32 v134, s81, 12, v190
	v_pk_fma_f32 v[220:221], v[22:23], v[180:181], v[220:221] neg_lo:[0,0,1] neg_hi:[0,0,1]
	v_pk_mul_f32 v[180:181], v[16:17], v[224:225]
	v_mov_b32_e32 v224, v214
	v_mov_b32_e32 v225, v183
	v_mov_b32_e32 v135, v173
	v_pk_fma_f32 v[222:223], v[156:157], v[226:227], v[180:181]
	v_mov_b32_e32 v180, v182
	v_mov_b32_e32 v181, v215
	v_pk_mul_f32 v[224:225], v[158:159], v[224:225]
	v_lshl_add_u64 v[134:135], v[110:111], 0, v[134:135]
	v_pk_fma_f32 v[224:225], v[18:19], v[180:181], v[224:225] neg_lo:[0,0,1] neg_hi:[0,0,1]
	v_pk_mul_f32 v[180:181], v[186:187], v[214:215]
	s_or_b32 s70, s70, 1
	v_pk_fma_f32 v[214:215], v[184:185], v[182:183], v[180:181]
	v_cvt_pk_bf16_f32 v180, v216, v217
	v_cvt_pk_bf16_f32 v181, v188, v189
	v_cvt_pk_bf16_f32 v182, v220, v221
	v_cvt_pk_bf16_f32 v183, v224, v225
	v_lshl_add_u64 v[188:189], v[134:135], 0, s[72:73]
	v_and_b32_e32 v225, 0xffff0000, v160
	global_store_dwordx4 v[188:189], v[180:183], off sc1
	v_lshlrev_b32_e32 v220, 16, v161
	v_lshlrev_b32_e32 v224, 16, v162
	v_cvt_pk_bf16_f32 v180, v92, v93
	v_lshlrev_b32_e32 v92, 16, v171
	v_and_b32_e32 v183, 0xffff0000, v171
	v_and_b32_e32 v171, 0xffff0000, v161
	v_lshlrev_b32_e32 v160, 16, v160
	v_and_b32_e32 v161, 0xffff0000, v162
	v_mul_f32_e32 v162, v225, v225
	v_cvt_pk_bf16_f32 v181, v218, v219
	v_and_b32_e32 v93, 0xffff0000, v167
	v_lshlrev_b32_e32 v216, 16, v167
	v_and_b32_e32 v182, 16, v167
	v_lshlrev_b32_e32 v218, 16, v170
	v_and_b32_e32 v167, 0xffff0000, v170
	v_lshlrev_b32_e32 v170, 16, v163
	v_and_b32_e32 v221, 0xffff0000, v163
	v_pk_fma_f32 v[162:163], v[160:161], v[160:161], v[162:163] op_sel_hi:[1,1,0]
	v_mul_f32_e32 v226, v171, v171
	v_pk_fma_f32 v[162:163], v[220:221], v[220:221], v[162:163]
	v_and_b32_e32 v219, 0xffff0000, v166
	v_lshlrev_b32_e32 v166, 16, v166
	v_pk_add_f32 v[162:163], v[226:227], v[162:163] op_sel_hi:[0,1]
	v_pk_fma_f32 v[162:163], v[166:167], v[166:167], v[162:163]
	v_mul_f32_e32 v226, v219, v219
	v_mov_b32_e32 v217, v183
	v_pk_add_f32 v[162:163], v[226:227], v[162:163] op_sel_hi:[0,1]
	v_pk_fma_f32 v[162:163], v[216:217], v[216:217], v[162:163]
	v_mul_f32_e32 v226, v93, v93
	v_pk_add_f32 v[162:163], v[226:227], v[162:163] op_sel_hi:[0,1]
	v_pk_fma_f32 v[162:163], v[224:225], v[224:225], v[162:163]
	v_mul_f32_e32 v226, v161, v161
	v_pk_add_f32 v[162:163], v[226:227], v[162:163] op_sel_hi:[0,1]
	v_pk_fma_f32 v[162:163], v[170:171], v[170:171], v[162:163]
	v_mul_f32_e32 v226, v221, v221
	v_pk_add_f32 v[162:163], v[226:227], v[162:163] op_sel_hi:[0,1]
	v_pk_mov_b32 v[182:183], v[182:183], v[92:93] op_sel:[1,0]
	v_pk_fma_f32 v[162:163], v[218:219], v[218:219], v[162:163]
	v_mul_f32_e32 v226, v167, v167
	v_pk_add_f32 v[162:163], v[226:227], v[162:163] op_sel_hi:[0,1]
	v_mul_f32_e32 v226, v183, v183
	v_pk_add_f32 v[162:163], v[226:227], v[162:163] op_sel_hi:[0,1]
	v_pk_fma_f32 v[162:163], v[182:183], v[182:183], v[162:163]
	s_ashr_i32 s71, s70, 31
	v_mov_b32_e32 v163, v162
	s_nop 1
	v_permlane32_swap_b32_e32 v162, v163
	v_add_f32_e32 v162, v162, v163
	v_fmamk_f32 v162, v162, 0x3d000000, v204
	v_rsq_f32_e32 v162, v162
	s_lshl_b64 s[70:71], s[70:71], 19
	v_cvt_pk_bf16_f32 v182, v222, v223
	v_cvt_pk_bf16_f32 v183, v214, v215
	v_mul_f32_e32 v162, 0x3e8293ee, v162
	v_pk_mul_f32 v[178:179], v[178:179], v[162:163] op_sel_hi:[1,0]
	v_pk_mul_f32 v[88:89], v[88:89], v[162:163] op_sel_hi:[1,0]
	v_pk_mul_f32 v[178:179], v[178:179], v[224:225]
	v_pk_mul_f32 v[88:89], v[88:89], v[160:161]
	v_pk_mul_f32 v[164:165], v[164:165], v[162:163] op_sel_hi:[1,0]
	v_pk_mul_f32 v[160:161], v[176:177], v[162:163] op_sel_hi:[1,0]
	v_pk_mul_f32 v[90:91], v[90:91], v[162:163] op_sel_hi:[1,0]
	v_pk_mul_f32 v[92:93], v[164:165], v[92:93]
	v_mov_b32_e32 v164, v178
	v_mov_b32_e32 v165, v89
	v_pk_mul_f32 v[160:161], v[160:161], v[170:171]
	v_pk_mul_f32 v[90:91], v[90:91], v[220:221]
	v_pk_mul_f32 v[168:169], v[168:169], v[162:163] op_sel_hi:[1,0]
	v_pk_mul_f32 v[84:85], v[84:85], v[162:163] op_sel_hi:[1,0]
	v_pk_mul_f32 v[86:87], v[86:87], v[162:163] op_sel_hi:[1,0]
	v_mov_b32_e32 v162, v88
	v_mov_b32_e32 v163, v179
	v_pk_mul_f32 v[164:165], v[146:147], v[164:165]
	v_pk_mul_f32 v[84:85], v[84:85], v[166:167]
	v_pk_fma_f32 v[162:163], v[144:145], v[162:163], v[164:165] neg_lo:[0,0,1] neg_hi:[0,0,1]
	v_pk_mul_f32 v[164:165], v[68:69], v[178:179]
	v_mov_b32_e32 v166, v160
	v_mov_b32_e32 v167, v91
	v_pk_mul_f32 v[168:169], v[168:169], v[218:219]
	v_pk_fma_f32 v[88:89], v[148:149], v[88:89], v[164:165]
	v_mov_b32_e32 v164, v90
	v_mov_b32_e32 v165, v161
	v_pk_mul_f32 v[166:167], v[150:151], v[166:167]
	v_pk_mul_f32 v[160:161], v[20:21], v[160:161]
	v_pk_fma_f32 v[164:165], v[70:71], v[164:165], v[166:167] neg_lo:[0,0,1] neg_hi:[0,0,1]
	v_mov_b32_e32 v166, v168
	v_mov_b32_e32 v167, v85
	v_pk_mul_f32 v[86:87], v[86:87], v[216:217]
	v_pk_fma_f32 v[90:91], v[152:153], v[90:91], v[160:161]
	v_mov_b32_e32 v160, v84
	v_mov_b32_e32 v161, v169
	v_pk_mul_f32 v[166:167], v[154:155], v[166:167]
	v_lshl_add_u64 v[170:171], v[108:109], 0, s[70:71]
	v_pk_fma_f32 v[160:161], v[22:23], v[160:161], v[166:167] neg_lo:[0,0,1] neg_hi:[0,0,1]
	v_pk_mul_f32 v[166:167], v[16:17], v[168:169]
	v_mov_b32_e32 v168, v92
	v_mov_b32_e32 v169, v87
	v_pk_fma_f32 v[166:167], v[156:157], v[84:85], v[166:167]
	v_mov_b32_e32 v84, v86
	v_mov_b32_e32 v85, v93
	v_pk_mul_f32 v[168:169], v[158:159], v[168:169]
	global_store_dwordx4 v[188:189], v[180:183], off offset:2048 sc1
	v_pk_fma_f32 v[168:169], v[18:19], v[84:85], v[168:169] neg_lo:[0,0,1] neg_hi:[0,0,1]
	v_pk_mul_f32 v[84:85], v[186:187], v[92:93]
	s_nop 0
	v_pk_fma_f32 v[92:93], v[184:185], v[86:87], v[84:85]
	v_cvt_pk_bf16_f32 v84, v162, v163
	v_cvt_pk_bf16_f32 v85, v164, v165
	v_cvt_pk_bf16_f32 v86, v160, v161
	v_cvt_pk_bf16_f32 v87, v168, v169
	v_lshl_add_u64 v[160:161], v[170:171], 0, v[172:173]
	global_store_dwordx4 v[160:161], v[84:87], off sc1
	v_lshlrev_b32_e32 v162, 16, v137
	v_lshlrev_b32_e32 v168, 16, v138
	v_cvt_pk_bf16_f32 v84, v88, v89
	v_cvt_pk_bf16_f32 v85, v90, v91
	v_cvt_pk_bf16_f32 v86, v166, v167
	v_cvt_pk_bf16_f32 v87, v92, v93
	global_store_dwordx4 v[160:161], v[84:87], off offset:1024 sc1
	v_and_b32_e32 v161, 0xffff0000, v137
	v_and_b32_e32 v169, 0xffff0000, v136
	v_and_b32_e32 v86, 0xffff0000, v143
	v_lshlrev_b32_e32 v136, 16, v136
	v_and_b32_e32 v137, 0xffff0000, v138
	v_lshlrev_b32_e32 v85, 16, v143
	v_mov_b32_e32 v84, v86
	v_lshlrev_b32_e32 v160, 16, v139
	v_and_b32_e32 v163, 0xffff0000, v139
	v_pk_mul_f32 v[138:139], v[136:137], v[136:137]
	v_pk_mul_f32 v[170:171], v[168:169], v[168:169]
	v_pk_mul_f32 v[88:89], v[84:85], v[84:85]
	v_pk_mul_f32 v[164:165], v[162:163], v[162:163]
	v_add_f32_e32 v84, v138, v171
	v_pk_mul_f32 v[166:167], v[160:161], v[160:161]
	v_add_f32_e32 v84, v164, v84
	v_lshlrev_b32_e32 v92, 16, v140
	v_add_f32_e32 v84, v167, v84
	v_and_b32_e32 v91, 0xffff0000, v140
	v_fmac_f32_e32 v84, v92, v92
	v_lshlrev_b32_e32 v172, 16, v141
	v_fmac_f32_e32 v84, v91, v91
	v_and_b32_e32 v87, 0xffff0000, v141
	v_fmac_f32_e32 v84, v172, v172
	v_fmac_f32_e32 v84, v87, v87
	v_add_f32_e32 v84, v170, v84
	v_lshlrev_b32_e32 v90, 16, v142
	v_and_b32_e32 v141, 0xffff0000, v142
	v_and_b32_e32 v140, 16, v140
	v_add_f32_e32 v84, v139, v84
	v_pk_mov_b32 v[142:143], v[140:141], v[90:91] op_sel:[1,0]
	v_add_f32_e32 v84, v166, v84
	v_pk_mul_f32 v[142:143], v[142:143], v[142:143]
	v_add_f32_e32 v84, v165, v84
	v_add_f32_e32 v84, v143, v84
	v_add_f32_e32 v84, v142, v84
	v_add_f32_e32 v84, v89, v84
	v_add_f32_e32 v84, v88, v84
	v_mov_b32_e32 v88, v84
	s_nop 1
	v_permlane32_swap_b32_e32 v84, v88
	v_add_f32_e32 v84, v84, v88
	v_fmamk_f32 v84, v84, 0x3d000000, v204
	v_rsq_f32_e32 v84, v84
	v_mov_b32_e32 v88, v79
	v_mov_b32_e32 v89, v75
	v_mov_b32_e32 v93, v141
	v_pk_mul_f32 v[94:95], v[94:95], v[84:85] op_sel_hi:[1,0]
	v_pk_mul_f32 v[80:81], v[80:81], v[84:85] op_sel_hi:[1,0]
	v_pk_mul_f32 v[94:95], v[94:95], v[168:169]
	v_pk_mul_f32 v[80:81], v[80:81], v[136:137]
	v_mul_f32_e32 v75, v78, v84
	v_mul_f32_e32 v74, v74, v84
	v_pk_mul_f32 v[76:77], v[76:77], v[84:85] op_sel_hi:[1,0]
	v_pk_mul_f32 v[82:83], v[82:83], v[84:85] op_sel_hi:[1,0]
	v_pk_mul_f32 v[136:137], v[174:175], v[84:85] op_sel_hi:[1,0]
	v_pk_mul_f32 v[72:73], v[72:73], v[84:85] op_sel_hi:[1,0]
	v_mul_f32_e32 v78, v75, v85
	v_pk_mul_f32 v[84:85], v[88:89], v[84:85] op_sel_hi:[1,0]
	v_mov_b32_e32 v88, v94
	v_mov_b32_e32 v89, v81
	v_pk_mul_f32 v[76:77], v[76:77], v[160:161]
	v_pk_mul_f32 v[82:83], v[82:83], v[162:163]
	v_pk_mul_f32 v[84:85], v[84:85], v[86:87]
	v_mov_b32_e32 v86, v80
	v_mov_b32_e32 v87, v95
	v_pk_mul_f32 v[88:89], v[146:147], v[88:89]
	v_pk_mul_f32 v[68:69], v[68:69], v[94:95]
	v_pk_fma_f32 v[86:87], v[144:145], v[86:87], v[88:89] neg_lo:[0,0,1] neg_hi:[0,0,1]
	v_mov_b32_e32 v88, v76
	v_mov_b32_e32 v89, v83
	v_pk_mul_f32 v[90:91], v[136:137], v[90:91]
	v_pk_mul_f32 v[72:73], v[72:73], v[92:93]
	v_pk_fma_f32 v[68:69], v[148:149], v[80:81], v[68:69]
	v_mov_b32_e32 v80, v82
	v_mov_b32_e32 v81, v77
	v_pk_mul_f32 v[88:89], v[150:151], v[88:89]
	v_pk_mul_f32 v[20:21], v[20:21], v[76:77]
	v_pk_fma_f32 v[70:71], v[70:71], v[80:81], v[88:89] neg_lo:[0,0,1] neg_hi:[0,0,1]
	v_mov_b32_e32 v80, v90
	v_mov_b32_e32 v81, v73
	v_mov_b32_e32 v76, v72
	v_mov_b32_e32 v77, v91
	v_pk_mul_f32 v[80:81], v[154:155], v[80:81]
	v_mov_b32_e32 v79, v84
	v_mul_f32_e32 v74, v74, v172
	v_pk_fma_f32 v[22:23], v[22:23], v[76:77], v[80:81] neg_lo:[0,0,1] neg_hi:[0,0,1]
	v_pk_mul_f32 v[16:17], v[16:17], v[90:91]
	v_mov_b32_e32 v75, v85
	v_pk_mul_f32 v[76:77], v[158:159], v[78:79]
	v_pk_mul_f32 v[14:15], v[14:15], v[84:85]
	v_pk_fma_f32 v[16:17], v[156:157], v[72:73], v[16:17]
	v_mul_f32_e32 v12, v12, v78
	v_mul_f32_e32 v72, v13, v74
	v_pk_fma_f32 v[18:19], v[18:19], v[74:75], v[76:77] neg_lo:[0,0,1] neg_hi:[0,0,1]
	v_mov_b32_e32 v13, v14
	v_mov_b32_e32 v73, v15
	v_pk_fma_f32 v[20:21], v[152:153], v[82:83], v[20:21]
	v_pk_add_f32 v[72:73], v[12:13], v[72:73]
	v_cvt_pk_bf16_f32 v12, v86, v87
	v_cvt_pk_bf16_f32 v13, v70, v71
	v_cvt_pk_bf16_f32 v14, v22, v23
	v_cvt_pk_bf16_f32 v15, v18, v19
	v_lshl_add_u64 v[74:75], v[134:135], 0, s[70:71]
	global_store_dwordx4 v[74:75], v[12:15], off sc1
	v_cvt_pk_bf16_f32 v68, v68, v69
	v_cvt_pk_bf16_f32 v69, v20, v21
	v_cvt_pk_bf16_f32 v70, v16, v17
	v_mfma_f32_32x32x16_bf16 v[8:23], v[8:11], v[24:27], 0
	v_cvt_pk_bf16_f32 v71, v72, v73
	global_store_dwordx4 v[74:75], v[68:71], off offset:2048 sc1
	s_lshl_b32 s70, s82, 2
	s_add_i32 s70, s70, s75
	s_ashr_i32 s71, s70, 31
	s_lshl_b64 s[70:71], s[70:71], 20
	s_add_u32 s72, s78, s70
	v_mfma_f32_32x32x16_bf16 v[8:23], v[4:7], v[28:31], v[8:23]
	v_and_b32_e32 v79, 0xffff0000, v122
	v_and_b32_e32 v81, 0xffff0000, v118
	s_addc_u32 s73, s79, s71
	v_lshl_or_b32 v172, s81, 13, v192
	v_lshlrev_b32_e32 v78, 16, v122
	v_lshlrev_b32_e32 v80, 16, v118
	v_mov_b32_e32 v88, v81
	s_nop 4
	v_cvt_pk_bf16_f32 v68, v8, v9
	v_cvt_pk_bf16_f32 v69, v10, v11
	v_cvt_pk_bf16_f32 v70, v12, v13
	v_cvt_pk_bf16_f32 v71, v14, v15
	v_mfma_f32_32x32x16_bf16 v[0:15], v[0:3], v[24:27], 0
	v_mov_b32_e32 v89, v79
	v_lshl_add_u64 v[72:73], s[72:73], 0, v[172:173]
	v_lshlrev_b32_e32 v74, 16, v123
	v_lshlrev_b32_e32 v76, 16, v119
	v_mov_b32_e32 v86, v80
	v_mov_b32_e32 v87, v78
	v_pk_mul_f32 v[88:89], v[88:89], v[88:89]
	v_mfma_f32_32x32x16_bf16 v[0:15], v[64:67], v[28:31], v[0:15]
	v_lshl_add_u64 v[72:73], v[72:73], 0, v[106:107]
	v_and_b32_e32 v75, 0xffff0000, v123
	v_and_b32_e32 v77, 0xffff0000, v119
	v_mov_b32_e32 v82, v76
	v_mov_b32_e32 v83, v74
	v_pk_fma_f32 v[86:87], v[86:87], v[86:87], v[88:89]
	global_store_dwordx4 v[72:73], v[68:71], off sc1
	s_nop 4
	v_cvt_pk_bf16_f32 v0, v0, v1
	v_cvt_pk_bf16_f32 v1, v2, v3
	v_cvt_pk_bf16_f32 v2, v4, v5
	v_cvt_pk_bf16_f32 v3, v6, v7
	v_lshlrev_b32_e32 v68, 16, v126
	v_lshlrev_b32_e32 v70, 16, v120
	v_mov_b32_e32 v84, v77
	v_mov_b32_e32 v85, v75
	v_pk_fma_f32 v[82:83], v[82:83], v[82:83], v[86:87]
	global_store_dwordx4 v[72:73], v[0:3], off offset:512 sc1
	v_and_b32_e32 v69, 0xffff0000, v126
	v_and_b32_e32 v71, 0xffff0000, v120
	v_mov_b32_e32 v2, v70
	v_mov_b32_e32 v3, v68
	v_pk_fma_f32 v[82:83], v[84:85], v[84:85], v[82:83]
	v_lshlrev_b32_e32 v64, 16, v127
	v_and_b32_e32 v65, 0xffff0000, v127
	v_lshlrev_b32_e32 v66, 16, v121
	v_mov_b32_e32 v126, v71
	v_mov_b32_e32 v127, v69
	v_pk_fma_f32 v[2:3], v[2:3], v[2:3], v[82:83]
	v_cvt_pk_bf16_f32 v16, v16, v17
	v_cvt_pk_bf16_f32 v17, v18, v19
	v_cvt_pk_bf16_f32 v18, v20, v21
	v_cvt_pk_bf16_f32 v19, v22, v23
	v_and_b32_e32 v67, 0xffff0000, v121
	v_mov_b32_e32 v122, v66
	v_mov_b32_e32 v123, v64
	v_pk_fma_f32 v[2:3], v[126:127], v[126:127], v[2:3]
	global_store_dwordx4 v[72:73], v[16:19], off offset:2048 sc1
	v_lshlrev_b32_e32 v20, 16, v130
	v_lshlrev_b32_e32 v22, 16, v124
	v_lshlrev_b32_e32 v18, 16, v125
	v_and_b32_e32 v19, 0xffff0000, v125
	v_and_b32_e32 v23, 0xffff0000, v124
	v_mov_b32_e32 v124, v67
	v_mov_b32_e32 v125, v65
	v_pk_fma_f32 v[2:3], v[122:123], v[122:123], v[2:3]
	v_and_b32_e32 v21, 0xffff0000, v130
	v_mov_b32_e32 v118, v22
	v_mov_b32_e32 v119, v20
	v_pk_fma_f32 v[2:3], v[124:125], v[124:125], v[2:3]
	v_lshlrev_b32_e32 v16, 16, v131
	v_mov_b32_e32 v120, v23
	v_mov_b32_e32 v121, v21
	v_pk_fma_f32 v[2:3], v[118:119], v[118:119], v[2:3]
	v_and_b32_e32 v17, 0xffff0000, v131
	v_mov_b32_e32 v92, v18
	v_mov_b32_e32 v93, v16
	v_pk_fma_f32 v[2:3], v[120:121], v[120:121], v[2:3]
	v_cvt_pk_bf16_f32 v0, v8, v9
	v_cvt_pk_bf16_f32 v1, v10, v11
	v_lshlrev_b32_e32 v8, 16, v132
	v_lshlrev_b32_e32 v10, 16, v128
	v_mov_b32_e32 v94, v19
	v_mov_b32_e32 v95, v17
	v_pk_fma_f32 v[2:3], v[92:93], v[92:93], v[2:3]
	v_and_b32_e32 v9, 0xffff0000, v132
	v_and_b32_e32 v11, 0xffff0000, v128
	v_mov_b32_e32 v88, v10
	v_mov_b32_e32 v89, v8
	v_pk_fma_f32 v[2:3], v[94:95], v[94:95], v[2:3]
	v_lshlrev_b32_e32 v4, 16, v133
	v_lshlrev_b32_e32 v6, 16, v129
	v_mov_b32_e32 v90, v11
	v_mov_b32_e32 v91, v9
	v_pk_fma_f32 v[2:3], v[88:89], v[88:89], v[2:3]
	v_and_b32_e32 v5, 0xffff0000, v133
	v_and_b32_e32 v7, 0xffff0000, v129
	v_mov_b32_e32 v84, v6
	v_mov_b32_e32 v85, v4
	v_pk_fma_f32 v[2:3], v[90:91], v[90:91], v[2:3]
	v_mov_b32_e32 v86, v7
	v_mov_b32_e32 v87, v5
	v_pk_fma_f32 v[2:3], v[84:85], v[84:85], v[2:3]
	v_lshl_or_b32 v172, s80, 12, v191
	v_pk_fma_f32 v[2:3], v[86:87], v[86:87], v[2:3]
	s_add_i32 s33, s33, s76
	v_pk_add_f32 v[2:3], v[2:3], v[2:3] op_sel:[0,1] op_sel_hi:[1,0]
	s_cmpk_gt_u32 s33, 0xff
	v_mov_b32_e32 v3, v2
	s_nop 1
	v_permlane32_swap_b32_e32 v2, v3
	v_add_f32_e32 v2, v2, v3
	v_fmamk_f32 v2, v2, 0x3c800000, v204
	v_rsq_f32_e32 v82, v2
	v_cvt_pk_bf16_f32 v2, v12, v13
	v_cvt_pk_bf16_f32 v3, v14, v15
	global_store_dwordx4 v[72:73], v[0:3], off offset:2560 sc1
	s_nop 1
	v_mul_f32_e32 v0, 0x3e38aa3b, v82
	v_pk_mul_f32 v[40:41], v[40:41], v[0:1] op_sel_hi:[1,0]
	v_pk_mul_f32 v[32:33], v[32:33], v[0:1] op_sel_hi:[1,0]
	v_pk_mul_f32 v[22:23], v[40:41], v[22:23]
	v_pk_mul_f32 v[40:41], v[44:45], v[0:1] op_sel_hi:[1,0]
	v_pk_mul_f32 v[10:11], v[32:33], v[10:11]
	v_pk_mul_f32 v[32:33], v[36:37], v[0:1] op_sel_hi:[1,0]
	v_pk_mul_f32 v[2:3], v[56:57], v[0:1] op_sel_hi:[1,0]
	v_pk_mul_f32 v[14:15], v[58:59], v[0:1] op_sel_hi:[1,0]
	v_pk_mul_f32 v[48:49], v[48:49], v[0:1] op_sel_hi:[1,0]
	v_pk_mul_f32 v[50:51], v[50:51], v[0:1] op_sel_hi:[1,0]
	v_pk_mul_f32 v[20:21], v[40:41], v[20:21]
	v_pk_mul_f32 v[40:41], v[42:43], v[0:1] op_sel_hi:[1,0]
	v_pk_mul_f32 v[8:9], v[32:33], v[8:9]
	v_pk_mul_f32 v[32:33], v[34:35], v[0:1] op_sel_hi:[1,0]
	v_pk_mul_f32 v[2:3], v[2:3], v[80:81]
	v_pk_mul_f32 v[12:13], v[60:61], v[0:1] op_sel_hi:[1,0]
	v_pk_mul_f32 v[14:15], v[14:15], v[76:77]
	v_pk_mul_f32 v[56:57], v[62:63], v[0:1] op_sel_hi:[1,0]
	v_pk_mul_f32 v[48:49], v[48:49], v[70:71]
	v_pk_mul_f32 v[52:53], v[52:53], v[0:1] op_sel_hi:[1,0]
	v_pk_mul_f32 v[50:51], v[50:51], v[66:67]
	v_pk_mul_f32 v[54:55], v[54:55], v[0:1] op_sel_hi:[1,0]
	v_pk_mul_f32 v[18:19], v[40:41], v[18:19]
	v_pk_mul_f32 v[40:41], v[46:47], v[0:1] op_sel_hi:[1,0]
	v_pk_mul_f32 v[6:7], v[32:33], v[6:7]
	v_pk_mul_f32 v[0:1], v[38:39], v[0:1] op_sel_hi:[1,0]
	v_lshl_add_u64 v[32:33], v[112:113], 0, s[70:71]
	v_pk_mul_f32 v[4:5], v[0:1], v[4:5]
	v_cvt_pk_bf16_f32 v0, v2, v3
	v_cvt_pk_bf16_f32 v1, v14, v15
	v_cvt_pk_bf16_f32 v2, v48, v49
	v_cvt_pk_bf16_f32 v3, v50, v51
	v_lshl_add_u64 v[14:15], v[32:33], 0, v[172:173]
	v_pk_mul_f32 v[12:13], v[12:13], v[78:79]
	v_pk_mul_f32 v[56:57], v[56:57], v[74:75]
	v_pk_mul_f32 v[52:53], v[52:53], v[68:69]
	v_pk_mul_f32 v[54:55], v[54:55], v[64:65]
	global_store_dwordx4 v[14:15], v[0:3], off sc1
	v_pk_mul_f32 v[16:17], v[40:41], v[16:17]
	s_nop 0
	v_cvt_pk_bf16_f32 v0, v22, v23
	v_cvt_pk_bf16_f32 v1, v18, v19
	v_cvt_pk_bf16_f32 v2, v10, v11
	v_cvt_pk_bf16_f32 v3, v6, v7
	global_store_dwordx4 v[14:15], v[0:3], off offset:1024 sc1
	s_nop 1
	v_cvt_pk_bf16_f32 v0, v12, v13
	v_cvt_pk_bf16_f32 v1, v56, v57
	v_cvt_pk_bf16_f32 v2, v52, v53
	v_cvt_pk_bf16_f32 v3, v54, v55
	global_store_dwordx4 v[14:15], v[0:3], off offset:2048 sc1
	s_nop 1
	v_cvt_pk_bf16_f32 v0, v20, v21
	v_cvt_pk_bf16_f32 v1, v16, v17
	v_cvt_pk_bf16_f32 v2, v8, v9
	v_cvt_pk_bf16_f32 v3, v4, v5
	global_store_dwordx4 v[14:15], v[0:3], off offset:3072 sc1
	s_cbranch_scc0 .LBB0_338

.LBB0_342:
	s_ashr_i32 s2, s6, 6
	s_bfe_u32 s4, s6, 0x10005
	s_ashr_i32 s3, s2, 31
	s_bfe_u32 s16, s6, 0x20003
	s_lshl_b64 s[18:19], s[2:3], 9
	s_lshl_b32 s3, s4, 8
	s_bfe_u32 s15, s6, 0x10002
	s_or_b32 s3, s18, s3
	s_lshl_b32 s5, s16, 6
	s_or_b32 s3, s3, s5
	s_lshl_b32 s17, s15, 5
	s_or_b32 s3, s3, s17
	v_mov_b32_e32 v1, s19
	v_or_b32_e32 v0, s3, v96
	v_lshlrev_b64 v[0:1], 10, v[0:1]
	v_lshl_add_u64 v[0:1], s[0:1], 0, v[0:1]
	v_lshl_add_u64 v[2:3], v[0:1], 0, v[172:173]
	global_load_dwordx2 v[42:43], v[2:3], off
	global_load_dwordx2 v[44:45], v[2:3], off offset:16
	global_load_dwordx2 v[46:47], v[2:3], off offset:32
	global_load_dwordx2 v[48:49], v[2:3], off offset:48
	global_load_dwordx2 v[50:51], v[2:3], off offset:64
	global_load_dwordx2 v[62:63], v[2:3], off offset:80
	global_load_dwordx2 v[64:65], v[2:3], off offset:96
	s_nop 0
	global_load_dwordx2 v[2:3], v[2:3], off offset:112
	s_and_b32 s18, s6, 0xffffffc0
	s_ashr_i32 s19, s18, 31
	v_lshl_add_u64 v[56:57], s[18:19], 2, v[26:27]
	global_load_dwordx4 v[4:7], v[56:57], off
	global_load_dwordx4 v[8:11], v[56:57], off offset:32
	global_load_dwordx4 v[12:15], v[56:57], off offset:64
	global_load_dwordx4 v[52:55], v[56:57], off offset:96
	global_load_dwordx4 v[30:33], v[56:57], off offset:128
	global_load_dwordx4 v[34:37], v[56:57], off offset:160
	global_load_dwordx4 v[38:41], v[56:57], off offset:192
	s_nop 0
	global_load_dwordx4 v[56:59], v[56:57], off offset:224
	s_lshl_b32 s2, s2, 3
	s_lshl_b32 s3, s4, 2
	s_or_b32 s2, s3, s2
	s_or_b32 s2, s2, s14
	s_ashr_i32 s3, s2, 31
	s_lshl_b64 s[2:3], s[2:3], 15
	s_add_u32 s4, s7, s2
	s_addc_u32 s5, s9, s3
	s_lshl_b32 s16, s16, 3
	s_add_u32 s2, s10, s2
	s_addc_u32 s3, s11, s3
	s_add_i32 s6, s6, s13
	s_waitcnt vmcnt(0)
	v_lshlrev_b32_e32 v68, 16, v46
	v_lshlrev_b32_e32 v82, 16, v43
	v_and_b32_e32 v85, 0xffff0000, v50
	v_lshlrev_b32_e32 v61, 16, v63
	v_and_b32_e32 v67, 0xffff0000, v63
	v_lshlrev_b32_e32 v80, 16, v62
	v_and_b32_e32 v81, 0xffff0000, v62
	v_lshlrev_b32_e32 v62, 16, v51
	v_and_b32_e32 v63, 0xffff0000, v51
	v_and_b32_e32 v51, 0xffff0000, v42
	v_lshlrev_b32_e32 v84, 16, v50
	v_lshlrev_b32_e32 v50, 16, v42
	v_mov_b32_e32 v90, v51
	v_mov_b32_e32 v91, v85
	v_mov_b32_e32 v88, v50
	v_mov_b32_e32 v89, v84
	v_pk_mul_f32 v[90:91], v[90:91], v[90:91]
	v_and_b32_e32 v83, 0xffff0000, v43
	v_mov_b32_e32 v42, v82
	v_mov_b32_e32 v43, v62
	v_pk_fma_f32 v[88:89], v[88:89], v[88:89], v[90:91]
	v_lshlrev_b32_e32 v74, 16, v48
	v_and_b32_e32 v76, 0xffff0000, v48
	v_lshlrev_b32_e32 v48, 16, v44
	v_mov_b32_e32 v86, v83
	v_mov_b32_e32 v87, v63
	v_pk_fma_f32 v[42:43], v[42:43], v[42:43], v[88:89]
	v_lshlrev_b32_e32 v60, 16, v45
	v_and_b32_e32 v66, 0xffff0000, v45
	v_lshlrev_b32_e32 v75, 16, v2
	v_and_b32_e32 v77, 0xffff0000, v2
	v_lshlrev_b32_e32 v78, 16, v49
	v_and_b32_e32 v2, 0xffff0000, v49
	v_and_b32_e32 v49, 0xffff0000, v44
	v_mov_b32_e32 v44, v48
	v_mov_b32_e32 v45, v80
	v_pk_fma_f32 v[42:43], v[86:87], v[86:87], v[42:43]
	v_lshlrev_b32_e32 v69, 16, v64
	v_and_b32_e32 v71, 0xffff0000, v64
	v_and_b32_e32 v70, 0xffff0000, v46
	v_lshlrev_b32_e32 v72, 16, v47
	v_and_b32_e32 v64, 0xffff0000, v47
	v_mov_b32_e32 v46, v49
	v_mov_b32_e32 v47, v81
	v_pk_fma_f32 v[42:43], v[44:45], v[44:45], v[42:43]
	v_lshlrev_b32_e32 v73, 16, v65
	v_pk_fma_f32 v[42:43], v[46:47], v[46:47], v[42:43]
	v_and_b32_e32 v65, 0xffff0000, v65
	v_pk_fma_f32 v[42:43], v[60:61], v[60:61], v[42:43]
	v_lshlrev_b32_e32 v79, 16, v3
	v_pk_fma_f32 v[42:43], v[66:67], v[66:67], v[42:43]
	v_and_b32_e32 v3, 0xffff0000, v3
	v_pk_fma_f32 v[42:43], v[68:69], v[68:69], v[42:43]
	s_nop 0
	v_pk_fma_f32 v[42:43], v[70:71], v[70:71], v[42:43]
	s_nop 0
	v_pk_fma_f32 v[42:43], v[72:73], v[72:73], v[42:43]
	s_nop 0
	v_pk_fma_f32 v[42:43], v[64:65], v[64:65], v[42:43]
	s_nop 0
	v_pk_fma_f32 v[42:43], v[74:75], v[74:75], v[42:43]
	s_nop 0
	v_pk_fma_f32 v[42:43], v[76:77], v[76:77], v[42:43]
	s_nop 0
	v_pk_fma_f32 v[42:43], v[78:79], v[78:79], v[42:43]
	s_nop 0
	v_pk_fma_f32 v[42:43], v[2:3], v[2:3], v[42:43]
	s_nop 0
	v_pk_add_f32 v[42:43], v[42:43], v[42:43] op_sel:[0,1] op_sel_hi:[1,0]
	s_nop 0
	v_mov_b32_e32 v29, v42
	s_nop 1
	v_permlane32_swap_b32_e32 v42, v29
	v_add_f32_e32 v29, v42, v29
	v_fmamk_f32 v29, v29, 0x3c800000, v204
	v_rsq_f32_e32 v86, v29
	v_or_b32_e32 v29, s16, v97
	v_pk_mul_f32 v[6:7], v[6:7], v[86:87] op_sel_hi:[1,0]
	v_pk_mul_f32 v[4:5], v[4:5], v[86:87] op_sel_hi:[1,0]
	v_pk_mul_f32 v[46:47], v[6:7], v[82:83]
	v_pk_mul_f32 v[6:7], v[32:33], v[86:87] op_sel_hi:[1,0]
	v_pk_mul_f32 v[8:9], v[8:9], v[86:87] op_sel_hi:[1,0]
	v_pk_mul_f32 v[14:15], v[14:15], v[86:87] op_sel_hi:[1,0]
	v_mov_b32_e32 v32, v72
	v_mov_b32_e32 v33, v64
	v_pk_mul_f32 v[42:43], v[4:5], v[50:51]
	v_pk_mul_f32 v[4:5], v[30:31], v[86:87] op_sel_hi:[1,0]
	v_pk_mul_f32 v[48:49], v[8:9], v[48:49]
	v_pk_mul_f32 v[8:9], v[34:35], v[86:87] op_sel_hi:[1,0]
	v_pk_mul_f32 v[10:11], v[10:11], v[86:87] op_sel_hi:[1,0]
	v_mov_b32_e32 v30, v60
	v_mov_b32_e32 v31, v66
	v_pk_mul_f32 v[34:35], v[14:15], v[32:33]
	v_pk_mul_f32 v[32:33], v[52:53], v[86:87] op_sel_hi:[1,0]
	v_or_b32_e32 v52, s17, v96
	v_pk_mul_f32 v[50:51], v[10:11], v[30:31]
	v_pk_mul_f32 v[10:11], v[36:37], v[86:87] op_sel_hi:[1,0]
	v_pk_mul_f32 v[12:13], v[12:13], v[86:87] op_sel_hi:[1,0]
	v_mov_b32_e32 v30, v68
	v_mov_b32_e32 v31, v70
	v_mov_b32_e32 v36, v74
	v_mov_b32_e32 v37, v76
	v_lshlrev_b32_e32 v52, 4, v52
	v_mov_b32_e32 v53, v173
	v_pk_mul_f32 v[30:31], v[12:13], v[30:31]
	v_pk_mul_f32 v[12:13], v[38:39], v[86:87] op_sel_hi:[1,0]
	v_pk_mul_f32 v[38:39], v[32:33], v[36:37]
	v_pk_mul_f32 v[32:33], v[56:57], v[86:87] op_sel_hi:[1,0]
	v_lshl_add_u64 v[56:57], s[4:5], 0, v[52:53]
	v_cvt_pk_bf16_f32 v52, v42, v43
	v_lshlrev_b32_e32 v42, 10, v29
	v_mov_b32_e32 v43, v173
	v_pk_mul_f32 v[4:5], v[4:5], v[84:85]
	v_pk_mul_f32 v[6:7], v[6:7], v[62:63]
	v_pk_mul_f32 v[8:9], v[8:9], v[80:81]
	v_mov_b32_e32 v66, v61
	v_lshl_add_u64 v[42:43], v[56:57], 0, v[42:43]
	v_pk_mul_f32 v[10:11], v[10:11], v[66:67]
	v_mov_b32_e32 v70, v69
	v_pk_mul_f32 v[14:15], v[40:41], v[86:87] op_sel_hi:[1,0]
	v_mov_b32_e32 v64, v73
	v_mov_b32_e32 v76, v75
	v_mov_b32_e32 v40, v78
	v_mov_b32_e32 v41, v2
	v_pk_mul_f32 v[44:45], v[54:55], v[86:87] op_sel_hi:[1,0]
	v_mov_b32_e32 v2, v79
	v_pk_mul_f32 v[36:37], v[58:59], v[86:87] op_sel_hi:[1,0]
	v_cvt_pk_bf16_f32 v4, v4, v5
	v_cvt_pk_bf16_f32 v5, v6, v7
	v_cvt_pk_bf16_f32 v6, v8, v9
	v_add_co_u32_e32 v8, vcc, s23, v42
	v_pk_mul_f32 v[12:13], v[12:13], v[70:71]
	v_pk_mul_f32 v[14:15], v[14:15], v[64:65]
	v_pk_mul_f32 v[32:33], v[32:33], v[76:77]
	v_cvt_pk_bf16_f32 v53, v46, v47
	v_cvt_pk_bf16_f32 v46, v30, v31
	v_pk_mul_f32 v[30:31], v[44:45], v[40:41]
	v_cvt_pk_bf16_f32 v7, v10, v11
	v_addc_co_u32_e32 v9, vcc, 0, v43, vcc
	v_pk_mul_f32 v[2:3], v[36:37], v[2:3]
	v_cvt_pk_bf16_f32 v54, v48, v49
	v_cvt_pk_bf16_f32 v55, v50, v51
	v_cvt_pk_bf16_f32 v47, v34, v35
	v_cvt_pk_bf16_f32 v48, v38, v39
	v_cvt_pk_bf16_f32 v49, v30, v31
	global_store_dwordx4 v[8:9], v[4:7], off sc1
	v_mov_b32_e32 v29, v173
	global_store_dwordx4 v[42:43], v[52:55], off sc1
	v_cvt_pk_bf16_f32 v4, v12, v13
	v_cvt_pk_bf16_f32 v5, v14, v15
	v_cvt_pk_bf16_f32 v6, v32, v33
	v_cvt_pk_bf16_f32 v7, v2, v3
	global_store_dwordx4 v[42:43], v[46:49], off offset:2048 sc1
	global_store_dwordx4 v[8:9], v[4:7], off offset:2048 sc1
	v_lshl_add_u64 v[0:1], v[0:1], 0, v[28:29]
	global_load_dwordx4 v[2:5], v[0:1], off offset:512
	global_load_dwordx4 v[30:33], v[0:1], off offset:544
	global_load_dwordx4 v[34:37], v[0:1], off offset:576
	global_load_dwordx4 v[38:41], v[0:1], off offset:608
	s_lshl_b32 s4, s15, 2
	s_or_b32 s4, s4, s16
	v_or_b32_e32 v0, s4, v97
	v_lshlrev_b32_e32 v0, 10, v0
	v_mov_b32_e32 v1, v173
	v_lshl_add_u64 v[42:43], s[2:3], 0, v[0:1]
	s_waitcnt vmcnt(3)
	v_mfma_f32_32x32x16_bf16 v[0:15], v[2:5], v[16:19], 0
	s_cmpk_lt_i32 s6, 0x80
	s_waitcnt vmcnt(2)
	v_mfma_f32_32x32x16_bf16 v[0:15], v[30:33], v[20:23], v[0:15]
	v_lshl_add_u64 v[30:31], v[42:43], 0, v[24:25]
	s_nop 10
	v_cvt_pk_bf16_f32 v0, v0, v1
	v_cvt_pk_bf16_f32 v1, v2, v3
	v_cvt_pk_bf16_f32 v2, v4, v5
	v_cvt_pk_bf16_f32 v3, v6, v7
	global_store_dwordx4 v[30:31], v[0:3], off sc1
	s_nop 1
	v_cvt_pk_bf16_f32 v0, v8, v9
	v_cvt_pk_bf16_f32 v1, v10, v11
	v_cvt_pk_bf16_f32 v2, v12, v13
	v_cvt_pk_bf16_f32 v3, v14, v15
	global_store_dwordx4 v[30:31], v[0:3], off offset:2048 sc1
	s_waitcnt vmcnt(3)
	s_nop 0
	v_mfma_f32_32x32x16_bf16 v[0:15], v[34:37], v[16:19], 0
	s_waitcnt vmcnt(2)
	v_mfma_f32_32x32x16_bf16 v[0:15], v[38:41], v[20:23], v[0:15]
	s_nop 11
	v_cvt_pk_bf16_f32 v0, v0, v1
	v_cvt_pk_bf16_f32 v1, v2, v3
	v_cvt_pk_bf16_f32 v2, v4, v5
	v_cvt_pk_bf16_f32 v3, v6, v7
	global_store_dwordx4 v[30:31], v[0:3], off offset:512 sc1
	s_nop 1
	v_cvt_pk_bf16_f32 v0, v8, v9
	v_cvt_pk_bf16_f32 v1, v10, v11
	v_cvt_pk_bf16_f32 v2, v12, v13
	v_cvt_pk_bf16_f32 v3, v14, v15
	global_store_dwordx4 v[30:31], v[0:3], off offset:2560 sc1
	s_cbranch_scc1 .LBB0_342

.LBB0_353:
	s_add_i32 s11, s31, s34
	s_ashr_i32 s10, s11, 5
	s_and_b32 s10, s10, -8
	s_and_b32 s40, s11, 0xff
	s_or_b32 s10, s10, s30
	s_bfe_u32 s35, s11, 0x70001
	s_waitcnt vmcnt(0)
	v_and_b32_e32 v1, 0xffff0000, v32
	v_lshlrev_b32_e32 v0, 16, v32
	v_mul_f32_e32 v2, v1, v1
	v_fmac_f32_e32 v2, v0, v0
	v_lshlrev_b32_e32 v0, 16, v33
	v_fmac_f32_e32 v2, v0, v0
	v_and_b32_e32 v0, 0xffff0000, v33
	v_fmac_f32_e32 v2, v0, v0
	v_lshlrev_b32_e32 v0, 16, v34
	v_fmac_f32_e32 v2, v0, v0
	v_and_b32_e32 v0, 0xffff0000, v34
	v_fmac_f32_e32 v2, v0, v0
	v_lshlrev_b32_e32 v0, 16, v35
	v_fmac_f32_e32 v2, v0, v0
	v_and_b32_e32 v0, 0xffff0000, v35
	v_fmac_f32_e32 v2, v0, v0
	v_lshlrev_b32_e32 v0, 16, v152
	v_fmac_f32_e32 v2, v0, v0
	v_and_b32_e32 v0, 0xffff0000, v152
	v_fmac_f32_e32 v2, v0, v0
	v_lshlrev_b32_e32 v0, 16, v153
	v_fmac_f32_e32 v2, v0, v0
	v_and_b32_e32 v0, 0xffff0000, v153
	v_fmac_f32_e32 v2, v0, v0
	v_lshlrev_b32_e32 v0, 16, v154
	v_fmac_f32_e32 v2, v0, v0
	v_and_b32_e32 v0, 0xffff0000, v154
	v_fmac_f32_e32 v2, v0, v0
	v_lshlrev_b32_e32 v0, 16, v155
	v_fmac_f32_e32 v2, v0, v0
	v_and_b32_e32 v0, 0xffff0000, v155
	v_fmac_f32_e32 v2, v0, v0
	v_lshlrev_b32_e32 v0, 16, v148
	v_fmac_f32_e32 v2, v0, v0
	v_and_b32_e32 v0, 0xffff0000, v148
	v_fmac_f32_e32 v2, v0, v0
	v_lshlrev_b32_e32 v0, 16, v149
	v_fmac_f32_e32 v2, v0, v0
	v_and_b32_e32 v0, 0xffff0000, v149
	v_fmac_f32_e32 v2, v0, v0
	v_lshlrev_b32_e32 v0, 16, v150
	v_fmac_f32_e32 v2, v0, v0
	v_and_b32_e32 v0, 0xffff0000, v150
	v_fmac_f32_e32 v2, v0, v0
	v_lshlrev_b32_e32 v0, 16, v151
	v_fmac_f32_e32 v2, v0, v0
	v_and_b32_e32 v0, 0xffff0000, v151
	v_fmac_f32_e32 v2, v0, v0
	v_lshlrev_b32_e32 v0, 16, v144
	v_fmac_f32_e32 v2, v0, v0
	v_and_b32_e32 v0, 0xffff0000, v144
	v_fmac_f32_e32 v2, v0, v0
	v_lshlrev_b32_e32 v0, 16, v145
	v_fmac_f32_e32 v2, v0, v0
	v_and_b32_e32 v0, 0xffff0000, v145
	v_fmac_f32_e32 v2, v0, v0
	v_lshlrev_b32_e32 v0, 16, v146
	v_fmac_f32_e32 v2, v0, v0
	v_and_b32_e32 v0, 0xffff0000, v146
	v_fmac_f32_e32 v2, v0, v0
	v_lshlrev_b32_e32 v0, 16, v147
	v_fmac_f32_e32 v2, v0, v0
	v_and_b32_e32 v0, 0xffff0000, v147
	v_fmac_f32_e32 v2, v0, v0
	v_lshlrev_b32_e32 v0, 16, v140
	v_fmac_f32_e32 v2, v0, v0
	v_and_b32_e32 v0, 0xffff0000, v140
	v_fmac_f32_e32 v2, v0, v0
	v_lshlrev_b32_e32 v0, 16, v141
	v_fmac_f32_e32 v2, v0, v0
	v_and_b32_e32 v0, 0xffff0000, v141
	v_fmac_f32_e32 v2, v0, v0
	v_lshlrev_b32_e32 v0, 16, v142
	v_fmac_f32_e32 v2, v0, v0
	v_and_b32_e32 v0, 0xffff0000, v142
	v_fmac_f32_e32 v2, v0, v0
	v_lshlrev_b32_e32 v0, 16, v143
	v_fmac_f32_e32 v2, v0, v0
	v_and_b32_e32 v0, 0xffff0000, v143
	v_fmac_f32_e32 v2, v0, v0
	v_lshlrev_b32_e32 v0, 16, v136
	v_fmac_f32_e32 v2, v0, v0
	v_and_b32_e32 v0, 0xffff0000, v136
	v_fmac_f32_e32 v2, v0, v0
	v_lshlrev_b32_e32 v0, 16, v137
	v_fmac_f32_e32 v2, v0, v0
	v_and_b32_e32 v0, 0xffff0000, v137
	v_fmac_f32_e32 v2, v0, v0
	v_lshlrev_b32_e32 v0, 16, v138
	v_fmac_f32_e32 v2, v0, v0
	v_and_b32_e32 v0, 0xffff0000, v138
	v_fmac_f32_e32 v2, v0, v0
	v_lshlrev_b32_e32 v0, 16, v139
	v_fmac_f32_e32 v2, v0, v0
	v_and_b32_e32 v0, 0xffff0000, v139
	v_fmac_f32_e32 v2, v0, v0
	v_lshlrev_b32_e32 v0, 16, v132
	v_fmac_f32_e32 v2, v0, v0
	v_and_b32_e32 v0, 0xffff0000, v132
	v_fmac_f32_e32 v2, v0, v0
	v_lshlrev_b32_e32 v0, 16, v133
	v_fmac_f32_e32 v2, v0, v0
	v_and_b32_e32 v0, 0xffff0000, v133
	v_fmac_f32_e32 v2, v0, v0
	v_lshlrev_b32_e32 v0, 16, v134
	v_fmac_f32_e32 v2, v0, v0
	v_and_b32_e32 v0, 0xffff0000, v134
	v_fmac_f32_e32 v2, v0, v0
	v_lshlrev_b32_e32 v0, 16, v135
	v_fmac_f32_e32 v2, v0, v0
	v_and_b32_e32 v0, 0xffff0000, v135
	v_fmac_f32_e32 v2, v0, v0
	v_lshlrev_b32_e32 v0, 16, v128
	v_fmac_f32_e32 v2, v0, v0
	v_and_b32_e32 v0, 0xffff0000, v128
	v_fmac_f32_e32 v2, v0, v0
	v_lshlrev_b32_e32 v0, 16, v129
	v_fmac_f32_e32 v2, v0, v0
	v_and_b32_e32 v0, 0xffff0000, v129
	v_fmac_f32_e32 v2, v0, v0
	v_lshlrev_b32_e32 v0, 16, v130
	v_fmac_f32_e32 v2, v0, v0
	v_and_b32_e32 v0, 0xffff0000, v130
	v_fmac_f32_e32 v2, v0, v0
	v_lshlrev_b32_e32 v0, 16, v131
	v_fmac_f32_e32 v2, v0, v0
	v_and_b32_e32 v0, 0xffff0000, v131
	v_fmac_f32_e32 v2, v0, v0
	v_lshlrev_b32_e32 v0, 16, v124
	v_fmac_f32_e32 v2, v0, v0
	v_and_b32_e32 v0, 0xffff0000, v124
	v_fmac_f32_e32 v2, v0, v0
	v_lshlrev_b32_e32 v0, 16, v125
	v_fmac_f32_e32 v2, v0, v0
	v_and_b32_e32 v0, 0xffff0000, v125
	v_fmac_f32_e32 v2, v0, v0
	v_lshlrev_b32_e32 v0, 16, v126
	v_fmac_f32_e32 v2, v0, v0
	v_and_b32_e32 v0, 0xffff0000, v126
	v_fmac_f32_e32 v2, v0, v0
	v_lshlrev_b32_e32 v0, 16, v127
	v_fmac_f32_e32 v2, v0, v0
	v_and_b32_e32 v0, 0xffff0000, v127
	v_fmac_f32_e32 v2, v0, v0
	v_lshlrev_b32_e32 v0, 16, v120
	v_fmac_f32_e32 v2, v0, v0
	v_and_b32_e32 v0, 0xffff0000, v120
	v_fmac_f32_e32 v2, v0, v0
	v_lshlrev_b32_e32 v0, 16, v121
	v_fmac_f32_e32 v2, v0, v0
	v_and_b32_e32 v0, 0xffff0000, v121
	v_fmac_f32_e32 v2, v0, v0
	v_lshlrev_b32_e32 v0, 16, v122
	v_fmac_f32_e32 v2, v0, v0
	v_and_b32_e32 v0, 0xffff0000, v122
	v_fmac_f32_e32 v2, v0, v0
	v_lshlrev_b32_e32 v0, 16, v123
	v_fmac_f32_e32 v2, v0, v0
	v_and_b32_e32 v0, 0xffff0000, v123
	v_fmac_f32_e32 v2, v0, v0
	v_lshlrev_b32_e32 v0, 16, v116
	v_fmac_f32_e32 v2, v0, v0
	v_and_b32_e32 v0, 0xffff0000, v116
	v_fmac_f32_e32 v2, v0, v0
	v_lshlrev_b32_e32 v0, 16, v117
	v_fmac_f32_e32 v2, v0, v0
	v_and_b32_e32 v0, 0xffff0000, v117
	v_fmac_f32_e32 v2, v0, v0
	v_lshlrev_b32_e32 v0, 16, v118
	v_fmac_f32_e32 v2, v0, v0
	v_and_b32_e32 v0, 0xffff0000, v118
	v_fmac_f32_e32 v2, v0, v0
	v_lshlrev_b32_e32 v0, 16, v119
	v_fmac_f32_e32 v2, v0, v0
	v_and_b32_e32 v0, 0xffff0000, v119
	v_fmac_f32_e32 v2, v0, v0
	v_lshlrev_b32_e32 v0, 16, v112
	v_fmac_f32_e32 v2, v0, v0
	v_and_b32_e32 v0, 0xffff0000, v112
	v_fmac_f32_e32 v2, v0, v0
	v_lshlrev_b32_e32 v0, 16, v113
	v_fmac_f32_e32 v2, v0, v0
	v_and_b32_e32 v0, 0xffff0000, v113
	v_fmac_f32_e32 v2, v0, v0
	v_lshlrev_b32_e32 v0, 16, v114
	v_fmac_f32_e32 v2, v0, v0
	v_and_b32_e32 v0, 0xffff0000, v114
	v_fmac_f32_e32 v2, v0, v0
	v_lshlrev_b32_e32 v0, 16, v115
	v_fmac_f32_e32 v2, v0, v0
	v_and_b32_e32 v0, 0xffff0000, v115
	v_fmac_f32_e32 v2, v0, v0
	v_lshlrev_b32_e32 v0, 16, v108
	v_fmac_f32_e32 v2, v0, v0
	v_and_b32_e32 v0, 0xffff0000, v108
	v_fmac_f32_e32 v2, v0, v0
	v_lshlrev_b32_e32 v0, 16, v109
	v_fmac_f32_e32 v2, v0, v0
	v_and_b32_e32 v0, 0xffff0000, v109
	v_fmac_f32_e32 v2, v0, v0
	v_lshlrev_b32_e32 v0, 16, v110
	v_fmac_f32_e32 v2, v0, v0
	v_and_b32_e32 v0, 0xffff0000, v110
	v_fmac_f32_e32 v2, v0, v0
	v_lshlrev_b32_e32 v0, 16, v111
	v_fmac_f32_e32 v2, v0, v0
	v_and_b32_e32 v0, 0xffff0000, v111
	v_fmac_f32_e32 v2, v0, v0
	v_lshlrev_b32_e32 v0, 16, v60
	v_fmac_f32_e32 v2, v0, v0
	v_and_b32_e32 v0, 0xffff0000, v60
	v_fmac_f32_e32 v2, v0, v0
	v_lshlrev_b32_e32 v0, 16, v61
	v_fmac_f32_e32 v2, v0, v0
	v_and_b32_e32 v0, 0xffff0000, v61
	v_fmac_f32_e32 v2, v0, v0
	v_lshlrev_b32_e32 v0, 16, v62
	v_fmac_f32_e32 v2, v0, v0
	v_and_b32_e32 v0, 0xffff0000, v62
	v_fmac_f32_e32 v2, v0, v0
	v_lshlrev_b32_e32 v0, 16, v63
	v_fmac_f32_e32 v2, v0, v0
	v_and_b32_e32 v0, 0xffff0000, v63
	v_fmac_f32_e32 v2, v0, v0
	v_lshlrev_b32_e32 v0, 16, v56
	v_fmac_f32_e32 v2, v0, v0
	v_and_b32_e32 v0, 0xffff0000, v56
	v_fmac_f32_e32 v2, v0, v0
	v_lshlrev_b32_e32 v0, 16, v57
	v_fmac_f32_e32 v2, v0, v0
	v_and_b32_e32 v0, 0xffff0000, v57
	v_fmac_f32_e32 v2, v0, v0
	v_lshlrev_b32_e32 v0, 16, v58
	v_fmac_f32_e32 v2, v0, v0
	v_and_b32_e32 v0, 0xffff0000, v58
	v_fmac_f32_e32 v2, v0, v0
	v_lshlrev_b32_e32 v0, 16, v59
	v_fmac_f32_e32 v2, v0, v0
	v_and_b32_e32 v0, 0xffff0000, v59
	v_fmac_f32_e32 v2, v0, v0
	v_lshlrev_b32_e32 v0, 16, v52
	v_fmac_f32_e32 v2, v0, v0
	v_and_b32_e32 v0, 0xffff0000, v52
	v_fmac_f32_e32 v2, v0, v0
	v_lshlrev_b32_e32 v0, 16, v53
	v_fmac_f32_e32 v2, v0, v0
	v_and_b32_e32 v0, 0xffff0000, v53
	v_fmac_f32_e32 v2, v0, v0
	v_lshlrev_b32_e32 v0, 16, v54
	v_fmac_f32_e32 v2, v0, v0
	v_and_b32_e32 v0, 0xffff0000, v54
	v_fmac_f32_e32 v2, v0, v0
	v_and_b32_e32 v1, 0xffff0000, v55
	v_lshlrev_b32_e32 v0, 16, v55
	v_pk_mul_f32 v[0:1], v[0:1], v[0:1]
	s_nop 0
	v_add_f32_e32 v0, v0, v2
	v_add_f32_e32 v0, v1, v0
	v_mov_b32_e32 v1, v0
	s_nop 1
	v_permlane32_swap_b32_e32 v0, v1
	v_add_f32_e32 v0, v0, v1
	v_fmamk_f32 v172, v0, 0x3b800000, v204
	ds_read_b128 v[0:3], v169
	ds_read_b128 v[16:19], v169 offset:1024
	ds_read_b128 v[20:23], v169 offset:2048
	ds_read_b128 v[24:27], v169 offset:3072
	ds_read_b128 v[28:31], v169 offset:4096
	s_waitcnt lgkmcnt(0)
	v_mfma_f32_32x32x16_bf16 v[0:15], v[0:3], v[32:35], 0
	v_mfma_f32_32x32x16_bf16 v[0:15], v[16:19], v[152:155], v[0:15]
	ds_read_b128 v[16:19], v169 offset:5120
	v_mfma_f32_32x32x16_bf16 v[0:15], v[20:23], v[148:151], v[0:15]
	ds_read_b128 v[20:23], v169 offset:6144
	v_mfma_f32_32x32x16_bf16 v[0:15], v[24:27], v[144:147], v[0:15]
	ds_read_b128 v[24:27], v169 offset:7168
	v_mfma_f32_32x32x16_bf16 v[0:15], v[28:31], v[140:143], v[0:15]
	ds_read_b128 v[28:31], v169 offset:8192
	s_waitcnt lgkmcnt(3)
	v_mfma_f32_32x32x16_bf16 v[0:15], v[16:19], v[136:139], v[0:15]
	ds_read_b128 v[16:19], v169 offset:9216
	s_waitcnt lgkmcnt(3)
	v_mfma_f32_32x32x16_bf16 v[0:15], v[20:23], v[132:135], v[0:15]
	ds_read_b128 v[20:23], v169 offset:10240
	s_waitcnt lgkmcnt(3)
	v_mfma_f32_32x32x16_bf16 v[0:15], v[24:27], v[128:131], v[0:15]
	ds_read_b128 v[24:27], v169 offset:11264
	s_waitcnt lgkmcnt(3)
	v_mfma_f32_32x32x16_bf16 v[0:15], v[28:31], v[124:127], v[0:15]
	ds_read_b128 v[28:31], v169 offset:12288
	s_waitcnt lgkmcnt(3)
	v_mfma_f32_32x32x16_bf16 v[0:15], v[16:19], v[120:123], v[0:15]
	ds_read_b128 v[16:19], v169 offset:13312
	s_waitcnt lgkmcnt(3)
	v_mfma_f32_32x32x16_bf16 v[0:15], v[20:23], v[116:119], v[0:15]
	ds_read_b128 v[20:23], v169 offset:14336
	s_waitcnt lgkmcnt(3)
	v_mfma_f32_32x32x16_bf16 v[0:15], v[24:27], v[112:115], v[0:15]
	ds_read_b128 v[24:27], v169 offset:15360
	s_waitcnt lgkmcnt(3)
	v_mfma_f32_32x32x16_bf16 v[0:15], v[28:31], v[108:111], v[0:15]
	ds_read_b128 v[28:31], v169 offset:16384
	ds_read_b128 v[36:39], v169 offset:17408
	s_waitcnt lgkmcnt(4)
	v_mfma_f32_32x32x16_bf16 v[0:15], v[16:19], v[60:63], v[0:15]
	ds_read_b128 v[40:43], v169 offset:18432
	s_waitcnt lgkmcnt(4)
	v_mfma_f32_32x32x16_bf16 v[0:15], v[20:23], v[56:59], v[0:15]
	ds_read_b128 v[44:47], v169 offset:19456
	s_waitcnt lgkmcnt(4)
	v_mfma_f32_32x32x16_bf16 v[0:15], v[24:27], v[52:55], v[0:15]
	ds_read_b128 v[224:227], v169 offset:20480
	s_waitcnt lgkmcnt(4)
	v_mfma_f32_32x32x16_bf16 v[16:31], v[28:31], v[32:35], 0
	s_waitcnt lgkmcnt(3)
	v_mfma_f32_32x32x16_bf16 v[16:31], v[36:39], v[152:155], v[16:31]
	ds_read_b128 v[36:39], v169 offset:21504
	s_waitcnt lgkmcnt(3)
	v_mfma_f32_32x32x16_bf16 v[16:31], v[40:43], v[148:151], v[16:31]
	ds_read_b128 v[40:43], v169 offset:22528
	s_waitcnt lgkmcnt(3)
	v_mfma_f32_32x32x16_bf16 v[16:31], v[44:47], v[144:147], v[16:31]
	ds_read_b128 v[44:47], v169 offset:23552
	s_waitcnt lgkmcnt(3)
	v_mfma_f32_32x32x16_bf16 v[16:31], v[224:227], v[140:143], v[16:31]
	ds_read_b128 v[224:227], v169 offset:24576
	s_waitcnt lgkmcnt(3)
	v_mfma_f32_32x32x16_bf16 v[16:31], v[36:39], v[136:139], v[16:31]
	ds_read_b128 v[36:39], v169 offset:25600
	s_waitcnt lgkmcnt(3)
	v_mfma_f32_32x32x16_bf16 v[16:31], v[40:43], v[132:135], v[16:31]
	ds_read_b128 v[40:43], v169 offset:26624
	s_waitcnt lgkmcnt(3)
	v_mfma_f32_32x32x16_bf16 v[16:31], v[44:47], v[128:131], v[16:31]
	ds_read_b128 v[44:47], v169 offset:27648
	s_waitcnt lgkmcnt(3)
	v_mfma_f32_32x32x16_bf16 v[16:31], v[224:227], v[124:127], v[16:31]
	ds_read_b128 v[224:227], v169 offset:28672
	s_waitcnt lgkmcnt(3)
	v_mfma_f32_32x32x16_bf16 v[16:31], v[36:39], v[120:123], v[16:31]
	ds_read_b128 v[36:39], v169 offset:29696
	s_waitcnt lgkmcnt(3)
	v_mfma_f32_32x32x16_bf16 v[16:31], v[40:43], v[116:119], v[16:31]
	ds_read_b128 v[40:43], v169 offset:30720
	s_waitcnt lgkmcnt(3)
	v_mfma_f32_32x32x16_bf16 v[16:31], v[44:47], v[112:115], v[16:31]
	ds_read_b128 v[44:47], v169 offset:31744
	s_waitcnt lgkmcnt(3)
	v_mfma_f32_32x32x16_bf16 v[16:31], v[224:227], v[108:111], v[16:31]
	ds_read_b128 v[224:227], v169 offset:32768
	ds_read_b128 v[228:231], v169 offset:33792
	s_waitcnt lgkmcnt(4)
	v_mfma_f32_32x32x16_bf16 v[16:31], v[36:39], v[60:63], v[16:31]
	ds_read_b128 v[232:235], v169 offset:34816
	s_waitcnt lgkmcnt(4)
	v_mfma_f32_32x32x16_bf16 v[16:31], v[40:43], v[56:59], v[16:31]
	ds_read_b128 v[236:239], v169 offset:35840
	s_waitcnt lgkmcnt(4)
	v_mfma_f32_32x32x16_bf16 v[16:31], v[44:47], v[52:55], v[16:31]
	s_waitcnt lgkmcnt(3)
	v_mfma_f32_32x32x16_bf16 v[32:47], v[224:227], v[32:35], 0
	ds_read_b128 v[224:227], v169 offset:36864
	s_waitcnt lgkmcnt(3)
	v_mfma_f32_32x32x16_bf16 v[32:47], v[228:231], v[152:155], v[32:47]
	ds_read_b128 v[152:155], v169 offset:37888
	s_waitcnt lgkmcnt(3)
	v_mfma_f32_32x32x16_bf16 v[32:47], v[232:235], v[148:151], v[32:47]
	ds_read_b128 v[148:151], v169 offset:38912
	s_waitcnt lgkmcnt(3)
	v_mfma_f32_32x32x16_bf16 v[32:47], v[236:239], v[144:147], v[32:47]
	ds_read_b128 v[144:147], v169 offset:39936
	s_waitcnt lgkmcnt(3)
	v_mfma_f32_32x32x16_bf16 v[32:47], v[224:227], v[140:143], v[32:47]
	ds_read_b128 v[140:143], v169 offset:40960
	s_waitcnt lgkmcnt(3)
	v_mfma_f32_32x32x16_bf16 v[32:47], v[152:155], v[136:139], v[32:47]
	ds_read_b128 v[136:139], v169 offset:41984
	s_waitcnt lgkmcnt(3)
	v_mfma_f32_32x32x16_bf16 v[32:47], v[148:151], v[132:135], v[32:47]
	ds_read_b128 v[132:135], v169 offset:43008
	s_waitcnt lgkmcnt(3)
	v_mfma_f32_32x32x16_bf16 v[32:47], v[144:147], v[128:131], v[32:47]
	ds_read_b128 v[128:131], v169 offset:44032
	s_waitcnt lgkmcnt(3)
	v_mfma_f32_32x32x16_bf16 v[32:47], v[140:143], v[124:127], v[32:47]
	ds_read_b128 v[124:127], v169 offset:45056
	s_waitcnt lgkmcnt(3)
	v_mfma_f32_32x32x16_bf16 v[32:47], v[136:139], v[120:123], v[32:47]
	ds_read_b128 v[120:123], v169 offset:46080
	s_waitcnt lgkmcnt(3)
	v_mfma_f32_32x32x16_bf16 v[32:47], v[132:135], v[116:119], v[32:47]
	ds_read_b128 v[116:119], v169 offset:47104
	s_waitcnt lgkmcnt(3)
	v_mfma_f32_32x32x16_bf16 v[32:47], v[128:131], v[112:115], v[32:47]
	ds_read_b128 v[112:115], v169 offset:48128
	s_waitcnt lgkmcnt(3)
	v_mfma_f32_32x32x16_bf16 v[32:47], v[124:127], v[108:111], v[32:47]
	s_waitcnt lgkmcnt(2)
	v_mfma_f32_32x32x16_bf16 v[32:47], v[120:123], v[60:63], v[32:47]
	s_waitcnt lgkmcnt(1)
	v_mfma_f32_32x32x16_bf16 v[32:47], v[116:119], v[56:59], v[32:47]
	s_waitcnt lgkmcnt(0)
	v_mfma_f32_32x32x16_bf16 v[32:47], v[112:115], v[52:55], v[32:47]
	v_mul_f32_e32 v53, v1, v1
	v_mul_f32_e32 v54, v17, v17
	v_fmac_f32_e32 v53, v0, v0
	v_fmac_f32_e32 v54, v16, v16
	v_fmac_f32_e32 v53, v2, v2
	v_fmac_f32_e32 v54, v18, v18
	v_fmac_f32_e32 v53, v3, v3
	v_fmac_f32_e32 v54, v19, v19
	v_fmac_f32_e32 v53, v4, v4
	v_fmac_f32_e32 v54, v20, v20
	v_fmac_f32_e32 v53, v5, v5
	v_fmac_f32_e32 v54, v21, v21
	v_fmac_f32_e32 v53, v6, v6
	v_fmac_f32_e32 v54, v22, v22
	v_fmac_f32_e32 v53, v7, v7
	v_fmac_f32_e32 v54, v23, v23
	v_fmac_f32_e32 v53, v8, v8
	v_fmac_f32_e32 v54, v24, v24
	v_fmac_f32_e32 v53, v9, v9
	v_fmac_f32_e32 v54, v25, v25
	v_fmac_f32_e32 v53, v10, v10
	v_fmac_f32_e32 v54, v26, v26
	v_fmac_f32_e32 v53, v11, v11
	v_fmac_f32_e32 v54, v27, v27
	v_fmac_f32_e32 v53, v12, v12
	v_fmac_f32_e32 v54, v28, v28
	v_fmac_f32_e32 v53, v13, v13
	v_fmac_f32_e32 v54, v29, v29
	v_fmac_f32_e32 v53, v14, v14
	v_fmac_f32_e32 v54, v30, v30
	v_fmac_f32_e32 v53, v15, v15
	v_fmac_f32_e32 v54, v31, v31
	v_add_f32_e32 v53, v53, v54
	v_mul_f32_e32 v54, v33, v33
	v_fmac_f32_e32 v54, v32, v32
	v_fmac_f32_e32 v54, v34, v34
	v_fmac_f32_e32 v54, v35, v35
	v_fmac_f32_e32 v54, v36, v36
	v_fmac_f32_e32 v54, v37, v37
	v_fmac_f32_e32 v54, v38, v38
	v_fmac_f32_e32 v54, v39, v39
	v_fmac_f32_e32 v54, v40, v40
	v_fmac_f32_e32 v54, v41, v41
	v_fmac_f32_e32 v54, v42, v42
	v_fmac_f32_e32 v54, v43, v43
	v_fmac_f32_e32 v54, v44, v44
	v_fmac_f32_e32 v54, v45, v45
	v_fmac_f32_e32 v54, v46, v46
	v_fmac_f32_e32 v54, v47, v47
	v_rsq_f32_e32 v52, v172
	v_add_f32_e32 v53, v53, v54
	v_mov_b32_e32 v54, v53
	s_nop 1
	v_permlane32_swap_b32_e32 v53, v54
	v_add_f32_e32 v53, v53, v54
	v_mul_f32_e32 v53, v52, v53
	v_mul_f32_e32 v53, v52, v53
	v_fmamk_f32 v53, v53, 0x3c2aaaab, v204
	v_rsq_f32_e32 v53, v53
	v_add_u32_e32 v116, 0, v188
	v_mul_f32_e32 v52, 0x3e16c73f, v52
	s_mov_b64 s[44:45], s[4:5]
	v_add_u32_e32 v61, 0x14000, v116
	v_mul_f32_e32 v60, v52, v53
	ds_read_b128 v[52:55], v61
	ds_read_b128 v[56:59], v61 offset:32
	s_ashr_i32 s11, s10, 31
	s_mul_i32 s42, s10, 0x180000
	s_mul_hi_i32 s41, s10, 0x180000
	s_waitcnt lgkmcnt(1)
	v_pk_mul_f32 v[52:53], v[52:53], v[60:61] op_sel_hi:[1,0]
	s_waitcnt lgkmcnt(0)
	v_pk_mul_f32 v[56:57], v[56:57], v[60:61] op_sel_hi:[1,0]
	v_pk_mul_f32 v[52:53], v[0:1], v[52:53]
	v_pk_mul_f32 v[0:1], v[54:55], v[60:61] op_sel_hi:[1,0]
	v_pk_mul_f32 v[56:57], v[4:5], v[56:57]
	v_pk_mul_f32 v[54:55], v[2:3], v[0:1]
	ds_read_b128 v[0:3], v61 offset:64
	v_pk_mul_f32 v[4:5], v[58:59], v[60:61] op_sel_hi:[1,0]
	s_add_u32 s44, s44, s42
	v_pk_mul_f32 v[58:59], v[6:7], v[4:5]
	ds_read_b128 v[4:7], v61 offset:96
	s_waitcnt lgkmcnt(1)
	v_pk_mul_f32 v[0:1], v[0:1], v[60:61] op_sel_hi:[1,0]
	s_mul_i32 s40, s40, 12
	v_pk_mul_f32 v[8:9], v[8:9], v[0:1]
	v_pk_mul_f32 v[0:1], v[2:3], v[60:61] op_sel_hi:[1,0]
	s_addc_u32 s45, s45, s41
	v_or_b32_e32 v108, s40, v165
	v_pk_mul_f32 v[10:11], v[10:11], v[0:1]
	s_waitcnt lgkmcnt(0)
	v_pk_mul_f32 v[0:1], v[4:5], v[60:61] op_sel_hi:[1,0]
	v_lshl_add_u64 v[62:63], s[44:45], 0, v[158:159]
	v_pk_mul_f32 v[4:5], v[12:13], v[0:1]
	v_pk_mul_f32 v[0:1], v[6:7], v[60:61] op_sel_hi:[1,0]
	v_lshlrev_b32_e32 v172, 9, v108
	v_pk_mul_f32 v[6:7], v[14:15], v[0:1]
	v_cvt_pk_bf16_f32 v0, v52, v53
	v_cvt_pk_bf16_f32 v1, v54, v55
	v_cvt_pk_bf16_f32 v2, v56, v57
	v_cvt_pk_bf16_f32 v3, v58, v59
	v_lshl_add_u64 v[52:53], v[62:63], 0, v[172:173]
	global_store_dwordx4 v[52:53], v[0:3], off sc1
	v_mov_b32_e32 v108, v72
	v_mov_b32_e32 v109, v74
	v_cvt_pk_bf16_f32 v0, v8, v9
	v_cvt_pk_bf16_f32 v1, v10, v11
	v_cvt_pk_bf16_f32 v2, v4, v5
	v_cvt_pk_bf16_f32 v3, v6, v7
	ds_read_b128 v[4:7], v61 offset:128
	global_store_dwordx4 v[52:53], v[0:3], off offset:1024 sc1
	ds_read_b128 v[0:3], v61 offset:160
	ds_read_b128 v[8:11], v61 offset:192
	ds_read_b128 v[12:15], v61 offset:224
	v_mov_b32_e32 v74, v73
	v_mov_b32_e32 v72, v68
	s_waitcnt lgkmcnt(3)
	v_pk_mul_f32 v[4:5], v[60:61], v[4:5] op_sel_hi:[0,1]
	s_waitcnt lgkmcnt(2)
	v_pk_mul_f32 v[0:1], v[60:61], v[0:1] op_sel_hi:[0,1]
	v_pk_mul_f32 v[4:5], v[16:17], v[4:5]
	v_pk_mul_f32 v[6:7], v[60:61], v[6:7] op_sel_hi:[0,1]
	v_pk_mul_f32 v[16:17], v[20:21], v[0:1]
	v_pk_mul_f32 v[0:1], v[60:61], v[2:3] op_sel_hi:[0,1]
	v_pk_mul_f32 v[6:7], v[18:19], v[6:7]
	v_pk_mul_f32 v[18:19], v[22:23], v[0:1]
	s_waitcnt lgkmcnt(1)
	v_pk_mul_f32 v[0:1], v[60:61], v[8:9] op_sel_hi:[0,1]
	v_pk_mul_f32 v[8:9], v[24:25], v[0:1]
	v_pk_mul_f32 v[0:1], v[60:61], v[10:11] op_sel_hi:[0,1]
	v_pk_mul_f32 v[10:11], v[26:27], v[0:1]
	s_waitcnt lgkmcnt(0)
	v_pk_mul_f32 v[0:1], v[60:61], v[12:13] op_sel_hi:[0,1]
	v_pk_mul_f32 v[12:13], v[28:29], v[0:1]
	v_pk_mul_f32 v[0:1], v[60:61], v[14:15] op_sel_hi:[0,1]
	v_pk_mul_f32 v[20:21], v[30:31], v[0:1]
	v_cvt_pk_bf16_f32 v0, v4, v5
	v_cvt_pk_bf16_f32 v1, v6, v7
	v_cvt_pk_bf16_f32 v2, v16, v17
	v_cvt_pk_bf16_f32 v3, v18, v19
	global_store_dwordx4 v[52:53], v[0:3], off offset:2048 sc1
	v_mov_b32_e32 v73, v70
	v_mov_b32_e32 v70, v69
	v_cvt_pk_bf16_f32 v0, v8, v9
	v_cvt_pk_bf16_f32 v1, v10, v11
	v_cvt_pk_bf16_f32 v2, v12, v13
	ds_read_b128 v[4:7], v61 offset:288
	ds_read_b128 v[8:11], v61 offset:256
	ds_read_b128 v[12:15], v61 offset:352
	ds_read_b128 v[16:19], v61 offset:320
	v_cvt_pk_bf16_f32 v3, v20, v21
	global_store_dwordx4 v[52:53], v[0:3], off offset:3072 sc1
	v_mov_b32_e32 v110, v49
	v_mov_b32_e32 v111, v51
	s_waitcnt lgkmcnt(0)
	v_pk_mul_f32 v[2:3], v[60:61], v[16:17] op_sel_hi:[0,1]
	v_pk_mul_f32 v[0:1], v[60:61], v[8:9] op_sel_hi:[0,1]
	v_pk_mul_f32 v[2:3], v[40:41], v[2:3]
	v_pk_mul_f32 v[0:1], v[32:33], v[0:1]
	v_pk_mul_f32 v[8:9], v[74:75], v[2:3]
	v_pk_mul_f32 v[2:3], v[108:109], v[2:3]
	v_pk_fma_f32 v[8:9], v[108:109], v[0:1], v[8:9] neg_lo:[0,0,1] neg_hi:[0,0,1]
	v_pk_fma_f32 v[16:17], v[74:75], v[0:1], v[2:3]
	v_pk_mul_f32 v[2:3], v[60:61], v[18:19] op_sel_hi:[0,1]
	v_pk_mul_f32 v[0:1], v[60:61], v[10:11] op_sel_hi:[0,1]
	v_pk_mul_f32 v[2:3], v[42:43], v[2:3]
	v_pk_mul_f32 v[0:1], v[34:35], v[0:1]
	v_pk_mul_f32 v[10:11], v[70:71], v[2:3]
	v_pk_mul_f32 v[2:3], v[72:73], v[2:3]
	v_pk_fma_f32 v[10:11], v[72:73], v[0:1], v[10:11] neg_lo:[0,0,1] neg_hi:[0,0,1]
	v_pk_fma_f32 v[18:19], v[70:71], v[0:1], v[2:3]
	v_mov_b32_e32 v0, v4
	v_mov_b32_e32 v1, v13
	v_pk_mul_f32 v[0:1], v[60:61], v[0:1] op_sel_hi:[0,1]
	v_mov_b32_e32 v2, v36
	v_mov_b32_e32 v3, v45
	v_mov_b32_e32 v13, v5
	v_pk_mul_f32 v[0:1], v[2:3], v[0:1]
	v_pk_mul_f32 v[2:3], v[60:61], v[12:13] op_sel_hi:[0,1]
	v_mov_b32_e32 v45, v37
	v_pk_mul_f32 v[2:3], v[44:45], v[2:3]
	v_mov_b32_e32 v13, v1
	v_mov_b32_e32 v12, v2
	v_mov_b32_e32 v68, v48
	v_mov_b32_e32 v69, v50
	v_mov_b32_e32 v4, v0
	v_mov_b32_e32 v5, v3
	v_pk_mul_f32 v[12:13], v[110:111], v[12:13]
	v_mov_b32_e32 v114, v65
	v_pk_fma_f32 v[4:5], v[68:69], v[4:5], v[12:13] neg_lo:[0,0,1] neg_hi:[0,0,1]
	v_mov_b32_e32 v12, v49
	v_mov_b32_e32 v49, v51
	v_mov_b32_e32 v13, v50
	v_pk_mul_f32 v[2:3], v[48:49], v[2:3]
	v_mov_b32_e32 v115, v67
	v_pk_fma_f32 v[12:13], v[12:13], v[0:1], v[2:3]
	v_mov_b32_e32 v0, v6
	v_mov_b32_e32 v1, v15
	v_pk_mul_f32 v[0:1], v[60:61], v[0:1] op_sel_hi:[0,1]
	v_mov_b32_e32 v2, v38
	v_mov_b32_e32 v3, v47
	v_mov_b32_e32 v15, v7
	v_pk_mul_f32 v[0:1], v[2:3], v[0:1]
	v_pk_mul_f32 v[2:3], v[60:61], v[14:15] op_sel_hi:[0,1]
	v_mov_b32_e32 v47, v39
	v_pk_mul_f32 v[2:3], v[46:47], v[2:3]
	v_mov_b32_e32 v15, v1
	v_mov_b32_e32 v14, v2
	v_mov_b32_e32 v112, v64
	v_mov_b32_e32 v113, v66
	v_mov_b32_e32 v6, v0
	v_mov_b32_e32 v7, v3
	v_pk_mul_f32 v[14:15], v[114:115], v[14:15]
	s_nop 0
	v_pk_fma_f32 v[6:7], v[112:113], v[6:7], v[14:15] neg_lo:[0,0,1] neg_hi:[0,0,1]
	v_mov_b32_e32 v14, v64
	v_mov_b32_e32 v15, v67
	v_pk_mul_f32 v[2:3], v[14:15], v[2:3]
	v_mov_b32_e32 v14, v65
	v_mov_b32_e32 v15, v66
	v_pk_fma_f32 v[14:15], v[14:15], v[0:1], v[2:3]
	v_cvt_pk_bf16_f32 v2, v4, v5
	v_add_co_u32_e32 v4, vcc, s23, v52
	v_cvt_pk_bf16_f32 v0, v8, v9
	v_cvt_pk_bf16_f32 v1, v10, v11
	v_cvt_pk_bf16_f32 v3, v6, v7
	v_addc_co_u32_e32 v5, vcc, 0, v53, vcc
	global_store_dwordx4 v[4:5], v[0:3], off sc1
	s_nop 1
	v_cvt_pk_bf16_f32 v0, v16, v17
	v_cvt_pk_bf16_f32 v1, v18, v19
	v_cvt_pk_bf16_f32 v2, v12, v13
	v_cvt_pk_bf16_f32 v3, v14, v15
	global_store_dwordx4 v[4:5], v[0:3], off offset:1024 sc1
	s_nop 1
	v_and_b32_e32 v1, 0xffff0000, v104
	v_lshlrev_b32_e32 v0, 16, v104
	v_mul_f32_e32 v2, v1, v1
	v_fmac_f32_e32 v2, v0, v0
	v_lshlrev_b32_e32 v0, 16, v105
	v_fmac_f32_e32 v2, v0, v0
	v_and_b32_e32 v0, 0xffff0000, v105
	v_fmac_f32_e32 v2, v0, v0
	v_lshlrev_b32_e32 v0, 16, v106
	v_fmac_f32_e32 v2, v0, v0
	v_and_b32_e32 v0, 0xffff0000, v106
	v_fmac_f32_e32 v2, v0, v0
	v_lshlrev_b32_e32 v0, 16, v107
	v_fmac_f32_e32 v2, v0, v0
	v_and_b32_e32 v0, 0xffff0000, v107
	v_fmac_f32_e32 v2, v0, v0
	v_lshlrev_b32_e32 v0, 16, v100
	v_fmac_f32_e32 v2, v0, v0
	v_and_b32_e32 v0, 0xffff0000, v100
	v_fmac_f32_e32 v2, v0, v0
	v_lshlrev_b32_e32 v0, 16, v101
	v_fmac_f32_e32 v2, v0, v0
	v_and_b32_e32 v0, 0xffff0000, v101
	v_fmac_f32_e32 v2, v0, v0
	v_lshlrev_b32_e32 v0, 16, v102
	v_fmac_f32_e32 v2, v0, v0
	v_and_b32_e32 v0, 0xffff0000, v102
	v_fmac_f32_e32 v2, v0, v0
	v_lshlrev_b32_e32 v0, 16, v103
	v_fmac_f32_e32 v2, v0, v0
	v_and_b32_e32 v0, 0xffff0000, v103
	v_fmac_f32_e32 v2, v0, v0
	v_lshlrev_b32_e32 v0, 16, v96
	v_fmac_f32_e32 v2, v0, v0
	v_and_b32_e32 v0, 0xffff0000, v96
	v_fmac_f32_e32 v2, v0, v0
	v_lshlrev_b32_e32 v0, 16, v97
	v_fmac_f32_e32 v2, v0, v0
	v_and_b32_e32 v0, 0xffff0000, v97
	v_fmac_f32_e32 v2, v0, v0
	v_lshlrev_b32_e32 v0, 16, v98
	v_fmac_f32_e32 v2, v0, v0
	v_and_b32_e32 v0, 0xffff0000, v98
	v_fmac_f32_e32 v2, v0, v0
	v_lshlrev_b32_e32 v0, 16, v99
	v_fmac_f32_e32 v2, v0, v0
	v_and_b32_e32 v0, 0xffff0000, v99
	v_fmac_f32_e32 v2, v0, v0
	v_lshlrev_b32_e32 v0, 16, v92
	v_fmac_f32_e32 v2, v0, v0
	v_and_b32_e32 v0, 0xffff0000, v92
	v_fmac_f32_e32 v2, v0, v0
	v_lshlrev_b32_e32 v0, 16, v93
	v_fmac_f32_e32 v2, v0, v0
	v_and_b32_e32 v0, 0xffff0000, v93
	v_fmac_f32_e32 v2, v0, v0
	v_lshlrev_b32_e32 v0, 16, v94
	v_fmac_f32_e32 v2, v0, v0
	v_and_b32_e32 v0, 0xffff0000, v94
	v_fmac_f32_e32 v2, v0, v0
	v_lshlrev_b32_e32 v0, 16, v95
	v_fmac_f32_e32 v2, v0, v0
	v_and_b32_e32 v0, 0xffff0000, v95
	v_fmac_f32_e32 v2, v0, v0
	v_lshlrev_b32_e32 v0, 16, v88
	v_fmac_f32_e32 v2, v0, v0
	v_and_b32_e32 v0, 0xffff0000, v88
	v_fmac_f32_e32 v2, v0, v0
	v_lshlrev_b32_e32 v0, 16, v89
	v_fmac_f32_e32 v2, v0, v0
	v_and_b32_e32 v0, 0xffff0000, v89
	v_fmac_f32_e32 v2, v0, v0
	v_lshlrev_b32_e32 v0, 16, v90
	v_fmac_f32_e32 v2, v0, v0
	v_and_b32_e32 v0, 0xffff0000, v90
	v_fmac_f32_e32 v2, v0, v0
	v_lshlrev_b32_e32 v0, 16, v91
	v_fmac_f32_e32 v2, v0, v0
	v_and_b32_e32 v0, 0xffff0000, v91
	v_fmac_f32_e32 v2, v0, v0
	v_lshlrev_b32_e32 v0, 16, v84
	v_fmac_f32_e32 v2, v0, v0
	v_and_b32_e32 v0, 0xffff0000, v84
	v_fmac_f32_e32 v2, v0, v0
	v_lshlrev_b32_e32 v0, 16, v85
	v_fmac_f32_e32 v2, v0, v0
	v_and_b32_e32 v0, 0xffff0000, v85
	v_fmac_f32_e32 v2, v0, v0
	v_lshlrev_b32_e32 v0, 16, v86
	v_fmac_f32_e32 v2, v0, v0
	v_and_b32_e32 v0, 0xffff0000, v86
	v_fmac_f32_e32 v2, v0, v0
	v_lshlrev_b32_e32 v0, 16, v87
	v_fmac_f32_e32 v2, v0, v0
	v_and_b32_e32 v0, 0xffff0000, v87
	v_fmac_f32_e32 v2, v0, v0
	v_lshlrev_b32_e32 v0, 16, v80
	v_fmac_f32_e32 v2, v0, v0
	v_and_b32_e32 v0, 0xffff0000, v80
	v_fmac_f32_e32 v2, v0, v0
	v_lshlrev_b32_e32 v0, 16, v81
	v_fmac_f32_e32 v2, v0, v0
	v_and_b32_e32 v0, 0xffff0000, v81
	v_fmac_f32_e32 v2, v0, v0
	v_lshlrev_b32_e32 v0, 16, v82
	v_fmac_f32_e32 v2, v0, v0
	v_and_b32_e32 v0, 0xffff0000, v82
	v_fmac_f32_e32 v2, v0, v0
	v_lshlrev_b32_e32 v0, 16, v83
	v_fmac_f32_e32 v2, v0, v0
	v_and_b32_e32 v0, 0xffff0000, v83
	v_fmac_f32_e32 v2, v0, v0
	v_lshlrev_b32_e32 v0, 16, v76
	v_fmac_f32_e32 v2, v0, v0
	v_and_b32_e32 v0, 0xffff0000, v76
	v_fmac_f32_e32 v2, v0, v0
	v_lshlrev_b32_e32 v0, 16, v77
	v_fmac_f32_e32 v2, v0, v0
	v_and_b32_e32 v0, 0xffff0000, v77
	v_fmac_f32_e32 v2, v0, v0
	v_lshlrev_b32_e32 v0, 16, v78
	v_fmac_f32_e32 v2, v0, v0
	v_and_b32_e32 v0, 0xffff0000, v78
	v_fmac_f32_e32 v2, v0, v0
	v_and_b32_e32 v1, 0xffff0000, v79
	v_lshlrev_b32_e32 v0, 16, v79
	v_pk_mul_f32 v[0:1], v[0:1], v[0:1]
	s_nop 0
	v_add_f32_e32 v0, v0, v2
	v_add_f32_e32 v0, v1, v0
	v_mov_b32_e32 v1, v0
	s_nop 1
	v_permlane32_swap_b32_e32 v0, v1
	v_add_f32_e32 v0, v0, v1
	v_fmamk_f32 v117, v0, 0x3c000000, v204
	ds_read_b128 v[0:3], v169 offset:49152
	ds_read_b128 v[4:7], v169 offset:50176
	ds_read_b128 v[8:11], v169 offset:51200
	ds_read_b128 v[12:15], v169 offset:52224
	s_waitcnt lgkmcnt(3)
	v_mfma_f32_32x32x16_bf16 v[16:31], v[0:3], v[104:107], 0
	ds_read_b128 v[0:3], v169 offset:53248
	s_waitcnt lgkmcnt(3)
	v_mfma_f32_32x32x16_bf16 v[16:31], v[4:7], v[100:103], v[16:31]
	ds_read_b128 v[4:7], v169 offset:54272
	s_waitcnt lgkmcnt(3)
	v_mfma_f32_32x32x16_bf16 v[16:31], v[8:11], v[96:99], v[16:31]
	ds_read_b128 v[8:11], v169 offset:55296
	s_waitcnt lgkmcnt(3)
	v_mfma_f32_32x32x16_bf16 v[16:31], v[12:15], v[92:95], v[16:31]
	ds_read_b128 v[12:15], v169 offset:56320
	s_waitcnt lgkmcnt(3)
	v_mfma_f32_32x32x16_bf16 v[16:31], v[0:3], v[88:91], v[16:31]
	ds_read_b128 v[0:3], v169 offset:57344
	s_waitcnt lgkmcnt(3)
	v_mfma_f32_32x32x16_bf16 v[16:31], v[4:7], v[84:87], v[16:31]
	ds_read_b128 v[4:7], v169 offset:58368
	s_waitcnt lgkmcnt(3)
	v_mfma_f32_32x32x16_bf16 v[16:31], v[8:11], v[80:83], v[16:31]
	ds_read_b128 v[8:11], v169 offset:59392
	s_waitcnt lgkmcnt(3)
	v_mfma_f32_32x32x16_bf16 v[16:31], v[12:15], v[76:79], v[16:31]
	ds_read_b128 v[12:15], v169 offset:60416
	s_waitcnt lgkmcnt(3)
	v_mfma_f32_32x32x16_bf16 v[48:63], v[0:3], v[104:107], 0
	ds_read_b128 v[0:3], v169 offset:61440
	s_waitcnt lgkmcnt(3)
	v_mfma_f32_32x32x16_bf16 v[48:63], v[4:7], v[100:103], v[48:63]
	ds_read_b128 v[4:7], v169 offset:62464
	s_waitcnt lgkmcnt(3)
	v_mfma_f32_32x32x16_bf16 v[48:63], v[8:11], v[96:99], v[48:63]
	ds_read_b128 v[8:11], v169 offset:63488
	s_waitcnt lgkmcnt(3)
	v_mfma_f32_32x32x16_bf16 v[48:63], v[12:15], v[92:95], v[48:63]
	ds_read_b128 v[12:15], v169 offset:64512
	s_waitcnt lgkmcnt(3)
	v_mfma_f32_32x32x16_bf16 v[48:63], v[0:3], v[88:91], v[48:63]
	ds_read_b128 v[0:3], v186 offset:16384
	ds_read_b128 v[32:35], v186 offset:17408
	s_waitcnt lgkmcnt(4)
	v_mfma_f32_32x32x16_bf16 v[48:63], v[4:7], v[84:87], v[48:63]
	ds_read_b128 v[36:39], v186 offset:18432
	s_waitcnt lgkmcnt(4)
	v_mfma_f32_32x32x16_bf16 v[48:63], v[8:11], v[80:83], v[48:63]
	ds_read_b128 v[40:43], v186 offset:19456
	s_waitcnt lgkmcnt(4)
	v_mfma_f32_32x32x16_bf16 v[48:63], v[12:15], v[76:79], v[48:63]
	ds_read_b128 v[44:47], v186 offset:20480
	s_waitcnt lgkmcnt(4)
	v_mfma_f32_32x32x16_bf16 v[0:15], v[104:107], v[0:3], 0
	s_waitcnt lgkmcnt(3)
	v_mfma_f32_32x32x16_bf16 v[0:15], v[100:103], v[32:35], v[0:15]
	ds_read_b128 v[32:35], v186 offset:21504
	s_waitcnt lgkmcnt(3)
	v_mfma_f32_32x32x16_bf16 v[0:15], v[96:99], v[36:39], v[0:15]
	ds_read_b128 v[36:39], v186 offset:22528
	s_waitcnt lgkmcnt(3)
	v_mfma_f32_32x32x16_bf16 v[0:15], v[92:95], v[40:43], v[0:15]
	ds_read_b128 v[40:43], v186 offset:23552
	s_waitcnt lgkmcnt(3)
	v_mfma_f32_32x32x16_bf16 v[0:15], v[88:91], v[44:47], v[0:15]
	ds_read_b128 v[44:47], v186 offset:24576
	ds_read_b128 v[118:121], v186 offset:25600
	s_waitcnt lgkmcnt(4)
	v_mfma_f32_32x32x16_bf16 v[0:15], v[84:87], v[32:35], v[0:15]
	ds_read_b128 v[122:125], v186 offset:26624
	s_waitcnt lgkmcnt(4)
	v_mfma_f32_32x32x16_bf16 v[0:15], v[80:83], v[36:39], v[0:15]
	ds_read_b128 v[126:129], v186 offset:27648
	s_waitcnt lgkmcnt(4)
	v_mfma_f32_32x32x16_bf16 v[0:15], v[76:79], v[40:43], v[0:15]
	s_waitcnt lgkmcnt(3)
	v_mfma_f32_32x32x16_bf16 v[32:47], v[104:107], v[44:47], 0
	ds_read_b128 v[104:107], v186 offset:28672
	s_waitcnt lgkmcnt(3)
	v_mfma_f32_32x32x16_bf16 v[32:47], v[100:103], v[118:121], v[32:47]
	ds_read_b128 v[100:103], v186 offset:29696
	s_waitcnt lgkmcnt(3)
	v_mfma_f32_32x32x16_bf16 v[32:47], v[96:99], v[122:125], v[32:47]
	ds_read_b128 v[96:99], v186 offset:30720
	s_waitcnt lgkmcnt(3)
	v_mfma_f32_32x32x16_bf16 v[32:47], v[92:95], v[126:129], v[32:47]
	ds_read_b128 v[92:95], v186 offset:31744
	s_waitcnt lgkmcnt(3)
	v_mfma_f32_32x32x16_bf16 v[32:47], v[88:91], v[104:107], v[32:47]
	s_waitcnt lgkmcnt(2)
	v_mfma_f32_32x32x16_bf16 v[32:47], v[84:87], v[100:103], v[32:47]
	s_waitcnt lgkmcnt(1)
	v_mfma_f32_32x32x16_bf16 v[32:47], v[80:83], v[96:99], v[32:47]
	s_waitcnt lgkmcnt(0)
	v_mfma_f32_32x32x16_bf16 v[32:47], v[76:79], v[92:95], v[32:47]
	v_mul_f32_e32 v76, v17, v17
	v_mul_f32_e32 v78, v49, v49
	v_fmac_f32_e32 v76, v16, v16
	v_fmac_f32_e32 v78, v48, v48
	v_fmac_f32_e32 v76, v18, v18
	v_fmac_f32_e32 v78, v50, v50
	v_fmac_f32_e32 v76, v19, v19
	v_fmac_f32_e32 v78, v51, v51
	v_fmac_f32_e32 v76, v20, v20
	v_fmac_f32_e32 v78, v52, v52
	v_fmac_f32_e32 v76, v21, v21
	v_fmac_f32_e32 v78, v53, v53
	v_fmac_f32_e32 v76, v22, v22
	v_fmac_f32_e32 v78, v54, v54
	v_fmac_f32_e32 v76, v23, v23
	v_fmac_f32_e32 v78, v55, v55
	v_fmac_f32_e32 v76, v24, v24
	v_fmac_f32_e32 v78, v56, v56
	v_fmac_f32_e32 v76, v25, v25
	v_fmac_f32_e32 v78, v57, v57
	v_fmac_f32_e32 v76, v26, v26
	v_fmac_f32_e32 v78, v58, v58
	v_fmac_f32_e32 v76, v27, v27
	v_fmac_f32_e32 v78, v59, v59
	v_fmac_f32_e32 v76, v28, v28
	v_fmac_f32_e32 v78, v60, v60
	v_fmac_f32_e32 v76, v29, v29
	v_fmac_f32_e32 v78, v61, v61
	v_fmac_f32_e32 v76, v30, v30
	v_fmac_f32_e32 v78, v62, v62
	v_fmac_f32_e32 v76, v31, v31
	v_fmac_f32_e32 v78, v63, v63
	v_rsq_f32_e32 v225, v117
	v_add_f32_e32 v76, v76, v78
	v_mov_b32_e32 v78, v76
	s_mov_b64 s[44:45], s[4:5]
	s_nop 0
	v_permlane32_swap_b32_e32 v76, v78
	s_add_u32 s42, s44, s42
	v_add_f32_e32 v76, v76, v78
	s_addc_u32 s43, s45, s41
	s_mul_i32 s40, s35, 12
	v_mul_f32_e32 v226, v225, v76
	v_or_b32_e32 v76, s40, v165
	v_lshl_add_u64 v[78:79], s[42:43], 0, v[162:163]
	s_mov_b64 s[42:43], 0x1800000
	v_lshl_add_u64 v[78:79], v[78:79], 0, s[42:43]
	v_lshlrev_b32_e32 v172, 10, v76
	v_add_u32_e32 v92, 0x14180, v116
	v_lshl_add_u64 v[136:137], v[78:79], 0, v[172:173]
	v_add_u32_e32 v172, 0x14200, v116
	v_add_u32_e32 v76, 0x14280, v116
	v_and_b32_e32 v138, 0xffff0000, v183
	v_lshlrev_b32_e32 v150, 16, v180
	v_and_b32_e32 v151, 0xffff0000, v180
	v_lshlrev_b32_e32 v77, 16, v183
	ds_read_b128 v[80:83], v92
	ds_read_b128 v[84:87], v92 offset:32
	ds_read_b128 v[88:91], v92 offset:64
	ds_read_b128 v[92:95], v92 offset:96
	ds_read_b128 v[96:99], v172
	ds_read_b128 v[100:103], v172 offset:32
	ds_read_b128 v[104:107], v76
	ds_read_b128 v[116:119], v76 offset:32
	ds_read_b128 v[120:123], v76 offset:64
	ds_read_b128 v[124:127], v76 offset:96
	v_mov_b32_e32 v76, v138
	v_lshlrev_b32_e32 v144, 16, v181
	v_and_b32_e32 v145, 0xffff0000, v181
	v_pk_mul_f32 v[154:155], v[150:151], v[150:151]
	v_pk_mul_f32 v[128:129], v[76:77], v[76:77]
	v_pk_mul_f32 v[134:135], v[144:145], v[144:145]
	v_add_f32_e32 v76, v154, v155
	v_lshlrev_b32_e32 v140, 16, v184
	v_and_b32_e32 v141, 0xffff0000, v184
	v_add_f32_e32 v76, v134, v76
	v_pk_mul_f32 v[130:131], v[140:141], v[140:141]
	v_add_f32_e32 v76, v135, v76
	v_add_f32_e32 v76, v130, v76
	v_lshlrev_b32_e32 v224, 16, v185
	v_add_f32_e32 v76, v131, v76
	v_and_b32_e32 v139, 0xffff0000, v185
	v_lshlrev_b32_e32 v152, 16, v178
	v_and_b32_e32 v153, 0xffff0000, v178
	v_fmac_f32_e32 v76, v224, v224
	v_lshlrev_b32_e32 v146, 16, v179
	v_and_b32_e32 v147, 0xffff0000, v179
	v_pk_mul_f32 v[178:179], v[152:153], v[152:153]
	v_fmac_f32_e32 v76, v139, v139
	v_add_f32_e32 v76, v178, v76
	v_pk_mul_f32 v[148:149], v[146:147], v[146:147]
	v_add_f32_e32 v76, v179, v76
	v_lshlrev_b32_e32 v142, 16, v182
	v_and_b32_e32 v143, 0xffff0000, v182
	v_add_f32_e32 v76, v148, v76
	v_pk_mul_f32 v[132:133], v[142:143], v[142:143]
	v_add_f32_e32 v76, v149, v76
	v_add_f32_e32 v76, v132, v76
	v_add_f32_e32 v76, v133, v76
	v_add_f32_e32 v76, v129, v76
	v_add_f32_e32 v76, v128, v76
	v_mov_b32_e32 v128, v76
	s_nop 1
	v_permlane32_swap_b32_e32 v76, v128
	v_add_f32_e32 v76, v76, v128
	v_fmac_f32_e32 v76, v225, v226
	v_fmamk_f32 v76, v76, 0x3c2aaaab, v204
	v_rsq_f32_e32 v76, v76
	ds_read_b128 v[128:131], v172 offset:64
	ds_read_b128 v[132:135], v172 offset:96
	s_waitcnt lgkmcnt(2)
	v_mov_b32_e32 v148, v127
	v_mov_b32_e32 v149, v119
	v_mul_f32_e32 v154, v225, v76
	v_pk_mul_f32 v[80:81], v[80:81], v[154:155] op_sel_hi:[1,0]
	v_add_lshl_u32 v172, s40, v187, 10
	v_pk_mul_f32 v[16:17], v[16:17], v[80:81]
	v_pk_mul_f32 v[80:81], v[82:83], v[154:155] op_sel_hi:[1,0]
	v_cvt_pk_bf16_f32 v16, v16, v17
	v_pk_mul_f32 v[18:19], v[18:19], v[80:81]
	v_pk_mul_f32 v[80:81], v[84:85], v[154:155] op_sel_hi:[1,0]
	v_cvt_pk_bf16_f32 v17, v18, v19
	v_pk_mul_f32 v[20:21], v[20:21], v[80:81]
	v_pk_mul_f32 v[80:81], v[86:87], v[154:155] op_sel_hi:[1,0]
	v_cvt_pk_bf16_f32 v18, v20, v21
	v_pk_mul_f32 v[22:23], v[22:23], v[80:81]
	v_pk_mul_f32 v[80:81], v[88:89], v[154:155] op_sel_hi:[1,0]
	v_cvt_pk_bf16_f32 v19, v22, v23
	v_pk_mul_f32 v[24:25], v[24:25], v[80:81]
	v_pk_mul_f32 v[80:81], v[90:91], v[154:155] op_sel_hi:[1,0]
	global_store_dwordx4 v[136:137], v[16:19], off sc1
	v_pk_mul_f32 v[26:27], v[26:27], v[80:81]
	v_pk_mul_f32 v[80:81], v[92:93], v[154:155] op_sel_hi:[1,0]
	v_cvt_pk_bf16_f32 v16, v24, v25
	v_pk_mul_f32 v[28:29], v[28:29], v[80:81]
	v_pk_mul_f32 v[80:81], v[94:95], v[154:155] op_sel_hi:[1,0]
	v_cvt_pk_bf16_f32 v17, v26, v27
	v_pk_mul_f32 v[30:31], v[30:31], v[80:81]
	v_cvt_pk_bf16_f32 v18, v28, v29
	v_cvt_pk_bf16_f32 v19, v30, v31
	global_store_dwordx4 v[136:137], v[16:19], off offset:2048 sc1
	v_pk_mul_f32 v[20:21], v[154:155], v[100:101] op_sel_hi:[0,1]
	v_pk_mul_f32 v[20:21], v[52:53], v[20:21]
	v_pk_mul_f32 v[16:17], v[154:155], v[96:97] op_sel_hi:[0,1]
	v_pk_mul_f32 v[18:19], v[154:155], v[98:99] op_sel_hi:[0,1]
	v_pk_mul_f32 v[16:17], v[48:49], v[16:17]
	v_pk_mul_f32 v[18:19], v[50:51], v[18:19]
	v_pk_mul_f32 v[22:23], v[154:155], v[102:103] op_sel_hi:[0,1]
	v_pk_mul_f32 v[22:23], v[54:55], v[22:23]
	s_waitcnt lgkmcnt(1)
	v_pk_mul_f32 v[24:25], v[154:155], v[128:129] op_sel_hi:[0,1]
	v_pk_mul_f32 v[26:27], v[154:155], v[130:131] op_sel_hi:[0,1]
	s_waitcnt lgkmcnt(0)
	v_pk_mul_f32 v[28:29], v[154:155], v[132:133] op_sel_hi:[0,1]
	v_pk_mul_f32 v[30:31], v[154:155], v[134:135] op_sel_hi:[0,1]
	v_cvt_pk_bf16_f32 v16, v16, v17
	v_cvt_pk_bf16_f32 v17, v18, v19
	v_cvt_pk_bf16_f32 v18, v20, v21
	v_add_co_u32_e32 v20, vcc, s23, v136
	v_pk_mul_f32 v[24:25], v[56:57], v[24:25]
	v_pk_mul_f32 v[26:27], v[58:59], v[26:27]
	v_pk_mul_f32 v[28:29], v[60:61], v[28:29]
	v_pk_mul_f32 v[30:31], v[62:63], v[30:31]
	v_cvt_pk_bf16_f32 v19, v22, v23
	v_addc_co_u32_e32 v21, vcc, 0, v137, vcc
	global_store_dwordx4 v[20:21], v[16:19], off sc1
	v_pk_mul_f32 v[48:49], v[76:77], v[148:149] op_sel_hi:[0,1]
	v_mul_f32_e32 v23, v76, v126
	v_cvt_pk_bf16_f32 v16, v24, v25
	v_cvt_pk_bf16_f32 v17, v26, v27
	v_cvt_pk_bf16_f32 v18, v28, v29
	v_cvt_pk_bf16_f32 v19, v30, v31
	v_pk_mul_f32 v[24:25], v[76:77], v[120:121] op_sel_hi:[0,1]
	global_store_dwordx4 v[20:21], v[16:19], off offset:2048 sc1
	v_pk_mul_f32 v[24:25], v[24:25], v[152:153]
	v_pk_mul_f32 v[26:27], v[76:77], v[122:123] op_sel_hi:[0,1]
	v_pk_mul_f32 v[16:17], v[76:77], v[104:105] op_sel_hi:[0,1]
	v_pk_mul_f32 v[16:17], v[16:17], v[150:151]
	v_pk_mul_f32 v[18:19], v[76:77], v[106:107] op_sel_hi:[0,1]
	v_pk_mul_f32 v[26:27], v[26:27], v[146:147]
	v_pk_mul_f32 v[50:51], v[74:75], v[24:25]
	v_pk_mul_f32 v[24:25], v[108:109], v[24:25]
	v_pk_mul_f32 v[18:19], v[18:19], v[144:145]
	v_pk_mul_f32 v[28:29], v[76:77], v[124:125] op_sel_hi:[0,1]
	v_pk_fma_f32 v[50:51], v[108:109], v[16:17], v[50:51] neg_lo:[0,0,1] neg_hi:[0,0,1]
	v_pk_fma_f32 v[24:25], v[74:75], v[16:17], v[24:25]
	v_pk_mul_f32 v[16:17], v[70:71], v[26:27]
	v_pk_mul_f32 v[20:21], v[76:77], v[116:117] op_sel_hi:[0,1]
	v_pk_mul_f32 v[28:29], v[28:29], v[142:143]
	v_pk_fma_f32 v[52:53], v[72:73], v[18:19], v[16:17] neg_lo:[0,0,1] neg_hi:[0,0,1]
	v_pk_mul_f32 v[16:17], v[72:73], v[26:27]
	v_pk_mul_f32 v[20:21], v[20:21], v[140:141]
	v_pk_mul_f32 v[48:49], v[48:49], v[138:139]
	v_pk_fma_f32 v[26:27], v[70:71], v[18:19], v[16:17]
	v_pk_mul_f32 v[16:17], v[110:111], v[28:29]
	v_mul_f32_e32 v22, v76, v118
	v_mul_f32_e32 v30, v23, v77
	v_pk_fma_f32 v[18:19], v[68:69], v[20:21], v[16:17] neg_lo:[0,0,1] neg_hi:[0,0,1]
	v_pk_mul_f32 v[16:17], v[68:69], v[28:29]
	v_mov_b32_e32 v31, v48
	v_mul_f32_e32 v22, v22, v224
	v_pk_fma_f32 v[20:21], v[110:111], v[20:21], v[16:17]
	v_mul_f32_e32 v16, v64, v30
	v_mov_b32_e32 v23, v49
	v_pk_mul_f32 v[30:31], v[114:115], v[30:31]
	v_mul_f32_e32 v28, v65, v22
	v_pk_fma_f32 v[22:23], v[112:113], v[22:23], v[30:31] neg_lo:[0,0,1] neg_hi:[0,0,1]
	v_pk_mul_f32 v[30:31], v[66:67], v[48:49]
	v_cvt_pk_bf16_f32 v18, v18, v19
	v_mov_b32_e32 v29, v31
	v_mov_b32_e32 v17, v30
	v_pk_add_f32 v[28:29], v[28:29], v[16:17]
	v_cvt_pk_bf16_f32 v16, v50, v51
	v_cvt_pk_bf16_f32 v17, v52, v53
	v_cvt_pk_bf16_f32 v19, v22, v23
	v_lshl_add_u64 v[22:23], v[78:79], 0, v[172:173]
	global_store_dwordx4 v[22:23], v[16:19], off sc1
	ds_bpermute_b32 v30, v219, v225
	ds_bpermute_b32 v31, v220, v225
	v_cvt_pk_bf16_f32 v16, v24, v25
	v_cvt_pk_bf16_f32 v17, v26, v27
	v_cvt_pk_bf16_f32 v18, v20, v21
	v_cvt_pk_bf16_f32 v19, v28, v29
	global_store_dwordx4 v[22:23], v[16:19], off offset:2048 sc1
	ds_bpermute_b32 v16, v188, v225
	ds_bpermute_b32 v17, v189, v225
	ds_bpermute_b32 v18, v190, v225
	ds_bpermute_b32 v19, v191, v225
	ds_bpermute_b32 v20, v192, v225
	ds_bpermute_b32 v21, v193, v225
	ds_bpermute_b32 v24, v213, v225
	ds_bpermute_b32 v25, v214, v225
	ds_bpermute_b32 v26, v215, v225
	ds_bpermute_b32 v27, v216, v225
	ds_bpermute_b32 v28, v217, v225
	ds_bpermute_b32 v29, v218, v225
	ds_bpermute_b32 v48, v221, v225
	ds_bpermute_b32 v49, v222, v225
	s_lshl_b64 s[10:11], s[10:11], 20
	s_add_u32 s10, s19, s10
	s_addc_u32 s11, s26, s11
	v_lshl_or_b32 v172, s35, 13, v223
	v_lshl_add_u64 v[22:23], s[10:11], 0, v[172:173]
	s_waitcnt lgkmcnt(12)
	v_pk_mul_f32 v[0:1], v[0:1], v[16:17]
	s_waitcnt lgkmcnt(10)
	v_pk_mul_f32 v[2:3], v[2:3], v[18:19]
	s_waitcnt lgkmcnt(8)
	v_pk_mul_f32 v[4:5], v[4:5], v[20:21]
	s_waitcnt lgkmcnt(6)
	v_pk_mul_f32 v[6:7], v[6:7], v[24:25]
	s_waitcnt lgkmcnt(4)
	v_pk_mul_f32 v[8:9], v[8:9], v[26:27]
	s_waitcnt lgkmcnt(2)
	v_pk_mul_f32 v[10:11], v[10:11], v[28:29]
	v_pk_mul_f32 v[12:13], v[12:13], v[30:31]
	s_waitcnt lgkmcnt(0)
	v_pk_mul_f32 v[14:15], v[14:15], v[48:49]
	v_cvt_pk_bf16_f32 v0, v0, v1
	v_cvt_pk_bf16_f32 v1, v2, v3
	v_cvt_pk_bf16_f32 v2, v4, v5
	v_cvt_pk_bf16_f32 v3, v6, v7
	v_lshl_add_u64 v[4:5], v[22:23], 0, v[158:159]
	global_store_dwordx4 v[4:5], v[0:3], off sc1
	v_pk_mul_f32 v[6:7], v[36:37], v[20:21]
	s_nop 0
	v_cvt_pk_bf16_f32 v0, v8, v9
	v_cvt_pk_bf16_f32 v1, v10, v11
	v_cvt_pk_bf16_f32 v2, v12, v13
	v_cvt_pk_bf16_f32 v3, v14, v15
	global_store_dwordx4 v[4:5], v[0:3], off offset:2048 sc1
	v_pk_mul_f32 v[8:9], v[38:39], v[24:25]
	v_pk_mul_f32 v[10:11], v[40:41], v[26:27]
	v_pk_mul_f32 v[0:1], v[32:33], v[16:17]
	v_pk_mul_f32 v[2:3], v[34:35], v[18:19]
	v_pk_mul_f32 v[12:13], v[42:43], v[28:29]
	v_pk_mul_f32 v[14:15], v[44:45], v[30:31]
	v_pk_mul_f32 v[16:17], v[46:47], v[48:49]
	v_cvt_pk_bf16_f32 v0, v0, v1
	v_cvt_pk_bf16_f32 v1, v2, v3
	v_cvt_pk_bf16_f32 v2, v6, v7
	v_cvt_pk_bf16_f32 v3, v8, v9
	global_store_dwordx4 v[4:5], v[0:3], off offset:512 sc1
	s_nop 1
	v_cvt_pk_bf16_f32 v0, v10, v11
	v_cvt_pk_bf16_f32 v1, v12, v13
	v_cvt_pk_bf16_f32 v2, v14, v15
	v_cvt_pk_bf16_f32 v3, v16, v17
	global_store_dwordx4 v[4:5], v[0:3], off offset:2560 sc1
	s_add_i32 s35, s34, 8
	s_add_i32 s33, s33, -8
	s_mov_b64 s[10:11], 0x8000
	v_lshl_add_u64 v[170:171], v[170:171], 0, s[24:25]
	v_lshl_add_u64 v[174:175], v[174:175], 0, s[24:25]
	v_lshl_add_u64 v[176:177], v[176:177], 0, s[10:11]
	s_cmp_gt_i32 s34, 7
	s_mov_b32 s34, s35
	s_cbranch_scc1 .LBB0_345

.LBB0_500:
	s_mul_hi_u32 s9, s51, 0xaaaaaaab
	s_lshr_b32 s9, s9, 2
	s_mul_i32 s9, s9, 0xfffe2000
	s_add_i32 s9, s9, 0
	v_add_u32_e32 v141, s50, v139
	v_add_u32_e32 v140, s9, v141
	ds_read_b128 v[34:37], v140 offset:12288
	ds_read_b128 v[38:41], v140 offset:12800
	ds_read_b128 v[42:45], v140 offset:20480
	ds_read_b128 v[46:49], v140 offset:20992
	ds_read_b128 v[142:145], v140 offset:22528
	s_mul_hi_u32 s9, s48, 0xaaaaaaab
	s_lshr_b32 s9, s9, 2
	s_mul_i32 s9, s9, 0xfffe2000
	s_add_i32 s52, s9, 0
	v_exp_f32_e32 v18, v18
	v_exp_f32_e32 v19, v19
	v_exp_f32_e32 v20, v20
	v_exp_f32_e32 v21, v21
	v_exp_f32_e32 v22, v22
	v_exp_f32_e32 v23, v23
	v_exp_f32_e32 v24, v24
	v_exp_f32_e32 v25, v25
	v_add_f32_e32 v50, 0, v18
	v_add_f32_e32 v51, 0, v19
	v_add_f32_e32 v50, v20, v50
	v_add_f32_e32 v51, v21, v51
	v_add_f32_e32 v50, v22, v50
	v_add_f32_e32 v51, v23, v51
	v_cvt_pk_bf16_f32 v134, v18, v19
	v_cvt_pk_bf16_f32 v135, v20, v21
	v_cvt_pk_bf16_f32 v136, v22, v23
	v_add_f32_e32 v162, v25, v51
	v_add_f32_e32 v163, v24, v50
	v_cvt_pk_bf16_f32 v137, v24, v25
	s_waitcnt lgkmcnt(4)
	s_nop 0
	v_mfma_f32_32x32x16_bf16 v[66:81], v[34:37], v[134:137], v[66:81]
	ds_read_b128 v[146:149], v140 offset:14336
	s_mov_b32 s10, s8
	s_mov_b32 s11, s8
	s_mov_b32 s9, s8
	v_exp_f32_e32 v26, v26
	v_exp_f32_e32 v27, v27
	s_waitcnt lgkmcnt(4)
	v_mfma_f32_32x32x16_bf16 v[82:97], v[38:41], v[134:137], v[82:97]
	ds_read_b128 v[150:153], v140 offset:14848
	v_exp_f32_e32 v28, v28
	v_exp_f32_e32 v29, v29
	s_mov_b32 s14, s12
	s_mov_b32 s15, s12
	s_mov_b32 s13, s12
	v_exp_f32_e32 v30, v30
	v_exp_f32_e32 v31, v31
	ds_read_b128 v[154:157], v140 offset:23040
	v_exp_f32_e32 v32, v32
	v_exp_f32_e32 v33, v33
	s_waitcnt lgkmcnt(5)
	v_mfma_f32_32x32x16_bf16 v[50:65], v[42:45], v[118:121], 0
	ds_read_b128 v[158:161], v140 offset:24576
	v_add_f32_e32 v163, v163, v26
	v_add_f32_e32 v162, v162, v27
	v_cvt_pk_bf16_f32 v130, v26, v27
	v_cvt_pk_bf16_f32 v131, v28, v29
	v_add_f32_e32 v163, v28, v163
	v_add_f32_e32 v162, v29, v162
	s_waitcnt lgkmcnt(5)
	v_mfma_f32_32x32x16_bf16 v[34:49], v[46:49], v[118:121], 0
	s_waitcnt lgkmcnt(4)
	v_mfma_f32_32x32x16_bf16 v[50:65], v[142:145], v[114:117], v[50:65]
	ds_read_b128 v[142:145], v140 offset:25088
	v_add_f32_e32 v163, v163, v30
	v_add_f32_e32 v162, v162, v31
	v_cvt_pk_bf16_f32 v132, v30, v31
	v_cvt_pk_bf16_f32 v133, v32, v33
	v_add_f32_e32 v163, v32, v163
	v_add_f32_e32 v162, v33, v162
	s_waitcnt lgkmcnt(4)
	v_mfma_f32_32x32x16_bf16 v[66:81], v[146:149], v[130:133], v[66:81]
	ds_read_b128 v[18:21], v140 offset:16384
	v_exp_f32_e32 v2, v2
	v_exp_f32_e32 v3, v3
	s_waitcnt lgkmcnt(4)
	v_mfma_f32_32x32x16_bf16 v[82:97], v[150:153], v[130:133], v[82:97]
	ds_read_b128 v[22:25], v140 offset:16896
	v_exp_f32_e32 v4, v4
	v_exp_f32_e32 v5, v5
	s_nop 0
	v_exp_f32_e32 v6, v6
	v_exp_f32_e32 v7, v7
	ds_read_b128 v[26:29], v140 offset:26624
	v_exp_f32_e32 v8, v8
	v_exp_f32_e32 v9, v9
	s_waitcnt lgkmcnt(5)
	v_mfma_f32_32x32x16_bf16 v[34:49], v[154:157], v[114:117], v[34:49]
	ds_read_b128 v[30:33], v140 offset:27136
	v_add_f32_e32 v146, v163, v2
	v_add_f32_e32 v147, v162, v3
	v_cvt_pk_bf16_f32 v134, v2, v3
	v_cvt_pk_bf16_f32 v135, v4, v5
	v_add_f32_e32 v146, v4, v146
	v_add_f32_e32 v147, v5, v147
	s_waitcnt lgkmcnt(5)
	v_mfma_f32_32x32x16_bf16 v[50:65], v[158:161], v[110:113], v[50:65]
	s_waitcnt lgkmcnt(4)
	v_mfma_f32_32x32x16_bf16 v[34:49], v[142:145], v[110:113], v[34:49]
	ds_read_b128 v[142:145], v140 offset:28672
	v_add_f32_e32 v146, v146, v6
	v_add_f32_e32 v147, v147, v7
	v_cvt_pk_bf16_f32 v136, v6, v7
	v_cvt_pk_bf16_f32 v137, v8, v9
	v_add_f32_e32 v146, v8, v146
	v_add_f32_e32 v147, v9, v147
	s_waitcnt lgkmcnt(4)
	v_mfma_f32_32x32x16_bf16 v[66:81], v[18:21], v[134:137], v[66:81]
	ds_read_b128 v[18:21], v140 offset:18432
	v_exp_f32_e32 v10, v10
	v_exp_f32_e32 v11, v11
	s_waitcnt lgkmcnt(4)
	v_mfma_f32_32x32x16_bf16 v[82:97], v[22:25], v[134:137], v[82:97]
	ds_read_b128 v[22:25], v140 offset:18944
	v_exp_f32_e32 v12, v12
	v_exp_f32_e32 v13, v13
	s_nop 0
	v_exp_f32_e32 v14, v14
	v_exp_f32_e32 v15, v15
	s_waitcnt lgkmcnt(4)
	v_mfma_f32_32x32x16_bf16 v[50:65], v[26:29], v[106:109], v[50:65]
	ds_read_b128 v[26:29], v140 offset:29184
	v_exp_f32_e32 v16, v16
	v_exp_f32_e32 v17, v17
	s_waitcnt lgkmcnt(4)
	v_mfma_f32_32x32x16_bf16 v[34:49], v[30:33], v[106:109], v[34:49]
	ds_read_b128 v[30:33], v140 offset:30720
	v_add_f32_e32 v134, v146, v10
	v_add_f32_e32 v135, v147, v11
	v_cvt_pk_bf16_f32 v130, v10, v11
	v_cvt_pk_bf16_f32 v131, v12, v13
	v_add_f32_e32 v134, v12, v134
	v_add_f32_e32 v135, v13, v135
	s_waitcnt lgkmcnt(4)
	v_mfma_f32_32x32x16_bf16 v[50:65], v[142:145], v[102:105], v[50:65]
	ds_read_b128 v[142:145], v140 offset:31232
	v_add_f32_e32 v134, v134, v14
	v_add_f32_e32 v135, v135, v15
	v_cvt_pk_bf16_f32 v132, v14, v15
	v_cvt_pk_bf16_f32 v133, v16, v17
	v_add_f32_e32 v134, v16, v134
	v_add_f32_e32 v136, v17, v135
	s_waitcnt lgkmcnt(4)
	v_mfma_f32_32x32x16_bf16 v[66:81], v[18:21], v[130:133], v[66:81]
	s_waitcnt lgkmcnt(3)
	v_mfma_f32_32x32x16_bf16 v[82:97], v[22:25], v[130:133], v[82:97]
	s_waitcnt lgkmcnt(2)
	v_mfma_f32_32x32x16_bf16 v[34:49], v[26:29], v[102:105], v[34:49]
	s_waitcnt lgkmcnt(1)
	v_mfma_f32_32x32x16_bf16 v[50:65], v[30:33], v[98:101], v[50:65]
	s_waitcnt lgkmcnt(0)
	v_mfma_f32_32x32x16_bf16 v[34:49], v[142:145], v[98:101], v[34:49]
	v_add_u32_e32 v135, s52, v141
	ds_read_b128 v[2:5], v140 offset:32768
	ds_read_b128 v[6:9], v140 offset:33280
	ds_read_b128 v[10:13], v135 offset:40960
	ds_read_b128 v[14:17], v135 offset:41472
	ds_read_b128 v[142:145], v135 offset:43008
	s_nop 3
	v_exp_f32_e32 v50, v50
	v_exp_f32_e32 v51, v51
	v_exp_f32_e32 v52, v52
	v_exp_f32_e32 v53, v53
	v_exp_f32_e32 v54, v54
	v_exp_f32_e32 v55, v55
	v_exp_f32_e32 v56, v56
	v_exp_f32_e32 v57, v57
	v_add_f32_e32 v18, 0, v50
	v_add_f32_e32 v19, 0, v51
	v_add_f32_e32 v18, v52, v18
	v_add_f32_e32 v19, v53, v19
	v_add_f32_e32 v18, v54, v18
	v_add_f32_e32 v19, v55, v19
	v_cvt_pk_bf16_f32 v130, v50, v51
	v_cvt_pk_bf16_f32 v131, v52, v53
	v_cvt_pk_bf16_f32 v132, v54, v55
	v_add_f32_e32 v137, v57, v19
	v_add_f32_e32 v141, v56, v18
	v_cvt_pk_bf16_f32 v133, v56, v57
	s_waitcnt lgkmcnt(4)
	s_nop 0
	v_mfma_f32_32x32x16_bf16 v[66:81], v[2:5], v[130:133], v[66:81]
	ds_read_b128 v[146:149], v140 offset:34816
	v_exp_f32_e32 v58, v58
	v_exp_f32_e32 v59, v59
	s_waitcnt lgkmcnt(4)
	v_mfma_f32_32x32x16_bf16 v[82:97], v[6:9], v[130:133], v[82:97]
	ds_read_b128 v[150:153], v140 offset:35328
	v_exp_f32_e32 v60, v60
	v_exp_f32_e32 v61, v61
	s_nop 0
	v_exp_f32_e32 v62, v62
	v_exp_f32_e32 v63, v63
	s_waitcnt lgkmcnt(4)
	v_mfma_f32_32x32x16_bf16 v[18:33], v[10:13], v[118:121], 0
	ds_read_b128 v[154:157], v135 offset:43520
	v_exp_f32_e32 v64, v64
	v_exp_f32_e32 v65, v65
	s_waitcnt lgkmcnt(4)
	v_mfma_f32_32x32x16_bf16 v[2:17], v[14:17], v[118:121], 0
	ds_read_b128 v[158:161], v135 offset:45056
	v_add_f32_e32 v141, v141, v58
	v_add_f32_e32 v137, v137, v59
	v_cvt_pk_bf16_f32 v122, v58, v59
	v_cvt_pk_bf16_f32 v123, v60, v61
	v_add_f32_e32 v141, v60, v141
	v_add_f32_e32 v137, v61, v137
	s_waitcnt lgkmcnt(4)
	v_mfma_f32_32x32x16_bf16 v[18:33], v[142:145], v[114:117], v[18:33]
	ds_read_b128 v[142:145], v135 offset:45568
	v_add_f32_e32 v141, v141, v62
	v_add_f32_e32 v137, v137, v63
	v_cvt_pk_bf16_f32 v124, v62, v63
	v_cvt_pk_bf16_f32 v125, v64, v65
	v_add_f32_e32 v141, v64, v141
	v_add_f32_e32 v137, v65, v137
	s_waitcnt lgkmcnt(4)
	v_mfma_f32_32x32x16_bf16 v[66:81], v[146:149], v[122:125], v[66:81]
	ds_read_b128 v[50:53], v140 offset:36864
	v_exp_f32_e32 v34, v34
	v_exp_f32_e32 v35, v35
	s_waitcnt lgkmcnt(4)
	v_mfma_f32_32x32x16_bf16 v[82:97], v[150:153], v[122:125], v[82:97]
	ds_read_b128 v[54:57], v140 offset:37376
	v_exp_f32_e32 v36, v36
	v_exp_f32_e32 v37, v37
	s_nop 0
	v_exp_f32_e32 v38, v38
	v_exp_f32_e32 v39, v39
	s_waitcnt lgkmcnt(4)
	v_mfma_f32_32x32x16_bf16 v[2:17], v[154:157], v[114:117], v[2:17]
	ds_read_b128 v[58:61], v135 offset:47104
	v_exp_f32_e32 v40, v40
	v_exp_f32_e32 v41, v41
	s_waitcnt lgkmcnt(4)
	v_mfma_f32_32x32x16_bf16 v[18:33], v[158:161], v[110:113], v[18:33]
	ds_read_b128 v[62:65], v135 offset:47616
	v_add_f32_e32 v141, v141, v34
	v_add_f32_e32 v137, v137, v35
	v_cvt_pk_bf16_f32 v130, v34, v35
	v_cvt_pk_bf16_f32 v131, v36, v37
	v_add_f32_e32 v141, v36, v141
	v_add_f32_e32 v137, v37, v137
	s_waitcnt lgkmcnt(4)
	v_mfma_f32_32x32x16_bf16 v[2:17], v[142:145], v[110:113], v[2:17]
	ds_read_b128 v[142:145], v135 offset:49152
	v_add_f32_e32 v141, v141, v38
	v_add_f32_e32 v137, v137, v39
	v_cvt_pk_bf16_f32 v132, v38, v39
	v_cvt_pk_bf16_f32 v133, v40, v41
	v_add_f32_e32 v141, v40, v141
	v_add_f32_e32 v137, v41, v137
	s_waitcnt lgkmcnt(4)
	v_mfma_f32_32x32x16_bf16 v[66:81], v[50:53], v[130:133], v[66:81]
	ds_read_b128 v[50:53], v140 offset:38912
	v_exp_f32_e32 v42, v42
	v_exp_f32_e32 v43, v43
	s_waitcnt lgkmcnt(4)
	v_mfma_f32_32x32x16_bf16 v[82:97], v[54:57], v[130:133], v[82:97]
	ds_read_b128 v[54:57], v140 offset:39424
	v_exp_f32_e32 v44, v44
	v_exp_f32_e32 v45, v45
	s_nop 0
	v_exp_f32_e32 v46, v46
	v_exp_f32_e32 v47, v47
	s_waitcnt lgkmcnt(4)
	v_mfma_f32_32x32x16_bf16 v[18:33], v[58:61], v[106:109], v[18:33]
	ds_read_b128 v[58:61], v135 offset:49664
	v_exp_f32_e32 v48, v48
	v_exp_f32_e32 v49, v49
	s_waitcnt lgkmcnt(4)
	v_mfma_f32_32x32x16_bf16 v[2:17], v[62:65], v[106:109], v[2:17]
	ds_read_b128 v[62:65], v135 offset:51200
	v_add_f32_e32 v130, v141, v42
	v_add_f32_e32 v131, v137, v43
	v_cvt_pk_bf16_f32 v122, v42, v43
	v_cvt_pk_bf16_f32 v123, v44, v45
	v_add_f32_e32 v137, v44, v130
	v_add_f32_e32 v140, v45, v131
	s_waitcnt lgkmcnt(4)
	v_mfma_f32_32x32x16_bf16 v[18:33], v[142:145], v[102:105], v[18:33]
	ds_read_b128 v[130:133], v135 offset:51712
	v_add_f32_e32 v135, v137, v46
	v_add_f32_e32 v137, v140, v47
	v_cvt_pk_bf16_f32 v124, v46, v47
	v_cvt_pk_bf16_f32 v125, v48, v49
	v_add_f32_e32 v135, v48, v135
	v_add_f32_e32 v137, v49, v137
	s_waitcnt lgkmcnt(4)
	v_mfma_f32_32x32x16_bf16 v[66:81], v[50:53], v[122:125], v[66:81]
	s_waitcnt lgkmcnt(3)
	v_mfma_f32_32x32x16_bf16 v[82:97], v[54:57], v[122:125], v[82:97]
	s_waitcnt lgkmcnt(2)
	v_mfma_f32_32x32x16_bf16 v[2:17], v[58:61], v[102:105], v[2:17]
	s_waitcnt lgkmcnt(1)
	v_mfma_f32_32x32x16_bf16 v[18:33], v[62:65], v[98:101], v[18:33]
	s_waitcnt lgkmcnt(0)
	v_mfma_f32_32x32x16_bf16 v[2:17], v[130:133], v[98:101], v[2:17]
	s_add_i32 s48, s48, 2
	s_add_i32 s9, s51, 2
	s_add_u32 s29, s29, 0x4000
	s_addc_u32 s30, s30, 0
	v_add_f32_e64 v34, v136, v134
	v_add_f32_e64 v35, v137, v135
	s_add_u32 s31, s31, 0x6000
	v_add_f32_e32 v34, v138, v34
	s_addc_u32 s33, s33, 0
	s_add_i32 s49, s49, 2
	s_add_i32 s50, s50, 0xa000
	s_add_i32 s10, s51, 4
	s_cmp_le_i32 s10, s27
	v_add_f32_e32 v138, v34, v35
	s_cbranch_scc0 .LBB0_503
	s_mov_b32 s51, s9
	s_branch .LBB0_496

.LBB0_547:
	s_and_b32 s2, s9, 3
	s_mulk_i32 s2, 0x5000
	v_add_u32_e32 v75, s2, v74
	ds_read_b128 v[18:21], v75 offset:8704
	ds_read_b128 v[22:25], v75 offset:8192
	ds_read_b128 v[26:29], v75 offset:4096
	v_exp_f32_e32 v92, v92
	v_exp_f32_e32 v93, v93
	v_exp_f32_e32 v94, v94
	v_exp_f32_e32 v95, v95
	v_exp_f32_e32 v96, v96
	v_exp_f32_e32 v97, v97
	v_exp_f32_e32 v98, v98
	v_exp_f32_e32 v99, v99
	v_cvt_pk_bf16_f32 v70, v92, v93
	v_cvt_pk_bf16_f32 v71, v94, v95
	v_cvt_pk_bf16_f32 v72, v96, v97
	v_cvt_pk_bf16_f32 v73, v98, v99
	s_waitcnt lgkmcnt(1)
	s_nop 0
	v_mfma_f32_32x32x16_bf16 v[156:171], v[22:25], v[70:73], v[156:171]
	ds_read_b128 v[30:33], v75 offset:10240
	s_mov_b32 s10, s8
	s_mov_b32 s11, s8
	s_mov_b32 s9, s8
	v_exp_f32_e32 v100, v100
	v_exp_f32_e32 v101, v101
	v_exp_f32_e32 v102, v102
	v_mfma_f32_32x32x16_bf16 v[140:155], v[18:21], v[70:73], v[140:155]
	ds_read_b128 v[18:21], v75 offset:10752
	v_exp_f32_e32 v103, v103
	v_exp_f32_e32 v104, v104
	v_exp_f32_e32 v105, v105
	v_mfma_f32_32x32x16_bf16 v[2:17], v[58:61], v[70:73], v[2:17]
	v_exp_f32_e32 v106, v106
	v_exp_f32_e32 v107, v107
	v_cvt_pk_bf16_f32 v182, v100, v101
	ds_read_b128 v[22:25], v75 offset:4608
	v_cvt_pk_bf16_f32 v183, v102, v103
	v_cvt_pk_bf16_f32 v184, v104, v105
	v_cvt_pk_bf16_f32 v185, v106, v107
	s_waitcnt lgkmcnt(3)
	v_mfma_f32_32x32x16_bf16 v[34:49], v[26:29], v[178:181], 0
	s_waitcnt lgkmcnt(2)
	v_mfma_f32_32x32x16_bf16 v[156:171], v[30:33], v[182:185], v[156:171]
	ds_read_b128 v[92:95], v75 offset:12288
	v_exp_f32_e32 v76, v76
	v_exp_f32_e32 v77, v77
	v_exp_f32_e32 v78, v78
	s_waitcnt lgkmcnt(2)
	v_mfma_f32_32x32x16_bf16 v[140:155], v[18:21], v[182:185], v[140:155]
	ds_read_b128 v[96:99], v75 offset:12800
	v_exp_f32_e32 v79, v79
	v_exp_f32_e32 v80, v80
	v_exp_f32_e32 v81, v81
	v_mfma_f32_32x32x16_bf16 v[2:17], v[58:61], v[182:185], v[2:17]
	v_exp_f32_e32 v82, v82
	v_exp_f32_e32 v83, v83
	v_cvt_pk_bf16_f32 v70, v76, v77
	ds_read_b128 v[100:103], v75 offset:6144
	v_cvt_pk_bf16_f32 v71, v78, v79
	v_cvt_pk_bf16_f32 v72, v80, v81
	v_cvt_pk_bf16_f32 v73, v82, v83
	s_waitcnt lgkmcnt(3)
	v_mfma_f32_32x32x16_bf16 v[18:33], v[22:25], v[178:181], 0
	s_waitcnt lgkmcnt(2)
	v_mfma_f32_32x32x16_bf16 v[156:171], v[92:95], v[70:73], v[156:171]
	ds_read_b128 v[92:95], v75 offset:14336
	v_exp_f32_e32 v84, v84
	v_exp_f32_e32 v85, v85
	v_exp_f32_e32 v86, v86
	s_waitcnt lgkmcnt(2)
	v_mfma_f32_32x32x16_bf16 v[140:155], v[96:99], v[70:73], v[140:155]
	ds_read_b128 v[96:99], v75 offset:14848
	v_exp_f32_e32 v87, v87
	v_exp_f32_e32 v88, v88
	v_exp_f32_e32 v89, v89
	v_mfma_f32_32x32x16_bf16 v[2:17], v[58:61], v[70:73], v[2:17]
	v_exp_f32_e32 v90, v90
	v_exp_f32_e32 v91, v91
	v_cvt_pk_bf16_f32 v182, v84, v85
	ds_read_b128 v[70:73], v75 offset:6656
	v_cvt_pk_bf16_f32 v183, v86, v87
	v_cvt_pk_bf16_f32 v184, v88, v89
	v_cvt_pk_bf16_f32 v185, v90, v91
	s_waitcnt lgkmcnt(3)
	v_mfma_f32_32x32x16_bf16 v[34:49], v[100:103], v[174:177], v[34:49]
	s_waitcnt lgkmcnt(2)
	v_mfma_f32_32x32x16_bf16 v[156:171], v[92:95], v[182:185], v[156:171]
	s_waitcnt lgkmcnt(1)
	v_mfma_f32_32x32x16_bf16 v[140:155], v[96:99], v[182:185], v[140:155]
	v_mfma_f32_32x32x16_bf16 v[2:17], v[58:61], v[182:185], v[2:17]
	s_waitcnt lgkmcnt(0)
	v_mfma_f32_32x32x16_bf16 v[18:33], v[70:73], v[174:177], v[18:33]
	s_and_b32 s2, s43, 3
	s_mulk_i32 s2, 0x5000
	v_add_u32_e32 v172, s2, v74
	ds_read_b128 v[76:79], v75 offset:8192
	ds_read_b128 v[80:83], v75 offset:8704
	ds_read_b128 v[84:87], v172
	v_exp_f32_e32 v34, v34
	v_exp_f32_e32 v35, v35
	v_exp_f32_e32 v36, v36
	v_exp_f32_e32 v37, v37
	v_exp_f32_e32 v38, v38
	v_exp_f32_e32 v39, v39
	v_exp_f32_e32 v40, v40
	v_exp_f32_e32 v41, v41
	v_cvt_pk_bf16_f32 v70, v34, v35
	v_cvt_pk_bf16_f32 v71, v36, v37
	v_cvt_pk_bf16_f32 v72, v38, v39
	v_cvt_pk_bf16_f32 v73, v40, v41
	s_waitcnt lgkmcnt(2)
	s_nop 0
	v_mfma_f32_32x32x16_bf16 v[124:139], v[76:79], v[70:73], v[124:139]
	ds_read_b128 v[76:79], v75 offset:10240
	v_exp_f32_e32 v42, v42
	v_exp_f32_e32 v43, v43
	v_exp_f32_e32 v44, v44
	s_waitcnt lgkmcnt(2)
	v_mfma_f32_32x32x16_bf16 v[108:123], v[80:83], v[70:73], v[108:123]
	ds_read_b128 v[80:83], v75 offset:10752
	v_exp_f32_e32 v45, v45
	v_exp_f32_e32 v46, v46
	v_exp_f32_e32 v47, v47
	v_mfma_f32_32x32x16_bf16 v[2:17], v[62:65], v[70:73], v[2:17]
	v_exp_f32_e32 v48, v48
	v_exp_f32_e32 v49, v49
	v_cvt_pk_bf16_f32 v66, v42, v43
	s_waitcnt lgkmcnt(2)
	v_mfma_f32_32x32x16_bf16 v[92:107], v[84:87], v[50:53], 0
	ds_read_b128 v[88:91], v172 offset:512
	v_cvt_pk_bf16_f32 v67, v44, v45
	v_cvt_pk_bf16_f32 v68, v46, v47
	v_cvt_pk_bf16_f32 v69, v48, v49
	s_waitcnt lgkmcnt(2)
	s_nop 0
	v_mfma_f32_32x32x16_bf16 v[124:139], v[76:79], v[66:69], v[124:139]
	ds_read_b128 v[34:37], v75 offset:12288
	v_exp_f32_e32 v18, v18
	v_exp_f32_e32 v19, v19
	v_exp_f32_e32 v20, v20
	s_waitcnt lgkmcnt(2)
	v_mfma_f32_32x32x16_bf16 v[108:123], v[80:83], v[66:69], v[108:123]
	ds_read_b128 v[38:41], v75 offset:12800
	v_exp_f32_e32 v21, v21
	v_exp_f32_e32 v22, v22
	v_exp_f32_e32 v23, v23
	v_mfma_f32_32x32x16_bf16 v[2:17], v[62:65], v[66:69], v[2:17]
	v_exp_f32_e32 v24, v24
	v_exp_f32_e32 v25, v25
	v_cvt_pk_bf16_f32 v70, v18, v19
	s_waitcnt lgkmcnt(2)
	v_mfma_f32_32x32x16_bf16 v[76:91], v[88:91], v[50:53], 0
	ds_read_b128 v[42:45], v172 offset:2048
	v_cvt_pk_bf16_f32 v71, v20, v21
	v_cvt_pk_bf16_f32 v72, v22, v23
	v_cvt_pk_bf16_f32 v73, v24, v25
	s_waitcnt lgkmcnt(2)
	s_nop 0
	v_mfma_f32_32x32x16_bf16 v[124:139], v[34:37], v[70:73], v[124:139]
	ds_read_b128 v[34:37], v75 offset:14336
	v_exp_f32_e32 v26, v26
	v_exp_f32_e32 v27, v27
	v_exp_f32_e32 v28, v28
	s_waitcnt lgkmcnt(2)
	v_mfma_f32_32x32x16_bf16 v[108:123], v[38:41], v[70:73], v[108:123]
	ds_read_b128 v[38:41], v75 offset:14848
	v_exp_f32_e32 v29, v29
	v_exp_f32_e32 v30, v30
	v_exp_f32_e32 v31, v31
	v_mfma_f32_32x32x16_bf16 v[2:17], v[62:65], v[70:73], v[2:17]
	v_exp_f32_e32 v32, v32
	v_exp_f32_e32 v33, v33
	v_cvt_pk_bf16_f32 v66, v26, v27
	s_waitcnt lgkmcnt(2)
	v_mfma_f32_32x32x16_bf16 v[92:107], v[42:45], v[54:57], v[92:107]
	ds_read_b128 v[42:45], v172 offset:2560
	v_cvt_pk_bf16_f32 v67, v28, v29
	v_cvt_pk_bf16_f32 v68, v30, v31
	v_cvt_pk_bf16_f32 v69, v32, v33
	s_waitcnt lgkmcnt(2)
	s_nop 0
	v_mfma_f32_32x32x16_bf16 v[124:139], v[34:37], v[66:69], v[124:139]
	s_waitcnt lgkmcnt(1)
	v_mfma_f32_32x32x16_bf16 v[108:123], v[38:41], v[66:69], v[108:123]
	v_mfma_f32_32x32x16_bf16 v[2:17], v[62:65], v[66:69], v[2:17]
	s_waitcnt lgkmcnt(0)
	v_mfma_f32_32x32x16_bf16 v[76:91], v[42:45], v[54:57], v[76:91]
	s_add_i32 s2, s43, 1
	s_add_u32 s44, s44, 0x1000
	s_addc_u32 s45, s45, 0
	s_add_u32 s46, s46, 0x2000
	s_addc_u32 s47, s47, 0
	s_cmp_lg_u32 s43, s26
	s_cbranch_scc0 .LBB0_552
	s_mov_b32 s43, s2
	s_add_i32 s9, s43, -1
	s_cmp_ge_u32 s9, s28
	s_mov_b64 s[2:3], -1
	s_cbranch_scc1 .LBB0_539
	s_branch .LBB0_540
